# all per-segment s_setprio flips removed from every GEMM phase (336 sites); attention keeps its entry/exit pair
# baseline (speedup 1.0000x reference)
; #define PG8_STAGE(bufoff, gbase, voff) do { _Pragma("unroll") for (int _i = 0; _i < 2; ++_i) \
;         __builtin_amdgcn_global_load_lds((const unsigned*)((const char*)(gbase) + (voff)[_i]), (PG8_LAS unsigned*)(lds + (bufoff) + ldsw + _i * 8192), 16, 0, 0); } while (0)
; #define PG8_LDA(dst, b, h) do { _Pragma("unroll") for (int m = 0; m < 4; ++m) _Pragma("unroll") for (int k = 0; k < 2; ++k) dst[m][k] = *(const PG8_LAS bf16x8*)(lds + PG8_SA(b, h) + aoff + m * 2048 + k * 1024); } while (0)
; #define PG8_LDB(dst, b, h) do { _Pragma("unroll") for (int n = 0; n < 2; ++n) _Pragma("unroll") for (int k = 0; k < 2; ++k) dst[n][k] = *(const PG8_LAS bf16x8*)(lds + PG8_SB(b, h) + boff + n * 2048 + k * 1024); } while (0)
; #define PG8_MMA(ai, bj, At, Bt) do { __builtin_amdgcn_s_setprio(1); _Pragma("unroll") for (int m = 0; m < 4; ++m) _Pragma("unroll") for (int n = 0; n < 2; ++n) _Pragma("unroll") for (int k = 0; k < 2; ++k) \
;         acc[ai][bj][m][n] = __builtin_amdgcn_mfma_f32_16x16x32_bf16(Bt[n][k], At[m][k], acc[ai][bj][m][n], 0, 0, 0); __builtin_amdgcn_s_setprio(0); } while (0)
; #define PG8_WAIT_V(n) asm volatile("s_waitcnt vmcnt(" #n ")" ::: "memory")
; #define PG8_BAR __builtin_amdgcn_s_barrier()
; template <class Epi, class Sched, bool ALIGN_EPI = false, bool SP2 = false>
; __device__ __forceinline__ void gemm_phase(PG8_LAS unsigned char* lds, const Gemm g, const Sched& S, const Epi& E) {
;     ...
;         for (int t = 0; t < nt; t += 2) {
;             const bool last = (t == nt - 2);
;             const char* a1 = cA + (size_t)(t + 1) * kstep;
;             const char* a2 = last ? nA : cA + (size_t)(t + 2) * kstep; const char* b2 = last ? nB : cB + (size_t)(t + 2) * kstep;
;             const char* a3 = a2 + kstep; const char* b3 = b2 + kstep;
;             if (last && has_next) S.a_ready(nxt);
;             if constexpr (SP2) {
;             PG8_LDB(B0, 0, 0); PG8_LDB(B1, 0, 1); PG8_SCHED; PG8_LDA(At, 0, 0); PG8_STAGE(PG8_SA(1, 1), a1 + hstepA, voffA);
;             PG8_WAIT_V(8); PG8_WAIT_L(0); PG8_BAR; PG8_MMA(0, 0, At, B0); PG8_MMA(0, 1, At, B1); PG8_BAR; PG8_SCHED;
;             PG8_LDA(At, 0, 1); PG8_STAGE(PG8_SB(0, 0), b2, voffB); PG8_STAGE(PG8_SB(0, 1), b2 + hstepB, voffB); PG8_STAGE(PG8_SA(0, 0), a2, voffA);
;             PG8_WAIT_V(8); PG8_WAIT_L(0); PG8_BAR; PG8_MMA(1, 0, At, B0); PG8_MMA(1, 1, At, B1); PG8_BAR; PG8_SCHED;
.LBB0_832:
	s_add_u32 s36, s24, s28
	s_addc_u32 s37, s25, s29
	s_add_u32 s34, s36, 0x100
	s_addc_u32 s35, s37, 0
	s_and_b64 s[30:31], s[26:27], exec
	s_cselect_b32 s31, s19, s35
	s_cselect_b32 s30, s18, s34
	s_add_u32 s28, s22, s28
	s_addc_u32 s29, s23, s29
	s_add_u32 s28, s28, 0x100
	s_addc_u32 s29, s29, 0
	s_and_b64 s[26:27], s[26:27], exec
	s_cselect_b32 s35, s5, s29
	s_cselect_b32 s34, s17, s28
	s_add_u32 s38, s36, 0x2a080
	ds_read_b128 v[162:165], v151
	ds_read_b128 v[166:169], v151 offset:1024
	ds_read_b128 v[170:173], v151 offset:2048
	ds_read_b128 v[174:177], v151 offset:3072
	ds_read_b128 v[178:181], v152
	ds_read_b128 v[182:185], v152 offset:1024
	ds_read_b128 v[186:189], v152 offset:2048
	ds_read_b128 v[190:193], v152 offset:3072
	s_addc_u32 s39, s37, 0
	s_add_i32 s73, s55, s45
	s_add_i32 m0, s46, 0xc000
	s_add_i32 s76, s46, 0xe000
	s_add_i32 s70, s73, 0x2000
	s_add_u32 s36, s34, 0x10000
	s_addc_u32 s37, s35, 0
	s_add_i32 s72, s56, s45
	s_add_i32 s71, s72, 0x2000
	s_add_i32 s69, 0, 0x18000
	s_add_i32 s68, 0, 0x1c000
	s_add_u32 s28, s30, 0x2a000
	s_addc_u32 s29, s31, 0
	s_add_i32 s67, s69, s45
	s_add_i32 s66, s67, 0x2000
	s_add_u32 s26, s34, 0x10080
	s_addc_u32 s27, s35, 0
	s_add_i32 s75, s68, s45
	s_add_i32 s74, s75, 0x2000
	v_lshl_add_u64 v[148:149], s[38:39], 0, v[130:131]
	ds_read_b128 v[194:197], v153
	ds_read_b128 v[198:201], v153 offset:1024
	ds_read_b128 v[202:205], v153 offset:2048
	ds_read_b128 v[206:209], v153 offset:3072
	ds_read_b128 v[210:213], v153 offset:4096
	ds_read_b128 v[214:217], v153 offset:5120
	ds_read_b128 v[218:221], v153 offset:6144
	ds_read_b128 v[222:225], v153 offset:7168
	global_load_lds_dwordx4 v[148:149], off
	v_lshl_add_u64 v[148:149], s[38:39], 0, v[134:135]
	s_mov_b32 m0, s76
	s_nop 0
	global_load_lds_dwordx4 v[148:149], off
	s_waitcnt vmcnt(8)
	s_waitcnt lgkmcnt(0)
	s_barrier
	s_waitcnt lgkmcnt(0)
	v_mfma_f32_16x16x32_bf16 v[126:129], v[162:165], v[194:197], v[126:129]
	v_mfma_f32_16x16x32_bf16 v[122:125], v[170:173], v[194:197], v[122:125]
	v_mfma_f32_16x16x32_bf16 v[110:113], v[162:165], v[202:205], v[110:113]
	v_mfma_f32_16x16x32_bf16 v[106:109], v[170:173], v[202:205], v[106:109]
	v_mfma_f32_16x16x32_bf16 v[94:97], v[162:165], v[210:213], v[94:97]
	v_mfma_f32_16x16x32_bf16 v[90:93], v[170:173], v[210:213], v[90:93]
	v_mfma_f32_16x16x32_bf16 v[78:81], v[162:165], v[218:221], v[78:81]
	v_mfma_f32_16x16x32_bf16 v[74:77], v[170:173], v[218:221], v[74:77]
	v_mfma_f32_16x16x32_bf16 v[126:129], v[166:169], v[198:201], v[126:129]
	v_mfma_f32_16x16x32_bf16 v[122:125], v[174:177], v[198:201], v[122:125]
	v_mfma_f32_16x16x32_bf16 v[110:113], v[166:169], v[206:209], v[110:113]
	v_mfma_f32_16x16x32_bf16 v[106:109], v[174:177], v[206:209], v[106:109]
	v_mfma_f32_16x16x32_bf16 v[94:97], v[166:169], v[214:217], v[94:97]
	v_mfma_f32_16x16x32_bf16 v[90:93], v[174:177], v[214:217], v[90:93]
	v_mfma_f32_16x16x32_bf16 v[78:81], v[166:169], v[222:225], v[78:81]
	v_mfma_f32_16x16x32_bf16 v[74:77], v[174:177], v[222:225], v[74:77]
	v_mfma_f32_16x16x32_bf16 v[118:121], v[178:181], v[194:197], v[118:121]
	v_mfma_f32_16x16x32_bf16 v[114:117], v[186:189], v[194:197], v[114:117]
	v_mfma_f32_16x16x32_bf16 v[102:105], v[178:181], v[202:205], v[102:105]
	v_mfma_f32_16x16x32_bf16 v[98:101], v[186:189], v[202:205], v[98:101]
	v_mfma_f32_16x16x32_bf16 v[86:89], v[178:181], v[210:213], v[86:89]
	v_mfma_f32_16x16x32_bf16 v[82:85], v[186:189], v[210:213], v[82:85]
	v_mfma_f32_16x16x32_bf16 v[70:73], v[178:181], v[218:221], v[70:73]
	v_mfma_f32_16x16x32_bf16 v[66:69], v[186:189], v[218:221], v[66:69]
	v_mfma_f32_16x16x32_bf16 v[118:121], v[182:185], v[198:201], v[118:121]
	v_mfma_f32_16x16x32_bf16 v[114:117], v[190:193], v[198:201], v[114:117]
	v_mfma_f32_16x16x32_bf16 v[102:105], v[182:185], v[206:209], v[102:105]
	v_mfma_f32_16x16x32_bf16 v[98:101], v[190:193], v[206:209], v[98:101]
	v_mfma_f32_16x16x32_bf16 v[86:89], v[182:185], v[214:217], v[86:89]
	v_mfma_f32_16x16x32_bf16 v[82:85], v[190:193], v[214:217], v[82:85]
	v_mfma_f32_16x16x32_bf16 v[70:73], v[182:185], v[222:225], v[70:73]
	v_mfma_f32_16x16x32_bf16 v[66:69], v[190:193], v[222:225], v[66:69]
	s_barrier
	s_mov_b32 m0, s73
	v_lshl_add_u64 v[148:149], s[34:35], 0, v[132:133]
	ds_read_b128 v[194:197], v153 offset:16384
	ds_read_b128 v[198:201], v153 offset:17408
	ds_read_b128 v[202:205], v153 offset:18432
	ds_read_b128 v[206:209], v153 offset:19456
	ds_read_b128 v[210:213], v153 offset:20480
	ds_read_b128 v[214:217], v153 offset:21504
	ds_read_b128 v[218:221], v153 offset:22528
	ds_read_b128 v[222:225], v153 offset:23552
	global_load_lds_dwordx4 v[148:149], off
	v_lshl_add_u64 v[226:227], s[34:35], 0, v[136:137]
	s_mov_b32 m0, s70
	v_lshl_add_u64 v[228:229], s[36:37], 0, v[132:133]
	global_load_lds_dwordx4 v[226:227], off
	s_mov_b32 m0, s72
	v_lshl_add_u64 v[230:231], s[30:31], 0, v[134:135]
	global_load_lds_dwordx4 v[228:229], off
	v_lshl_add_u64 v[228:229], s[36:37], 0, v[136:137]
	s_mov_b32 m0, s71
	s_nop 0
	global_load_lds_dwordx4 v[228:229], off
	v_lshl_add_u64 v[228:229], s[30:31], 0, v[130:131]
	s_mov_b32 m0, s46
	s_nop 0
	global_load_lds_dwordx4 v[228:229], off
	s_mov_b32 m0, s47
	s_nop 0
	global_load_lds_dwordx4 v[230:231], off
	s_waitcnt vmcnt(8)
	s_waitcnt lgkmcnt(0)
	s_barrier
; #define PG8_STAGE(bufoff, gbase, voff) do { _Pragma("unroll") for (int _i = 0; _i < 2; ++_i) \
;         __builtin_amdgcn_global_load_lds((const unsigned*)((const char*)(gbase) + (voff)[_i]), (PG8_LAS unsigned*)(lds + (bufoff) + ldsw + _i * 8192), 16, 0, 0); } while (0)
; #define PG8_LDA(dst, b, h) do { _Pragma("unroll") for (int m = 0; m < 4; ++m) _Pragma("unroll") for (int k = 0; k < 2; ++k) dst[m][k] = *(const PG8_LAS bf16x8*)(lds + PG8_SA(b, h) + aoff + m * 2048 + k * 1024); } while (0)
; #define PG8_LDB(dst, b, h) do { _Pragma("unroll") for (int n = 0; n < 2; ++n) _Pragma("unroll") for (int k = 0; k < 2; ++k) dst[n][k] = *(const PG8_LAS bf16x8*)(lds + PG8_SB(b, h) + boff + n * 2048 + k * 1024); } while (0)
; #define PG8_MMA(ai, bj, At, Bt) do { __builtin_amdgcn_s_setprio(1); _Pragma("unroll") for (int m = 0; m < 4; ++m) _Pragma("unroll") for (int n = 0; n < 2; ++n) _Pragma("unroll") for (int k = 0; k < 2; ++k) \
;         acc[ai][bj][m][n] = __builtin_amdgcn_mfma_f32_16x16x32_bf16(Bt[n][k], At[m][k], acc[ai][bj][m][n], 0, 0, 0); __builtin_amdgcn_s_setprio(0); } while (0)
; #define PG8_WAIT_V(n) asm volatile("s_waitcnt vmcnt(" #n ")" ::: "memory")
; #define PG8_WAIT_L(n) asm volatile("s_waitcnt lgkmcnt(" #n ")" ::: "memory")
; #define PG8_BAR __builtin_amdgcn_s_barrier()
; #define PG8_SCHED __builtin_amdgcn_sched_barrier(0)
; template <class Epi, class Sched, bool ALIGN_EPI = false, bool SP2 = false>
; __device__ __forceinline__ void gemm_phase(PG8_LAS unsigned char* lds, const Gemm g, const Sched& S, const Epi& E) {
;     ...
;             PG8_WAIT_V(8); PG8_WAIT_L(0); PG8_BAR; PG8_MMA(1, 0, At, B0); PG8_MMA(1, 1, At, B1); PG8_BAR; PG8_SCHED;
;             PG8_LDB(B0, 1, 0); PG8_LDB(B1, 1, 1); PG8_SCHED; PG8_LDA(At, 1, 0); PG8_STAGE(PG8_SA(0, 1), a2 + hstepA, voffA);
;             PG8_WAIT_V(8); PG8_WAIT_L(0); PG8_BAR; PG8_MMA(0, 0, At, B0); PG8_MMA(0, 1, At, B1); PG8_BAR; PG8_SCHED;
	s_waitcnt lgkmcnt(0)
	v_mfma_f32_16x16x32_bf16 v[62:65], v[162:165], v[194:197], v[62:65]
	v_mfma_f32_16x16x32_bf16 v[58:61], v[170:173], v[194:197], v[58:61]
	v_mfma_f32_16x16x32_bf16 v[46:49], v[162:165], v[202:205], v[46:49]
	v_mfma_f32_16x16x32_bf16 v[42:45], v[170:173], v[202:205], v[42:45]
	v_mfma_f32_16x16x32_bf16 v[30:33], v[162:165], v[210:213], v[30:33]
	v_mfma_f32_16x16x32_bf16 v[26:29], v[170:173], v[210:213], v[26:29]
	v_mfma_f32_16x16x32_bf16 v[14:17], v[162:165], v[218:221], v[14:17]
	v_mfma_f32_16x16x32_bf16 v[10:13], v[170:173], v[218:221], v[10:13]
	v_mfma_f32_16x16x32_bf16 v[62:65], v[166:169], v[198:201], v[62:65]
	v_mfma_f32_16x16x32_bf16 v[58:61], v[174:177], v[198:201], v[58:61]
	v_mfma_f32_16x16x32_bf16 v[46:49], v[166:169], v[206:209], v[46:49]
	v_mfma_f32_16x16x32_bf16 v[42:45], v[174:177], v[206:209], v[42:45]
	v_mfma_f32_16x16x32_bf16 v[30:33], v[166:169], v[214:217], v[30:33]
	v_mfma_f32_16x16x32_bf16 v[26:29], v[174:177], v[214:217], v[26:29]
	v_mfma_f32_16x16x32_bf16 v[14:17], v[166:169], v[222:225], v[14:17]
	v_mfma_f32_16x16x32_bf16 v[10:13], v[174:177], v[222:225], v[10:13]
	v_mfma_f32_16x16x32_bf16 v[54:57], v[178:181], v[194:197], v[54:57]
	v_mfma_f32_16x16x32_bf16 v[50:53], v[186:189], v[194:197], v[50:53]
	v_mfma_f32_16x16x32_bf16 v[38:41], v[178:181], v[202:205], v[38:41]
	v_mfma_f32_16x16x32_bf16 v[34:37], v[186:189], v[202:205], v[34:37]
	v_mfma_f32_16x16x32_bf16 v[22:25], v[178:181], v[210:213], v[22:25]
	v_mfma_f32_16x16x32_bf16 v[18:21], v[186:189], v[210:213], v[18:21]
	v_mfma_f32_16x16x32_bf16 v[6:9], v[178:181], v[218:221], v[6:9]
	v_mfma_f32_16x16x32_bf16 v[2:5], v[186:189], v[218:221], v[2:5]
	v_mfma_f32_16x16x32_bf16 v[54:57], v[182:185], v[198:201], v[54:57]
	v_mfma_f32_16x16x32_bf16 v[50:53], v[190:193], v[198:201], v[50:53]
	v_mfma_f32_16x16x32_bf16 v[38:41], v[182:185], v[206:209], v[38:41]
	v_mfma_f32_16x16x32_bf16 v[34:37], v[190:193], v[206:209], v[34:37]
	v_mfma_f32_16x16x32_bf16 v[22:25], v[182:185], v[214:217], v[22:25]
	v_mfma_f32_16x16x32_bf16 v[18:21], v[190:193], v[214:217], v[18:21]
	v_mfma_f32_16x16x32_bf16 v[6:9], v[182:185], v[222:225], v[6:9]
	v_mfma_f32_16x16x32_bf16 v[2:5], v[190:193], v[222:225], v[2:5]
	s_barrier
	v_add_u32_e32 v138, s69, v150
	ds_read_b128 v[162:165], v138
	ds_read_b128 v[166:169], v138 offset:1024
	ds_read_b128 v[170:173], v138 offset:2048
	ds_read_b128 v[174:177], v138 offset:3072
	v_add_u32_e32 v138, s68, v150
	ds_read_b128 v[178:181], v138
	ds_read_b128 v[182:185], v138 offset:1024
	ds_read_b128 v[186:189], v138 offset:2048
	ds_read_b128 v[190:193], v138 offset:3072
	s_mov_b32 m0, s48
	v_lshl_add_u64 v[232:233], s[28:29], 0, v[130:131]
	ds_read_b128 v[194:197], v153 offset:32768
	ds_read_b128 v[198:201], v153 offset:33792
	ds_read_b128 v[202:205], v153 offset:34816
	ds_read_b128 v[206:209], v153 offset:35840
	ds_read_b128 v[210:213], v153 offset:36864
	ds_read_b128 v[214:217], v153 offset:37888
	ds_read_b128 v[218:221], v153 offset:38912
	ds_read_b128 v[222:225], v153 offset:39936
	global_load_lds_dwordx4 v[232:233], off
	v_lshl_add_u64 v[232:233], s[28:29], 0, v[134:135]
	s_mov_b32 m0, s49
	s_nop 0
	global_load_lds_dwordx4 v[232:233], off
	s_waitcnt vmcnt(8)
	s_waitcnt lgkmcnt(0)
	s_barrier
	s_waitcnt lgkmcnt(0)
	v_mfma_f32_16x16x32_bf16 v[126:129], v[162:165], v[194:197], v[126:129]
	v_mfma_f32_16x16x32_bf16 v[122:125], v[170:173], v[194:197], v[122:125]
	v_mfma_f32_16x16x32_bf16 v[110:113], v[162:165], v[202:205], v[110:113]
	v_mfma_f32_16x16x32_bf16 v[106:109], v[170:173], v[202:205], v[106:109]
	v_mfma_f32_16x16x32_bf16 v[94:97], v[162:165], v[210:213], v[94:97]
	v_mfma_f32_16x16x32_bf16 v[90:93], v[170:173], v[210:213], v[90:93]
	v_mfma_f32_16x16x32_bf16 v[78:81], v[162:165], v[218:221], v[78:81]
	v_mfma_f32_16x16x32_bf16 v[74:77], v[170:173], v[218:221], v[74:77]
	v_mfma_f32_16x16x32_bf16 v[126:129], v[166:169], v[198:201], v[126:129]
	v_mfma_f32_16x16x32_bf16 v[122:125], v[174:177], v[198:201], v[122:125]
	v_mfma_f32_16x16x32_bf16 v[110:113], v[166:169], v[206:209], v[110:113]
	v_mfma_f32_16x16x32_bf16 v[106:109], v[174:177], v[206:209], v[106:109]
	v_mfma_f32_16x16x32_bf16 v[94:97], v[166:169], v[214:217], v[94:97]
	v_mfma_f32_16x16x32_bf16 v[90:93], v[174:177], v[214:217], v[90:93]
	v_mfma_f32_16x16x32_bf16 v[78:81], v[166:169], v[222:225], v[78:81]
	v_mfma_f32_16x16x32_bf16 v[74:77], v[174:177], v[222:225], v[74:77]
	v_mfma_f32_16x16x32_bf16 v[118:121], v[178:181], v[194:197], v[118:121]
	v_mfma_f32_16x16x32_bf16 v[114:117], v[186:189], v[194:197], v[114:117]
	v_mfma_f32_16x16x32_bf16 v[102:105], v[178:181], v[202:205], v[102:105]
	v_mfma_f32_16x16x32_bf16 v[98:101], v[186:189], v[202:205], v[98:101]
	v_mfma_f32_16x16x32_bf16 v[86:89], v[178:181], v[210:213], v[86:89]
	v_mfma_f32_16x16x32_bf16 v[82:85], v[186:189], v[210:213], v[82:85]
	v_mfma_f32_16x16x32_bf16 v[70:73], v[178:181], v[218:221], v[70:73]
	v_mfma_f32_16x16x32_bf16 v[66:69], v[186:189], v[218:221], v[66:69]
	v_mfma_f32_16x16x32_bf16 v[118:121], v[182:185], v[198:201], v[118:121]
	v_mfma_f32_16x16x32_bf16 v[114:117], v[190:193], v[198:201], v[114:117]
	v_mfma_f32_16x16x32_bf16 v[102:105], v[182:185], v[206:209], v[102:105]
	v_mfma_f32_16x16x32_bf16 v[98:101], v[190:193], v[206:209], v[98:101]
	v_mfma_f32_16x16x32_bf16 v[86:89], v[182:185], v[214:217], v[86:89]
	v_mfma_f32_16x16x32_bf16 v[82:85], v[190:193], v[214:217], v[82:85]
	v_mfma_f32_16x16x32_bf16 v[70:73], v[182:185], v[222:225], v[70:73]
	v_mfma_f32_16x16x32_bf16 v[66:69], v[190:193], v[222:225], v[66:69]
	s_barrier
; #define PG8_STAGE(bufoff, gbase, voff) do { _Pragma("unroll") for (int _i = 0; _i < 2; ++_i) \
;         __builtin_amdgcn_global_load_lds((const unsigned*)((const char*)(gbase) + (voff)[_i]), (PG8_LAS unsigned*)(lds + (bufoff) + ldsw + _i * 8192), 16, 0, 0); } while (0)
; #define PG8_LDA(dst, b, h) do { _Pragma("unroll") for (int m = 0; m < 4; ++m) _Pragma("unroll") for (int k = 0; k < 2; ++k) dst[m][k] = *(const PG8_LAS bf16x8*)(lds + PG8_SA(b, h) + aoff + m * 2048 + k * 1024); } while (0)
; #define PG8_MMA(ai, bj, At, Bt) do { __builtin_amdgcn_s_setprio(1); _Pragma("unroll") for (int m = 0; m < 4; ++m) _Pragma("unroll") for (int n = 0; n < 2; ++n) _Pragma("unroll") for (int k = 0; k < 2; ++k) \
;         acc[ai][bj][m][n] = __builtin_amdgcn_mfma_f32_16x16x32_bf16(Bt[n][k], At[m][k], acc[ai][bj][m][n], 0, 0, 0); __builtin_amdgcn_s_setprio(0); } while (0)
; #define PG8_WAIT_V(n) asm volatile("s_waitcnt vmcnt(" #n ")" ::: "memory")
; #define PG8_WAIT_L(n) asm volatile("s_waitcnt lgkmcnt(" #n ")" ::: "memory")
; #define PG8_BAR __builtin_amdgcn_s_barrier()
; #define PG8_SCHED __builtin_amdgcn_sched_barrier(0)
; template <class Epi, class Sched, bool ALIGN_EPI = false, bool SP2 = false>
; __device__ __forceinline__ void gemm_phase(PG8_LAS unsigned char* lds, const Gemm g, const Sched& S, const Epi& E) {
;     ...
;         for (int t = 0; t < nt; t += 2) {
;             const bool last = (t == nt - 2);
;     ...
;             PG8_LDA(At, 1, 1); PG8_STAGE(PG8_SB(1, 0), b3, voffB); PG8_STAGE(PG8_SB(1, 1), b3 + hstepB, voffB); PG8_STAGE(PG8_SA(1, 0), a3, voffA);
;             PG8_WAIT_V(8); PG8_WAIT_L(0); PG8_BAR; PG8_MMA(1, 0, At, B0); PG8_MMA(1, 1, At, B1); PG8_BAR; PG8_SCHED;
	s_mov_b32 m0, s67
	v_lshl_add_u64 v[148:149], v[148:149], 0, s[8:9]
	ds_read_b128 v[194:197], v153 offset:49152
	ds_read_b128 v[198:201], v153 offset:50176
	ds_read_b128 v[202:205], v153 offset:51200
	ds_read_b128 v[206:209], v153 offset:52224
	ds_read_b128 v[210:213], v153 offset:53248
	ds_read_b128 v[214:217], v153 offset:54272
	ds_read_b128 v[218:221], v153 offset:55296
	ds_read_b128 v[222:225], v153 offset:56320
	global_load_lds_dwordx4 v[148:149], off
	v_lshl_add_u64 v[148:149], v[226:227], 0, s[8:9]
	s_mov_b32 m0, s66
	s_nop 0
	global_load_lds_dwordx4 v[148:149], off
	v_lshl_add_u64 v[148:149], s[26:27], 0, v[132:133]
	s_mov_b32 m0, s75
	s_nop 0
	global_load_lds_dwordx4 v[148:149], off
	v_lshl_add_u64 v[148:149], s[26:27], 0, v[136:137]
	s_mov_b32 m0, s74
	s_nop 0
	global_load_lds_dwordx4 v[148:149], off
	v_lshl_add_u64 v[148:149], v[228:229], 0, s[8:9]
	s_mov_b32 m0, s53
	s_nop 0
	global_load_lds_dwordx4 v[148:149], off
	v_lshl_add_u64 v[148:149], v[230:231], 0, s[8:9]
	s_mov_b32 m0, s54
	s_nop 0
	global_load_lds_dwordx4 v[148:149], off
	s_waitcnt vmcnt(8)
	s_waitcnt lgkmcnt(0)
	s_barrier
	s_waitcnt lgkmcnt(0)
	v_mfma_f32_16x16x32_bf16 v[62:65], v[162:165], v[194:197], v[62:65]
	v_mfma_f32_16x16x32_bf16 v[58:61], v[170:173], v[194:197], v[58:61]
	v_mfma_f32_16x16x32_bf16 v[46:49], v[162:165], v[202:205], v[46:49]
	v_mfma_f32_16x16x32_bf16 v[42:45], v[170:173], v[202:205], v[42:45]
	v_mfma_f32_16x16x32_bf16 v[30:33], v[162:165], v[210:213], v[30:33]
	v_mfma_f32_16x16x32_bf16 v[26:29], v[170:173], v[210:213], v[26:29]
	v_mfma_f32_16x16x32_bf16 v[14:17], v[162:165], v[218:221], v[14:17]
	v_mfma_f32_16x16x32_bf16 v[10:13], v[170:173], v[218:221], v[10:13]
	v_mfma_f32_16x16x32_bf16 v[62:65], v[166:169], v[198:201], v[62:65]
	v_mfma_f32_16x16x32_bf16 v[58:61], v[174:177], v[198:201], v[58:61]
	v_mfma_f32_16x16x32_bf16 v[46:49], v[166:169], v[206:209], v[46:49]
	v_mfma_f32_16x16x32_bf16 v[42:45], v[174:177], v[206:209], v[42:45]
	v_mfma_f32_16x16x32_bf16 v[30:33], v[166:169], v[214:217], v[30:33]
	v_mfma_f32_16x16x32_bf16 v[26:29], v[174:177], v[214:217], v[26:29]
	v_mfma_f32_16x16x32_bf16 v[14:17], v[166:169], v[222:225], v[14:17]
	v_mfma_f32_16x16x32_bf16 v[10:13], v[174:177], v[222:225], v[10:13]
	v_mfma_f32_16x16x32_bf16 v[54:57], v[178:181], v[194:197], v[54:57]
	v_mfma_f32_16x16x32_bf16 v[50:53], v[186:189], v[194:197], v[50:53]
	v_mfma_f32_16x16x32_bf16 v[38:41], v[178:181], v[202:205], v[38:41]
	v_mfma_f32_16x16x32_bf16 v[34:37], v[186:189], v[202:205], v[34:37]
	v_mfma_f32_16x16x32_bf16 v[22:25], v[178:181], v[210:213], v[22:25]
	v_mfma_f32_16x16x32_bf16 v[18:21], v[186:189], v[210:213], v[18:21]
	v_mfma_f32_16x16x32_bf16 v[6:9], v[178:181], v[218:221], v[6:9]
	v_mfma_f32_16x16x32_bf16 v[2:5], v[186:189], v[218:221], v[2:5]
	v_mfma_f32_16x16x32_bf16 v[54:57], v[182:185], v[198:201], v[54:57]
	v_mfma_f32_16x16x32_bf16 v[50:53], v[190:193], v[198:201], v[50:53]
	v_mfma_f32_16x16x32_bf16 v[38:41], v[182:185], v[206:209], v[38:41]
	v_mfma_f32_16x16x32_bf16 v[34:37], v[190:193], v[206:209], v[34:37]
	v_mfma_f32_16x16x32_bf16 v[22:25], v[182:185], v[214:217], v[22:25]
	v_mfma_f32_16x16x32_bf16 v[18:21], v[190:193], v[214:217], v[18:21]
	v_mfma_f32_16x16x32_bf16 v[6:9], v[182:185], v[222:225], v[6:9]
	v_mfma_f32_16x16x32_bf16 v[2:5], v[190:193], v[222:225], v[2:5]
	s_barrier
	s_andn2_b64 vcc, exec, s[0:1]
	s_mov_b64 s[26:27], -1
	s_mov_b64 s[0:1], 0
	s_mov_b64 s[28:29], 0x100
	s_cbranch_vccz .LBB0_832
	s_and_b64 vcc, exec, s[12:13]
	s_cbranch_vccz .LBB0_835
	s_barrier

; #define PG8_STAGE(bufoff, gbase, voff) do { _Pragma("unroll") for (int _i = 0; _i < 2; ++_i) \
;         __builtin_amdgcn_global_load_lds((const unsigned*)((const char*)(gbase) + (voff)[_i]), (PG8_LAS unsigned*)(lds + (bufoff) + ldsw + _i * 8192), 16, 0, 0); } while (0)
; #define PG8_LDA(dst, b, h) do { _Pragma("unroll") for (int m = 0; m < 4; ++m) _Pragma("unroll") for (int k = 0; k < 2; ++k) dst[m][k] = *(const PG8_LAS bf16x8*)(lds + PG8_SA(b, h) + aoff + m * 2048 + k * 1024); } while (0)
; #define PG8_LDB(dst, b, h) do { _Pragma("unroll") for (int n = 0; n < 2; ++n) _Pragma("unroll") for (int k = 0; k < 2; ++k) dst[n][k] = *(const PG8_LAS bf16x8*)(lds + PG8_SB(b, h) + boff + n * 2048 + k * 1024); } while (0)
; #define PG8_MMA(ai, bj, At, Bt) do { __builtin_amdgcn_s_setprio(1); _Pragma("unroll") for (int m = 0; m < 4; ++m) _Pragma("unroll") for (int n = 0; n < 2; ++n) _Pragma("unroll") for (int k = 0; k < 2; ++k) \
;         acc[ai][bj][m][n] = __builtin_amdgcn_mfma_f32_16x16x32_bf16(Bt[n][k], At[m][k], acc[ai][bj][m][n], 0, 0, 0); __builtin_amdgcn_s_setprio(0); } while (0)
; #define PG8_WAIT_V(n) asm volatile("s_waitcnt vmcnt(" #n ")" ::: "memory")
; #define PG8_BAR __builtin_amdgcn_s_barrier()
; template <class Epi, class Sched, bool ALIGN_EPI = false, bool SP2 = false>
; __device__ __forceinline__ void gemm_phase(PG8_LAS unsigned char* lds, const Gemm g, const Sched& S, const Epi& E) {
;     ...
;         for (int t = 0; t < nt; t += 2) {
;             const bool last = (t == nt - 2);
;             const char* a1 = cA + (size_t)(t + 1) * kstep;
;             const char* a2 = last ? nA : cA + (size_t)(t + 2) * kstep; const char* b2 = last ? nB : cB + (size_t)(t + 2) * kstep;
;             const char* a3 = a2 + kstep; const char* b3 = b2 + kstep;
;             if (last && has_next) S.a_ready(nxt);
;             if constexpr (SP2) {
;             PG8_LDB(B0, 0, 0); PG8_LDB(B1, 0, 1); PG8_SCHED; PG8_LDA(At, 0, 0); PG8_STAGE(PG8_SA(1, 1), a1 + hstepA, voffA);
;             PG8_WAIT_V(8); PG8_WAIT_L(0); PG8_BAR; PG8_MMA(0, 0, At, B0); PG8_MMA(0, 1, At, B1); PG8_BAR; PG8_SCHED;
;             PG8_LDA(At, 0, 1); PG8_STAGE(PG8_SB(0, 0), b2, voffB); PG8_STAGE(PG8_SB(0, 1), b2 + hstepB, voffB); PG8_STAGE(PG8_SA(0, 0), a2, voffA);
;             PG8_WAIT_V(8); PG8_WAIT_L(0); PG8_BAR; PG8_MMA(1, 0, At, B0); PG8_MMA(1, 1, At, B1); PG8_BAR; PG8_SCHED;
.LBB0_1324:
	s_add_u32 s37, s28, s36
	s_addc_u32 s42, s29, 0
	s_add_u32 s40, s37, 0x100
	s_addc_u32 s41, s42, 0
	s_and_b64 s[38:39], s[34:35], exec
	s_cselect_b32 s39, s17, s41
	s_cselect_b32 s38, s78, s40
	s_add_u32 s36, s26, s36
	s_addc_u32 s40, s27, 0
	s_add_u32 s36, s36, 0x100
	s_addc_u32 s40, s40, 0
	s_and_b64 s[34:35], s[34:35], exec
	s_cselect_b32 s41, s15, s40
	s_cselect_b32 s40, s79, s36
	s_add_u32 s44, s37, 0x40080
	ds_read_b128 v[130:133], v158
	ds_read_b128 v[134:137], v158 offset:1024
	ds_read_b128 v[138:141], v158 offset:2048
	ds_read_b128 v[142:145], v158 offset:3072
	ds_read_b128 v[152:155], v159
	ds_read_b128 v[162:165], v159 offset:1024
	ds_read_b128 v[166:169], v159 offset:2048
	ds_read_b128 v[170:173], v159 offset:3072
	s_addc_u32 s45, s42, 0
	s_add_i32 s87, s69, s56
	s_add_i32 m0, s25, 0xc000
	s_add_i32 s90, s25, 0xe000
	s_add_i32 s84, s87, 0x2000
	s_add_u32 s42, s40, 0x40000
	s_addc_u32 s43, s41, 0
	s_add_i32 s86, s70, s56
	s_add_i32 s85, s86, 0x2000
	s_add_i32 s83, 0, 0x18000
	s_add_i32 s82, 0, 0x1c000
	s_add_u32 s36, s38, 0x40000
	s_addc_u32 s37, s39, 0
	s_add_i32 s81, s83, s56
	s_add_i32 s80, s81, 0x2000
	s_add_u32 s34, s40, 0x40080
	s_addc_u32 s35, s41, 0
	s_add_i32 s89, s82, s56
	s_add_i32 s88, s89, 0x2000
	v_lshl_add_u64 v[206:207], s[44:45], 0, v[148:149]
	ds_read_b128 v[174:177], v160
	ds_read_b128 v[178:181], v160 offset:1024
	ds_read_b128 v[182:185], v160 offset:2048
	ds_read_b128 v[186:189], v160 offset:3072
	ds_read_b128 v[190:193], v160 offset:4096
	ds_read_b128 v[194:197], v160 offset:5120
	ds_read_b128 v[198:201], v160 offset:6144
	ds_read_b128 v[202:205], v160 offset:7168
	global_load_lds_dwordx4 v[206:207], off
	v_lshl_add_u64 v[206:207], s[44:45], 0, v[146:147]
	s_mov_b32 m0, s90
	s_nop 0
	global_load_lds_dwordx4 v[206:207], off
	s_waitcnt vmcnt(8)
	s_waitcnt lgkmcnt(0)
	s_barrier
	s_waitcnt lgkmcnt(0)
	v_mfma_f32_16x16x32_bf16 v[126:129], v[130:133], v[174:177], v[126:129]
	v_mfma_f32_16x16x32_bf16 v[122:125], v[138:141], v[174:177], v[122:125]
	v_mfma_f32_16x16x32_bf16 v[118:121], v[130:133], v[182:185], v[118:121]
	v_mfma_f32_16x16x32_bf16 v[114:117], v[138:141], v[182:185], v[114:117]
	v_mfma_f32_16x16x32_bf16 v[102:105], v[130:133], v[190:193], v[102:105]
	v_mfma_f32_16x16x32_bf16 v[90:93], v[138:141], v[190:193], v[90:93]
	v_mfma_f32_16x16x32_bf16 v[82:85], v[130:133], v[198:201], v[82:85]
	v_mfma_f32_16x16x32_bf16 v[74:77], v[138:141], v[198:201], v[74:77]
	v_mfma_f32_16x16x32_bf16 v[126:129], v[134:137], v[178:181], v[126:129]
	v_mfma_f32_16x16x32_bf16 v[122:125], v[142:145], v[178:181], v[122:125]
	v_mfma_f32_16x16x32_bf16 v[118:121], v[134:137], v[186:189], v[118:121]
	v_mfma_f32_16x16x32_bf16 v[114:117], v[142:145], v[186:189], v[114:117]
	v_mfma_f32_16x16x32_bf16 v[102:105], v[134:137], v[194:197], v[102:105]
	v_mfma_f32_16x16x32_bf16 v[90:93], v[142:145], v[194:197], v[90:93]
	v_mfma_f32_16x16x32_bf16 v[82:85], v[134:137], v[202:205], v[82:85]
	v_mfma_f32_16x16x32_bf16 v[74:77], v[142:145], v[202:205], v[74:77]
	v_mfma_f32_16x16x32_bf16 v[110:113], v[152:155], v[174:177], v[110:113]
	v_mfma_f32_16x16x32_bf16 v[106:109], v[166:169], v[174:177], v[106:109]
	v_mfma_f32_16x16x32_bf16 v[98:101], v[152:155], v[182:185], v[98:101]
	v_mfma_f32_16x16x32_bf16 v[94:97], v[166:169], v[182:185], v[94:97]
	v_mfma_f32_16x16x32_bf16 v[86:89], v[152:155], v[190:193], v[86:89]
	v_mfma_f32_16x16x32_bf16 v[78:81], v[166:169], v[190:193], v[78:81]
	v_mfma_f32_16x16x32_bf16 v[70:73], v[152:155], v[198:201], v[70:73]
	v_mfma_f32_16x16x32_bf16 v[66:69], v[166:169], v[198:201], v[66:69]
	v_mfma_f32_16x16x32_bf16 v[110:113], v[162:165], v[178:181], v[110:113]
	v_mfma_f32_16x16x32_bf16 v[106:109], v[170:173], v[178:181], v[106:109]
	v_mfma_f32_16x16x32_bf16 v[98:101], v[162:165], v[186:189], v[98:101]
	v_mfma_f32_16x16x32_bf16 v[94:97], v[170:173], v[186:189], v[94:97]
	v_mfma_f32_16x16x32_bf16 v[86:89], v[162:165], v[194:197], v[86:89]
	v_mfma_f32_16x16x32_bf16 v[78:81], v[170:173], v[194:197], v[78:81]
	v_mfma_f32_16x16x32_bf16 v[70:73], v[162:165], v[202:205], v[70:73]
	v_mfma_f32_16x16x32_bf16 v[66:69], v[170:173], v[202:205], v[66:69]
	s_barrier
	s_mov_b32 m0, s87
	v_lshl_add_u64 v[206:207], s[40:41], 0, v[148:149]
	ds_read_b128 v[174:177], v160 offset:16384
	ds_read_b128 v[178:181], v160 offset:17408
	ds_read_b128 v[182:185], v160 offset:18432
	ds_read_b128 v[186:189], v160 offset:19456
	ds_read_b128 v[190:193], v160 offset:20480
	ds_read_b128 v[194:197], v160 offset:21504
	ds_read_b128 v[198:201], v160 offset:22528
	ds_read_b128 v[202:205], v160 offset:23552
	global_load_lds_dwordx4 v[206:207], off
	v_lshl_add_u64 v[208:209], s[40:41], 0, v[146:147]
	s_mov_b32 m0, s84
	v_lshl_add_u64 v[210:211], s[42:43], 0, v[148:149]
	global_load_lds_dwordx4 v[208:209], off
	s_mov_b32 m0, s86
	v_lshl_add_u64 v[212:213], s[38:39], 0, v[146:147]
	global_load_lds_dwordx4 v[210:211], off
	v_lshl_add_u64 v[210:211], s[42:43], 0, v[146:147]
	s_mov_b32 m0, s85
	s_nop 0
	global_load_lds_dwordx4 v[210:211], off
	v_lshl_add_u64 v[210:211], s[38:39], 0, v[148:149]
	s_mov_b32 m0, s25
	s_nop 0
	global_load_lds_dwordx4 v[210:211], off
	s_mov_b32 m0, s58
	s_nop 0
	global_load_lds_dwordx4 v[212:213], off
	s_waitcnt vmcnt(8)
	s_waitcnt lgkmcnt(0)
	s_barrier
; #define PG8_STAGE(bufoff, gbase, voff) do { _Pragma("unroll") for (int _i = 0; _i < 2; ++_i) \
;         __builtin_amdgcn_global_load_lds((const unsigned*)((const char*)(gbase) + (voff)[_i]), (PG8_LAS unsigned*)(lds + (bufoff) + ldsw + _i * 8192), 16, 0, 0); } while (0)
; #define PG8_LDA(dst, b, h) do { _Pragma("unroll") for (int m = 0; m < 4; ++m) _Pragma("unroll") for (int k = 0; k < 2; ++k) dst[m][k] = *(const PG8_LAS bf16x8*)(lds + PG8_SA(b, h) + aoff + m * 2048 + k * 1024); } while (0)
; #define PG8_LDB(dst, b, h) do { _Pragma("unroll") for (int n = 0; n < 2; ++n) _Pragma("unroll") for (int k = 0; k < 2; ++k) dst[n][k] = *(const PG8_LAS bf16x8*)(lds + PG8_SB(b, h) + boff + n * 2048 + k * 1024); } while (0)
; #define PG8_MMA(ai, bj, At, Bt) do { __builtin_amdgcn_s_setprio(1); _Pragma("unroll") for (int m = 0; m < 4; ++m) _Pragma("unroll") for (int n = 0; n < 2; ++n) _Pragma("unroll") for (int k = 0; k < 2; ++k) \
;         acc[ai][bj][m][n] = __builtin_amdgcn_mfma_f32_16x16x32_bf16(Bt[n][k], At[m][k], acc[ai][bj][m][n], 0, 0, 0); __builtin_amdgcn_s_setprio(0); } while (0)
; #define PG8_WAIT_V(n) asm volatile("s_waitcnt vmcnt(" #n ")" ::: "memory")
; #define PG8_WAIT_L(n) asm volatile("s_waitcnt lgkmcnt(" #n ")" ::: "memory")
; #define PG8_BAR __builtin_amdgcn_s_barrier()
; #define PG8_SCHED __builtin_amdgcn_sched_barrier(0)
; template <class Epi, class Sched, bool ALIGN_EPI = false, bool SP2 = false>
; __device__ __forceinline__ void gemm_phase(PG8_LAS unsigned char* lds, const Gemm g, const Sched& S, const Epi& E) {
;     ...
;             PG8_WAIT_V(8); PG8_WAIT_L(0); PG8_BAR; PG8_MMA(1, 0, At, B0); PG8_MMA(1, 1, At, B1); PG8_BAR; PG8_SCHED;
;             PG8_LDB(B0, 1, 0); PG8_LDB(B1, 1, 1); PG8_SCHED; PG8_LDA(At, 1, 0); PG8_STAGE(PG8_SA(0, 1), a2 + hstepA, voffA);
;             PG8_WAIT_V(8); PG8_WAIT_L(0); PG8_BAR; PG8_MMA(0, 0, At, B0); PG8_MMA(0, 1, At, B1); PG8_BAR; PG8_SCHED;
	s_waitcnt lgkmcnt(0)
	v_mfma_f32_16x16x32_bf16 v[62:65], v[130:133], v[174:177], v[62:65]
	v_mfma_f32_16x16x32_bf16 v[58:61], v[138:141], v[174:177], v[58:61]
	v_mfma_f32_16x16x32_bf16 v[54:57], v[130:133], v[182:185], v[54:57]
	v_mfma_f32_16x16x32_bf16 v[50:53], v[138:141], v[182:185], v[50:53]
	v_mfma_f32_16x16x32_bf16 v[46:49], v[130:133], v[190:193], v[46:49]
	v_mfma_f32_16x16x32_bf16 v[38:41], v[138:141], v[190:193], v[38:41]
	v_mfma_f32_16x16x32_bf16 v[18:21], v[130:133], v[198:201], v[18:21]
	v_mfma_f32_16x16x32_bf16 v[10:13], v[138:141], v[198:201], v[10:13]
	v_mfma_f32_16x16x32_bf16 v[62:65], v[134:137], v[178:181], v[62:65]
	v_mfma_f32_16x16x32_bf16 v[58:61], v[142:145], v[178:181], v[58:61]
	v_mfma_f32_16x16x32_bf16 v[54:57], v[134:137], v[186:189], v[54:57]
	v_mfma_f32_16x16x32_bf16 v[50:53], v[142:145], v[186:189], v[50:53]
	v_mfma_f32_16x16x32_bf16 v[46:49], v[134:137], v[194:197], v[46:49]
	v_mfma_f32_16x16x32_bf16 v[38:41], v[142:145], v[194:197], v[38:41]
	v_mfma_f32_16x16x32_bf16 v[18:21], v[134:137], v[202:205], v[18:21]
	v_mfma_f32_16x16x32_bf16 v[10:13], v[142:145], v[202:205], v[10:13]
	v_mfma_f32_16x16x32_bf16 v[42:45], v[152:155], v[174:177], v[42:45]
	v_mfma_f32_16x16x32_bf16 v[34:37], v[166:169], v[174:177], v[34:37]
	v_mfma_f32_16x16x32_bf16 v[30:33], v[152:155], v[182:185], v[30:33]
	v_mfma_f32_16x16x32_bf16 v[26:29], v[166:169], v[182:185], v[26:29]
	v_mfma_f32_16x16x32_bf16 v[22:25], v[152:155], v[190:193], v[22:25]
	v_mfma_f32_16x16x32_bf16 v[14:17], v[166:169], v[190:193], v[14:17]
	v_mfma_f32_16x16x32_bf16 v[6:9], v[152:155], v[198:201], v[6:9]
	v_mfma_f32_16x16x32_bf16 v[2:5], v[166:169], v[198:201], v[2:5]
	v_mfma_f32_16x16x32_bf16 v[42:45], v[162:165], v[178:181], v[42:45]
	v_mfma_f32_16x16x32_bf16 v[34:37], v[170:173], v[178:181], v[34:37]
	v_mfma_f32_16x16x32_bf16 v[30:33], v[162:165], v[186:189], v[30:33]
	v_mfma_f32_16x16x32_bf16 v[26:29], v[170:173], v[186:189], v[26:29]
	v_mfma_f32_16x16x32_bf16 v[22:25], v[162:165], v[194:197], v[22:25]
	v_mfma_f32_16x16x32_bf16 v[14:17], v[170:173], v[194:197], v[14:17]
	v_mfma_f32_16x16x32_bf16 v[6:9], v[162:165], v[202:205], v[6:9]
	v_mfma_f32_16x16x32_bf16 v[2:5], v[170:173], v[202:205], v[2:5]
	s_barrier
	v_add_u32_e32 v142, s83, v1
	v_add_u32_e32 v170, s82, v1
	ds_read_b128 v[130:133], v142
	ds_read_b128 v[134:137], v142 offset:1024
	ds_read_b128 v[138:141], v142 offset:2048
	ds_read_b128 v[142:145], v142 offset:3072
	ds_read_b128 v[152:155], v170
	ds_read_b128 v[162:165], v170 offset:1024
	ds_read_b128 v[166:169], v170 offset:2048
	ds_read_b128 v[170:173], v170 offset:3072
	s_mov_b32 m0, s59
	v_lshl_add_u64 v[214:215], s[36:37], 0, v[148:149]
	ds_read_b128 v[174:177], v160 offset:32768
	ds_read_b128 v[178:181], v160 offset:33792
	ds_read_b128 v[182:185], v160 offset:34816
	ds_read_b128 v[186:189], v160 offset:35840
	ds_read_b128 v[190:193], v160 offset:36864
	ds_read_b128 v[194:197], v160 offset:37888
	ds_read_b128 v[198:201], v160 offset:38912
	ds_read_b128 v[202:205], v160 offset:39936
	global_load_lds_dwordx4 v[214:215], off
	v_lshl_add_u64 v[214:215], s[36:37], 0, v[146:147]
	s_mov_b32 m0, s60
	s_nop 0
	global_load_lds_dwordx4 v[214:215], off
	s_waitcnt vmcnt(8)
	s_waitcnt lgkmcnt(0)
	s_barrier
	s_waitcnt lgkmcnt(0)
	v_mfma_f32_16x16x32_bf16 v[126:129], v[130:133], v[174:177], v[126:129]
	v_mfma_f32_16x16x32_bf16 v[122:125], v[138:141], v[174:177], v[122:125]
	v_mfma_f32_16x16x32_bf16 v[118:121], v[130:133], v[182:185], v[118:121]
	v_mfma_f32_16x16x32_bf16 v[114:117], v[138:141], v[182:185], v[114:117]
	v_mfma_f32_16x16x32_bf16 v[102:105], v[130:133], v[190:193], v[102:105]
	v_mfma_f32_16x16x32_bf16 v[90:93], v[138:141], v[190:193], v[90:93]
	v_mfma_f32_16x16x32_bf16 v[82:85], v[130:133], v[198:201], v[82:85]
	v_mfma_f32_16x16x32_bf16 v[74:77], v[138:141], v[198:201], v[74:77]
	v_mfma_f32_16x16x32_bf16 v[126:129], v[134:137], v[178:181], v[126:129]
	v_mfma_f32_16x16x32_bf16 v[122:125], v[142:145], v[178:181], v[122:125]
	v_mfma_f32_16x16x32_bf16 v[118:121], v[134:137], v[186:189], v[118:121]
	v_mfma_f32_16x16x32_bf16 v[114:117], v[142:145], v[186:189], v[114:117]
	v_mfma_f32_16x16x32_bf16 v[102:105], v[134:137], v[194:197], v[102:105]
	v_mfma_f32_16x16x32_bf16 v[90:93], v[142:145], v[194:197], v[90:93]
	v_mfma_f32_16x16x32_bf16 v[82:85], v[134:137], v[202:205], v[82:85]
	v_mfma_f32_16x16x32_bf16 v[74:77], v[142:145], v[202:205], v[74:77]
	v_mfma_f32_16x16x32_bf16 v[110:113], v[152:155], v[174:177], v[110:113]
	v_mfma_f32_16x16x32_bf16 v[106:109], v[166:169], v[174:177], v[106:109]
	v_mfma_f32_16x16x32_bf16 v[98:101], v[152:155], v[182:185], v[98:101]
	v_mfma_f32_16x16x32_bf16 v[94:97], v[166:169], v[182:185], v[94:97]
	v_mfma_f32_16x16x32_bf16 v[86:89], v[152:155], v[190:193], v[86:89]
	v_mfma_f32_16x16x32_bf16 v[78:81], v[166:169], v[190:193], v[78:81]
	v_mfma_f32_16x16x32_bf16 v[70:73], v[152:155], v[198:201], v[70:73]
	v_mfma_f32_16x16x32_bf16 v[66:69], v[166:169], v[198:201], v[66:69]
	v_mfma_f32_16x16x32_bf16 v[110:113], v[162:165], v[178:181], v[110:113]
	v_mfma_f32_16x16x32_bf16 v[106:109], v[170:173], v[178:181], v[106:109]
	v_mfma_f32_16x16x32_bf16 v[98:101], v[162:165], v[186:189], v[98:101]
	v_mfma_f32_16x16x32_bf16 v[94:97], v[170:173], v[186:189], v[94:97]
	v_mfma_f32_16x16x32_bf16 v[86:89], v[162:165], v[194:197], v[86:89]
	v_mfma_f32_16x16x32_bf16 v[78:81], v[170:173], v[194:197], v[78:81]
	v_mfma_f32_16x16x32_bf16 v[70:73], v[162:165], v[202:205], v[70:73]
	v_mfma_f32_16x16x32_bf16 v[66:69], v[170:173], v[202:205], v[66:69]
	s_barrier
; #define PG8_STAGE(bufoff, gbase, voff) do { _Pragma("unroll") for (int _i = 0; _i < 2; ++_i) \
;         __builtin_amdgcn_global_load_lds((const unsigned*)((const char*)(gbase) + (voff)[_i]), (PG8_LAS unsigned*)(lds + (bufoff) + ldsw + _i * 8192), 16, 0, 0); } while (0)
; #define PG8_LDA(dst, b, h) do { _Pragma("unroll") for (int m = 0; m < 4; ++m) _Pragma("unroll") for (int k = 0; k < 2; ++k) dst[m][k] = *(const PG8_LAS bf16x8*)(lds + PG8_SA(b, h) + aoff + m * 2048 + k * 1024); } while (0)
; #define PG8_MMA(ai, bj, At, Bt) do { __builtin_amdgcn_s_setprio(1); _Pragma("unroll") for (int m = 0; m < 4; ++m) _Pragma("unroll") for (int n = 0; n < 2; ++n) _Pragma("unroll") for (int k = 0; k < 2; ++k) \
;         acc[ai][bj][m][n] = __builtin_amdgcn_mfma_f32_16x16x32_bf16(Bt[n][k], At[m][k], acc[ai][bj][m][n], 0, 0, 0); __builtin_amdgcn_s_setprio(0); } while (0)
; #define PG8_WAIT_V(n) asm volatile("s_waitcnt vmcnt(" #n ")" ::: "memory")
; #define PG8_WAIT_L(n) asm volatile("s_waitcnt lgkmcnt(" #n ")" ::: "memory")
; #define PG8_BAR __builtin_amdgcn_s_barrier()
; #define PG8_SCHED __builtin_amdgcn_sched_barrier(0)
; template <class Epi, class Sched, bool ALIGN_EPI = false, bool SP2 = false>
; __device__ __forceinline__ void gemm_phase(PG8_LAS unsigned char* lds, const Gemm g, const Sched& S, const Epi& E) {
;     ...
;         for (int t = 0; t < nt; t += 2) {
;             const bool last = (t == nt - 2);
;     ...
;             PG8_LDA(At, 1, 1); PG8_STAGE(PG8_SB(1, 0), b3, voffB); PG8_STAGE(PG8_SB(1, 1), b3 + hstepB, voffB); PG8_STAGE(PG8_SA(1, 0), a3, voffA);
;             PG8_WAIT_V(8); PG8_WAIT_L(0); PG8_BAR; PG8_MMA(1, 0, At, B0); PG8_MMA(1, 1, At, B1); PG8_BAR; PG8_SCHED;
	s_mov_b32 m0, s81
	v_lshl_add_u64 v[206:207], v[206:207], 0, s[4:5]
	ds_read_b128 v[174:177], v160 offset:49152
	ds_read_b128 v[178:181], v160 offset:50176
	ds_read_b128 v[182:185], v160 offset:51200
	ds_read_b128 v[186:189], v160 offset:52224
	ds_read_b128 v[190:193], v160 offset:53248
	ds_read_b128 v[194:197], v160 offset:54272
	ds_read_b128 v[198:201], v160 offset:55296
	ds_read_b128 v[202:205], v160 offset:56320
	global_load_lds_dwordx4 v[206:207], off
	v_lshl_add_u64 v[206:207], v[208:209], 0, s[4:5]
	s_mov_b32 m0, s80
	s_nop 0
	global_load_lds_dwordx4 v[206:207], off
	v_lshl_add_u64 v[206:207], s[34:35], 0, v[148:149]
	s_mov_b32 m0, s89
	s_nop 0
	global_load_lds_dwordx4 v[206:207], off
	v_lshl_add_u64 v[206:207], s[34:35], 0, v[146:147]
	s_mov_b32 m0, s88
	s_nop 0
	global_load_lds_dwordx4 v[206:207], off
	v_lshl_add_u64 v[206:207], v[210:211], 0, s[4:5]
	s_mov_b32 m0, s66
	s_nop 0
	global_load_lds_dwordx4 v[206:207], off
	v_lshl_add_u64 v[206:207], v[212:213], 0, s[4:5]
	s_mov_b32 m0, s67
	s_nop 0
	global_load_lds_dwordx4 v[206:207], off
	s_waitcnt vmcnt(8)
	s_waitcnt lgkmcnt(0)
	s_barrier
	s_waitcnt lgkmcnt(0)
	v_mfma_f32_16x16x32_bf16 v[62:65], v[130:133], v[174:177], v[62:65]
	v_mfma_f32_16x16x32_bf16 v[58:61], v[138:141], v[174:177], v[58:61]
	v_mfma_f32_16x16x32_bf16 v[54:57], v[130:133], v[182:185], v[54:57]
	v_mfma_f32_16x16x32_bf16 v[50:53], v[138:141], v[182:185], v[50:53]
	v_mfma_f32_16x16x32_bf16 v[46:49], v[130:133], v[190:193], v[46:49]
	v_mfma_f32_16x16x32_bf16 v[38:41], v[138:141], v[190:193], v[38:41]
	v_mfma_f32_16x16x32_bf16 v[18:21], v[130:133], v[198:201], v[18:21]
	v_mfma_f32_16x16x32_bf16 v[10:13], v[138:141], v[198:201], v[10:13]
	v_mfma_f32_16x16x32_bf16 v[62:65], v[134:137], v[178:181], v[62:65]
	v_mfma_f32_16x16x32_bf16 v[58:61], v[142:145], v[178:181], v[58:61]
	v_mfma_f32_16x16x32_bf16 v[54:57], v[134:137], v[186:189], v[54:57]
	v_mfma_f32_16x16x32_bf16 v[50:53], v[142:145], v[186:189], v[50:53]
	v_mfma_f32_16x16x32_bf16 v[46:49], v[134:137], v[194:197], v[46:49]
	v_mfma_f32_16x16x32_bf16 v[38:41], v[142:145], v[194:197], v[38:41]
	v_mfma_f32_16x16x32_bf16 v[18:21], v[134:137], v[202:205], v[18:21]
	v_mfma_f32_16x16x32_bf16 v[10:13], v[142:145], v[202:205], v[10:13]
	v_mfma_f32_16x16x32_bf16 v[42:45], v[152:155], v[174:177], v[42:45]
	v_mfma_f32_16x16x32_bf16 v[34:37], v[166:169], v[174:177], v[34:37]
	v_mfma_f32_16x16x32_bf16 v[30:33], v[152:155], v[182:185], v[30:33]
	v_mfma_f32_16x16x32_bf16 v[26:29], v[166:169], v[182:185], v[26:29]
	v_mfma_f32_16x16x32_bf16 v[22:25], v[152:155], v[190:193], v[22:25]
	v_mfma_f32_16x16x32_bf16 v[14:17], v[166:169], v[190:193], v[14:17]
	v_mfma_f32_16x16x32_bf16 v[6:9], v[152:155], v[198:201], v[6:9]
	v_mfma_f32_16x16x32_bf16 v[2:5], v[166:169], v[198:201], v[2:5]
	v_mfma_f32_16x16x32_bf16 v[42:45], v[162:165], v[178:181], v[42:45]
	v_mfma_f32_16x16x32_bf16 v[34:37], v[170:173], v[178:181], v[34:37]
	v_mfma_f32_16x16x32_bf16 v[30:33], v[162:165], v[186:189], v[30:33]
	v_mfma_f32_16x16x32_bf16 v[26:29], v[170:173], v[186:189], v[26:29]
	v_mfma_f32_16x16x32_bf16 v[22:25], v[162:165], v[194:197], v[22:25]
	v_mfma_f32_16x16x32_bf16 v[14:17], v[170:173], v[194:197], v[14:17]
	v_mfma_f32_16x16x32_bf16 v[6:9], v[162:165], v[202:205], v[6:9]
	v_mfma_f32_16x16x32_bf16 v[2:5], v[170:173], v[202:205], v[2:5]
	s_barrier
	s_movk_i32 s36, 0x100
	s_andn2_b64 vcc, exec, s[30:31]
	s_mov_b64 s[34:35], -1
	s_mov_b64 s[30:31], 0
	s_cbranch_vccz .LBB0_1324
	s_and_b64 vcc, exec, s[8:9]
	s_cbranch_vccz .LBB0_1327
	s_barrier

; #define PG8_STAGE(bufoff, gbase, voff) do { _Pragma("unroll") for (int _i = 0; _i < 2; ++_i) \
;         __builtin_amdgcn_global_load_lds((const unsigned*)((const char*)(gbase) + (voff)[_i]), (PG8_LAS unsigned*)(lds + (bufoff) + ldsw + _i * 8192), 16, 0, 0); } while (0)
; #define PG8_LDA(dst, b, h) do { _Pragma("unroll") for (int m = 0; m < 4; ++m) _Pragma("unroll") for (int k = 0; k < 2; ++k) dst[m][k] = *(const PG8_LAS bf16x8*)(lds + PG8_SA(b, h) + aoff + m * 2048 + k * 1024); } while (0)
; #define PG8_LDB(dst, b, h) do { _Pragma("unroll") for (int n = 0; n < 2; ++n) _Pragma("unroll") for (int k = 0; k < 2; ++k) dst[n][k] = *(const PG8_LAS bf16x8*)(lds + PG8_SB(b, h) + boff + n * 2048 + k * 1024); } while (0)
; #define PG8_MMA(ai, bj, At, Bt) do { __builtin_amdgcn_s_setprio(1); _Pragma("unroll") for (int m = 0; m < 4; ++m) _Pragma("unroll") for (int n = 0; n < 2; ++n) _Pragma("unroll") for (int k = 0; k < 2; ++k) \
;         acc[ai][bj][m][n] = __builtin_amdgcn_mfma_f32_16x16x32_bf16(Bt[n][k], At[m][k], acc[ai][bj][m][n], 0, 0, 0); __builtin_amdgcn_s_setprio(0); } while (0)
; #define PG8_WAIT_V(n) asm volatile("s_waitcnt vmcnt(" #n ")" ::: "memory")
; #define PG8_BAR __builtin_amdgcn_s_barrier()
; template <class Epi, class Sched, bool ALIGN_EPI = false, bool SP2 = false>
; __device__ __forceinline__ void gemm_phase(PG8_LAS unsigned char* lds, const Gemm g, const Sched& S, const Epi& E) {
;     ...
;         for (int t = 0; t < nt; t += 2) {
;             const bool last = (t == nt - 2);
;             const char* a1 = cA + (size_t)(t + 1) * kstep;
;             const char* a2 = last ? nA : cA + (size_t)(t + 2) * kstep; const char* b2 = last ? nB : cB + (size_t)(t + 2) * kstep;
;             const char* a3 = a2 + kstep; const char* b3 = b2 + kstep;
;             if (last && has_next) S.a_ready(nxt);
;             if constexpr (SP2) {
;             PG8_LDB(B0, 0, 0); PG8_LDB(B1, 0, 1); PG8_SCHED; PG8_LDA(At, 0, 0); PG8_STAGE(PG8_SA(1, 1), a1 + hstepA, voffA);
;             PG8_WAIT_V(8); PG8_WAIT_L(0); PG8_BAR; PG8_MMA(0, 0, At, B0); PG8_MMA(0, 1, At, B1); PG8_BAR; PG8_SCHED;
;             PG8_LDA(At, 0, 1); PG8_STAGE(PG8_SB(0, 0), b2, voffB); PG8_STAGE(PG8_SB(0, 1), b2 + hstepB, voffB); PG8_STAGE(PG8_SA(0, 0), a2, voffA);
;             PG8_WAIT_V(8); PG8_WAIT_L(0); PG8_BAR; PG8_MMA(1, 0, At, B0); PG8_MMA(1, 1, At, B1); PG8_BAR; PG8_SCHED;
.LBB0_1344:
	s_add_u32 s72, s28, s71
	ds_read_b128 v[130:133], v158
	ds_read_b128 v[134:137], v158 offset:1024
	ds_read_b128 v[138:141], v158 offset:2048
	ds_read_b128 v[142:145], v158 offset:3072
	ds_read_b128 v[152:155], v159
	ds_read_b128 v[162:165], v159 offset:1024
	ds_read_b128 v[166:169], v159 offset:2048
	ds_read_b128 v[170:173], v159 offset:3072
	s_addc_u32 s73, s29, 0
	s_add_u32 s74, s72, 0x100
	s_addc_u32 s75, s73, 0
	s_and_b64 s[36:37], s[34:35], exec
	s_cselect_b32 s37, s17, s75
	s_cselect_b32 s36, s69, s74
	s_add_u32 s71, s26, s71
	s_addc_u32 s74, s27, 0
	s_add_u32 s71, s71, 0x100
	s_addc_u32 s74, s74, 0
	s_and_b64 s[34:35], s[34:35], exec
	s_cselect_b32 s35, s15, s74
	s_cselect_b32 s34, s70, s71
	s_add_u32 s72, s72, 0x40080
	s_addc_u32 s73, s73, 0
	v_lshl_add_u64 v[206:207], s[72:73], 0, v[148:149]
	s_add_i32 m0, s49, 0xc000
	ds_read_b128 v[174:177], v160
	ds_read_b128 v[178:181], v160 offset:1024
	ds_read_b128 v[182:185], v160 offset:2048
	ds_read_b128 v[186:189], v160 offset:3072
	ds_read_b128 v[190:193], v160 offset:4096
	ds_read_b128 v[194:197], v160 offset:5120
	ds_read_b128 v[198:201], v160 offset:6144
	ds_read_b128 v[202:205], v160 offset:7168
	global_load_lds_dwordx4 v[206:207], off
	v_lshl_add_u64 v[206:207], s[72:73], 0, v[146:147]
	s_add_i32 m0, s49, 0xe000
	s_nop 0
	global_load_lds_dwordx4 v[206:207], off
	s_waitcnt vmcnt(8)
	s_waitcnt lgkmcnt(0)
	s_barrier
	s_waitcnt lgkmcnt(0)
	v_mfma_f32_16x16x32_bf16 v[126:129], v[130:133], v[174:177], v[126:129]
	v_mfma_f32_16x16x32_bf16 v[122:125], v[138:141], v[174:177], v[122:125]
	v_mfma_f32_16x16x32_bf16 v[118:121], v[130:133], v[182:185], v[118:121]
	v_mfma_f32_16x16x32_bf16 v[114:117], v[138:141], v[182:185], v[114:117]
	v_mfma_f32_16x16x32_bf16 v[102:105], v[130:133], v[190:193], v[102:105]
	v_mfma_f32_16x16x32_bf16 v[90:93], v[138:141], v[190:193], v[90:93]
	v_mfma_f32_16x16x32_bf16 v[82:85], v[130:133], v[198:201], v[82:85]
	v_mfma_f32_16x16x32_bf16 v[74:77], v[138:141], v[198:201], v[74:77]
	v_mfma_f32_16x16x32_bf16 v[126:129], v[134:137], v[178:181], v[126:129]
	v_mfma_f32_16x16x32_bf16 v[122:125], v[142:145], v[178:181], v[122:125]
	v_mfma_f32_16x16x32_bf16 v[118:121], v[134:137], v[186:189], v[118:121]
	v_mfma_f32_16x16x32_bf16 v[114:117], v[142:145], v[186:189], v[114:117]
	v_mfma_f32_16x16x32_bf16 v[102:105], v[134:137], v[194:197], v[102:105]
	v_mfma_f32_16x16x32_bf16 v[90:93], v[142:145], v[194:197], v[90:93]
	v_mfma_f32_16x16x32_bf16 v[82:85], v[134:137], v[202:205], v[82:85]
	v_mfma_f32_16x16x32_bf16 v[74:77], v[142:145], v[202:205], v[74:77]
	v_mfma_f32_16x16x32_bf16 v[110:113], v[152:155], v[174:177], v[110:113]
	v_mfma_f32_16x16x32_bf16 v[106:109], v[166:169], v[174:177], v[106:109]
	v_mfma_f32_16x16x32_bf16 v[98:101], v[152:155], v[182:185], v[98:101]
	v_mfma_f32_16x16x32_bf16 v[94:97], v[166:169], v[182:185], v[94:97]
	v_mfma_f32_16x16x32_bf16 v[86:89], v[152:155], v[190:193], v[86:89]
	v_mfma_f32_16x16x32_bf16 v[78:81], v[166:169], v[190:193], v[78:81]
	v_mfma_f32_16x16x32_bf16 v[70:73], v[152:155], v[198:201], v[70:73]
	v_mfma_f32_16x16x32_bf16 v[66:69], v[166:169], v[198:201], v[66:69]
	v_mfma_f32_16x16x32_bf16 v[110:113], v[162:165], v[178:181], v[110:113]
	v_mfma_f32_16x16x32_bf16 v[106:109], v[170:173], v[178:181], v[106:109]
	v_mfma_f32_16x16x32_bf16 v[98:101], v[162:165], v[186:189], v[98:101]
	v_mfma_f32_16x16x32_bf16 v[94:97], v[170:173], v[186:189], v[94:97]
	v_mfma_f32_16x16x32_bf16 v[86:89], v[162:165], v[194:197], v[86:89]
	v_mfma_f32_16x16x32_bf16 v[78:81], v[170:173], v[194:197], v[78:81]
	v_mfma_f32_16x16x32_bf16 v[70:73], v[162:165], v[202:205], v[70:73]
	v_mfma_f32_16x16x32_bf16 v[66:69], v[170:173], v[202:205], v[66:69]
	s_barrier
	s_add_i32 s71, s61, s45
	v_lshl_add_u64 v[206:207], s[34:35], 0, v[148:149]
	s_mov_b32 m0, s71
	ds_read_b128 v[174:177], v160 offset:16384
	ds_read_b128 v[178:181], v160 offset:17408
	ds_read_b128 v[182:185], v160 offset:18432
	ds_read_b128 v[186:189], v160 offset:19456
	ds_read_b128 v[190:193], v160 offset:20480
	ds_read_b128 v[194:197], v160 offset:21504
	ds_read_b128 v[198:201], v160 offset:22528
	ds_read_b128 v[202:205], v160 offset:23552
	global_load_lds_dwordx4 v[206:207], off
	s_add_i32 m0, s71, 0x2000
	s_add_u32 s72, s34, 0x40000
	v_lshl_add_u64 v[208:209], s[34:35], 0, v[146:147]
	s_addc_u32 s73, s35, 0
	s_add_i32 s71, s62, s45
	global_load_lds_dwordx4 v[208:209], off
	v_lshl_add_u64 v[210:211], s[72:73], 0, v[148:149]
	s_mov_b32 m0, s71
	v_lshl_add_u64 v[212:213], s[36:37], 0, v[146:147]
	global_load_lds_dwordx4 v[210:211], off
	v_lshl_add_u64 v[210:211], s[72:73], 0, v[146:147]
	s_add_i32 m0, s71, 0x2000
	s_nop 0
	global_load_lds_dwordx4 v[210:211], off
	v_lshl_add_u64 v[210:211], s[36:37], 0, v[148:149]
	s_mov_b32 m0, s49
	s_nop 0
	global_load_lds_dwordx4 v[210:211], off
	s_mov_b32 m0, s50
	s_nop 0
	global_load_lds_dwordx4 v[212:213], off
	s_waitcnt vmcnt(8)
	s_waitcnt lgkmcnt(0)
	s_barrier
; #define PG8_STAGE(bufoff, gbase, voff) do { _Pragma("unroll") for (int _i = 0; _i < 2; ++_i) \
;         __builtin_amdgcn_global_load_lds((const unsigned*)((const char*)(gbase) + (voff)[_i]), (PG8_LAS unsigned*)(lds + (bufoff) + ldsw + _i * 8192), 16, 0, 0); } while (0)
; #define PG8_LDA(dst, b, h) do { _Pragma("unroll") for (int m = 0; m < 4; ++m) _Pragma("unroll") for (int k = 0; k < 2; ++k) dst[m][k] = *(const PG8_LAS bf16x8*)(lds + PG8_SA(b, h) + aoff + m * 2048 + k * 1024); } while (0)
; #define PG8_LDB(dst, b, h) do { _Pragma("unroll") for (int n = 0; n < 2; ++n) _Pragma("unroll") for (int k = 0; k < 2; ++k) dst[n][k] = *(const PG8_LAS bf16x8*)(lds + PG8_SB(b, h) + boff + n * 2048 + k * 1024); } while (0)
; #define PG8_MMA(ai, bj, At, Bt) do { __builtin_amdgcn_s_setprio(1); _Pragma("unroll") for (int m = 0; m < 4; ++m) _Pragma("unroll") for (int n = 0; n < 2; ++n) _Pragma("unroll") for (int k = 0; k < 2; ++k) \
;         acc[ai][bj][m][n] = __builtin_amdgcn_mfma_f32_16x16x32_bf16(Bt[n][k], At[m][k], acc[ai][bj][m][n], 0, 0, 0); __builtin_amdgcn_s_setprio(0); } while (0)
; #define PG8_WAIT_V(n) asm volatile("s_waitcnt vmcnt(" #n ")" ::: "memory")
; #define PG8_WAIT_L(n) asm volatile("s_waitcnt lgkmcnt(" #n ")" ::: "memory")
; #define PG8_BAR __builtin_amdgcn_s_barrier()
; #define PG8_SCHED __builtin_amdgcn_sched_barrier(0)
; template <class Epi, class Sched, bool ALIGN_EPI = false, bool SP2 = false>
; __device__ __forceinline__ void gemm_phase(PG8_LAS unsigned char* lds, const Gemm g, const Sched& S, const Epi& E) {
;     ...
;             PG8_WAIT_V(8); PG8_WAIT_L(0); PG8_BAR; PG8_MMA(1, 0, At, B0); PG8_MMA(1, 1, At, B1); PG8_BAR; PG8_SCHED;
;             PG8_LDB(B0, 1, 0); PG8_LDB(B1, 1, 1); PG8_SCHED; PG8_LDA(At, 1, 0); PG8_STAGE(PG8_SA(0, 1), a2 + hstepA, voffA);
;             PG8_WAIT_V(8); PG8_WAIT_L(0); PG8_BAR; PG8_MMA(0, 0, At, B0); PG8_MMA(0, 1, At, B1); PG8_BAR; PG8_SCHED;
	s_waitcnt lgkmcnt(0)
	v_mfma_f32_16x16x32_bf16 v[62:65], v[130:133], v[174:177], v[62:65]
	v_mfma_f32_16x16x32_bf16 v[58:61], v[138:141], v[174:177], v[58:61]
	v_mfma_f32_16x16x32_bf16 v[54:57], v[130:133], v[182:185], v[54:57]
	v_mfma_f32_16x16x32_bf16 v[50:53], v[138:141], v[182:185], v[50:53]
	v_mfma_f32_16x16x32_bf16 v[46:49], v[130:133], v[190:193], v[46:49]
	v_mfma_f32_16x16x32_bf16 v[38:41], v[138:141], v[190:193], v[38:41]
	v_mfma_f32_16x16x32_bf16 v[18:21], v[130:133], v[198:201], v[18:21]
	v_mfma_f32_16x16x32_bf16 v[10:13], v[138:141], v[198:201], v[10:13]
	v_mfma_f32_16x16x32_bf16 v[62:65], v[134:137], v[178:181], v[62:65]
	v_mfma_f32_16x16x32_bf16 v[58:61], v[142:145], v[178:181], v[58:61]
	v_mfma_f32_16x16x32_bf16 v[54:57], v[134:137], v[186:189], v[54:57]
	v_mfma_f32_16x16x32_bf16 v[50:53], v[142:145], v[186:189], v[50:53]
	v_mfma_f32_16x16x32_bf16 v[46:49], v[134:137], v[194:197], v[46:49]
	v_mfma_f32_16x16x32_bf16 v[38:41], v[142:145], v[194:197], v[38:41]
	v_mfma_f32_16x16x32_bf16 v[18:21], v[134:137], v[202:205], v[18:21]
	v_mfma_f32_16x16x32_bf16 v[10:13], v[142:145], v[202:205], v[10:13]
	v_mfma_f32_16x16x32_bf16 v[42:45], v[152:155], v[174:177], v[42:45]
	v_mfma_f32_16x16x32_bf16 v[34:37], v[166:169], v[174:177], v[34:37]
	v_mfma_f32_16x16x32_bf16 v[30:33], v[152:155], v[182:185], v[30:33]
	v_mfma_f32_16x16x32_bf16 v[26:29], v[166:169], v[182:185], v[26:29]
	v_mfma_f32_16x16x32_bf16 v[22:25], v[152:155], v[190:193], v[22:25]
	v_mfma_f32_16x16x32_bf16 v[14:17], v[166:169], v[190:193], v[14:17]
	v_mfma_f32_16x16x32_bf16 v[6:9], v[152:155], v[198:201], v[6:9]
	v_mfma_f32_16x16x32_bf16 v[2:5], v[166:169], v[198:201], v[2:5]
	v_mfma_f32_16x16x32_bf16 v[42:45], v[162:165], v[178:181], v[42:45]
	v_mfma_f32_16x16x32_bf16 v[34:37], v[170:173], v[178:181], v[34:37]
	v_mfma_f32_16x16x32_bf16 v[30:33], v[162:165], v[186:189], v[30:33]
	v_mfma_f32_16x16x32_bf16 v[26:29], v[170:173], v[186:189], v[26:29]
	v_mfma_f32_16x16x32_bf16 v[22:25], v[162:165], v[194:197], v[22:25]
	v_mfma_f32_16x16x32_bf16 v[14:17], v[170:173], v[194:197], v[14:17]
	v_mfma_f32_16x16x32_bf16 v[6:9], v[162:165], v[202:205], v[6:9]
	v_mfma_f32_16x16x32_bf16 v[2:5], v[170:173], v[202:205], v[2:5]
	s_barrier
	s_add_i32 s71, 0, 0x18000
	s_add_i32 s72, 0, 0x1c000
	v_add_u32_e32 v142, s71, v1
	v_add_u32_e32 v170, s72, v1
	ds_read_b128 v[130:133], v142
	ds_read_b128 v[134:137], v142 offset:1024
	ds_read_b128 v[138:141], v142 offset:2048
	ds_read_b128 v[142:145], v142 offset:3072
	ds_read_b128 v[152:155], v170
	ds_read_b128 v[162:165], v170 offset:1024
	ds_read_b128 v[166:169], v170 offset:2048
	ds_read_b128 v[170:173], v170 offset:3072
	s_add_u32 s36, s36, 0x40000
	s_addc_u32 s37, s37, 0
	s_mov_b32 m0, s51
	v_lshl_add_u64 v[214:215], s[36:37], 0, v[148:149]
	ds_read_b128 v[174:177], v160 offset:32768
	ds_read_b128 v[178:181], v160 offset:33792
	ds_read_b128 v[182:185], v160 offset:34816
	ds_read_b128 v[186:189], v160 offset:35840
	ds_read_b128 v[190:193], v160 offset:36864
	ds_read_b128 v[194:197], v160 offset:37888
	ds_read_b128 v[198:201], v160 offset:38912
	ds_read_b128 v[202:205], v160 offset:39936
	global_load_lds_dwordx4 v[214:215], off
	v_lshl_add_u64 v[214:215], s[36:37], 0, v[146:147]
	s_mov_b32 m0, s52
	s_nop 0
	global_load_lds_dwordx4 v[214:215], off
	s_waitcnt vmcnt(8)
	s_waitcnt lgkmcnt(0)
	s_barrier
	s_waitcnt lgkmcnt(0)
	v_mfma_f32_16x16x32_bf16 v[126:129], v[130:133], v[174:177], v[126:129]
	v_mfma_f32_16x16x32_bf16 v[122:125], v[138:141], v[174:177], v[122:125]
	v_mfma_f32_16x16x32_bf16 v[118:121], v[130:133], v[182:185], v[118:121]
	v_mfma_f32_16x16x32_bf16 v[114:117], v[138:141], v[182:185], v[114:117]
	v_mfma_f32_16x16x32_bf16 v[102:105], v[130:133], v[190:193], v[102:105]
	v_mfma_f32_16x16x32_bf16 v[90:93], v[138:141], v[190:193], v[90:93]
	v_mfma_f32_16x16x32_bf16 v[82:85], v[130:133], v[198:201], v[82:85]
	v_mfma_f32_16x16x32_bf16 v[74:77], v[138:141], v[198:201], v[74:77]
	v_mfma_f32_16x16x32_bf16 v[126:129], v[134:137], v[178:181], v[126:129]
	v_mfma_f32_16x16x32_bf16 v[122:125], v[142:145], v[178:181], v[122:125]
	v_mfma_f32_16x16x32_bf16 v[118:121], v[134:137], v[186:189], v[118:121]
	v_mfma_f32_16x16x32_bf16 v[114:117], v[142:145], v[186:189], v[114:117]
	v_mfma_f32_16x16x32_bf16 v[102:105], v[134:137], v[194:197], v[102:105]
	v_mfma_f32_16x16x32_bf16 v[90:93], v[142:145], v[194:197], v[90:93]
	v_mfma_f32_16x16x32_bf16 v[82:85], v[134:137], v[202:205], v[82:85]
	v_mfma_f32_16x16x32_bf16 v[74:77], v[142:145], v[202:205], v[74:77]
	v_mfma_f32_16x16x32_bf16 v[110:113], v[152:155], v[174:177], v[110:113]
	v_mfma_f32_16x16x32_bf16 v[106:109], v[166:169], v[174:177], v[106:109]
	v_mfma_f32_16x16x32_bf16 v[98:101], v[152:155], v[182:185], v[98:101]
	v_mfma_f32_16x16x32_bf16 v[94:97], v[166:169], v[182:185], v[94:97]
	v_mfma_f32_16x16x32_bf16 v[86:89], v[152:155], v[190:193], v[86:89]
	v_mfma_f32_16x16x32_bf16 v[78:81], v[166:169], v[190:193], v[78:81]
	v_mfma_f32_16x16x32_bf16 v[70:73], v[152:155], v[198:201], v[70:73]
	v_mfma_f32_16x16x32_bf16 v[66:69], v[166:169], v[198:201], v[66:69]
	v_mfma_f32_16x16x32_bf16 v[110:113], v[162:165], v[178:181], v[110:113]
	v_mfma_f32_16x16x32_bf16 v[106:109], v[170:173], v[178:181], v[106:109]
	v_mfma_f32_16x16x32_bf16 v[98:101], v[162:165], v[186:189], v[98:101]
	v_mfma_f32_16x16x32_bf16 v[94:97], v[170:173], v[186:189], v[94:97]
	v_mfma_f32_16x16x32_bf16 v[86:89], v[162:165], v[194:197], v[86:89]
	v_mfma_f32_16x16x32_bf16 v[78:81], v[170:173], v[194:197], v[78:81]
	v_mfma_f32_16x16x32_bf16 v[70:73], v[162:165], v[202:205], v[70:73]
	v_mfma_f32_16x16x32_bf16 v[66:69], v[170:173], v[202:205], v[66:69]
	s_barrier
; #define PG8_STAGE(bufoff, gbase, voff) do { _Pragma("unroll") for (int _i = 0; _i < 2; ++_i) \
;         __builtin_amdgcn_global_load_lds((const unsigned*)((const char*)(gbase) + (voff)[_i]), (PG8_LAS unsigned*)(lds + (bufoff) + ldsw + _i * 8192), 16, 0, 0); } while (0)
; #define PG8_LDA(dst, b, h) do { _Pragma("unroll") for (int m = 0; m < 4; ++m) _Pragma("unroll") for (int k = 0; k < 2; ++k) dst[m][k] = *(const PG8_LAS bf16x8*)(lds + PG8_SA(b, h) + aoff + m * 2048 + k * 1024); } while (0)
; #define PG8_MMA(ai, bj, At, Bt) do { __builtin_amdgcn_s_setprio(1); _Pragma("unroll") for (int m = 0; m < 4; ++m) _Pragma("unroll") for (int n = 0; n < 2; ++n) _Pragma("unroll") for (int k = 0; k < 2; ++k) \
;         acc[ai][bj][m][n] = __builtin_amdgcn_mfma_f32_16x16x32_bf16(Bt[n][k], At[m][k], acc[ai][bj][m][n], 0, 0, 0); __builtin_amdgcn_s_setprio(0); } while (0)
; #define PG8_WAIT_V(n) asm volatile("s_waitcnt vmcnt(" #n ")" ::: "memory")
; #define PG8_WAIT_L(n) asm volatile("s_waitcnt lgkmcnt(" #n ")" ::: "memory")
; #define PG8_BAR __builtin_amdgcn_s_barrier()
; #define PG8_SCHED __builtin_amdgcn_sched_barrier(0)
; template <class Epi, class Sched, bool ALIGN_EPI = false, bool SP2 = false>
; __device__ __forceinline__ void gemm_phase(PG8_LAS unsigned char* lds, const Gemm g, const Sched& S, const Epi& E) {
;     ...
;         for (int t = 0; t < nt; t += 2) {
;             const bool last = (t == nt - 2);
;     ...
;             PG8_LDA(At, 1, 1); PG8_STAGE(PG8_SB(1, 0), b3, voffB); PG8_STAGE(PG8_SB(1, 1), b3 + hstepB, voffB); PG8_STAGE(PG8_SA(1, 0), a3, voffA);
;             PG8_WAIT_V(8); PG8_WAIT_L(0); PG8_BAR; PG8_MMA(1, 0, At, B0); PG8_MMA(1, 1, At, B1); PG8_BAR; PG8_SCHED;
	s_add_i32 s36, s71, s45
	v_lshl_add_u64 v[206:207], v[206:207], 0, s[4:5]
	s_mov_b32 m0, s36
	ds_read_b128 v[174:177], v160 offset:49152
	ds_read_b128 v[178:181], v160 offset:50176
	ds_read_b128 v[182:185], v160 offset:51200
	ds_read_b128 v[186:189], v160 offset:52224
	ds_read_b128 v[190:193], v160 offset:53248
	ds_read_b128 v[194:197], v160 offset:54272
	ds_read_b128 v[198:201], v160 offset:55296
	ds_read_b128 v[202:205], v160 offset:56320
	global_load_lds_dwordx4 v[206:207], off
	s_add_i32 m0, s36, 0x2000
	s_add_u32 s34, s34, 0x40080
	v_lshl_add_u64 v[206:207], v[208:209], 0, s[4:5]
	s_addc_u32 s35, s35, 0
	s_add_i32 s36, s72, s45
	global_load_lds_dwordx4 v[206:207], off
	v_lshl_add_u64 v[206:207], s[34:35], 0, v[148:149]
	s_mov_b32 m0, s36
	s_nop 0
	global_load_lds_dwordx4 v[206:207], off
	v_lshl_add_u64 v[206:207], s[34:35], 0, v[146:147]
	s_add_i32 m0, s36, 0x2000
	s_nop 0
	global_load_lds_dwordx4 v[206:207], off
	v_lshl_add_u64 v[206:207], v[210:211], 0, s[4:5]
	s_mov_b32 m0, s59
	s_nop 0
	global_load_lds_dwordx4 v[206:207], off
	v_lshl_add_u64 v[206:207], v[212:213], 0, s[4:5]
	s_mov_b32 m0, s60
	s_nop 0
	global_load_lds_dwordx4 v[206:207], off
	s_waitcnt vmcnt(8)
	s_waitcnt lgkmcnt(0)
	s_barrier
	s_waitcnt lgkmcnt(0)
	v_mfma_f32_16x16x32_bf16 v[62:65], v[130:133], v[174:177], v[62:65]
	v_mfma_f32_16x16x32_bf16 v[58:61], v[138:141], v[174:177], v[58:61]
	v_mfma_f32_16x16x32_bf16 v[54:57], v[130:133], v[182:185], v[54:57]
	v_mfma_f32_16x16x32_bf16 v[50:53], v[138:141], v[182:185], v[50:53]
	v_mfma_f32_16x16x32_bf16 v[46:49], v[130:133], v[190:193], v[46:49]
	v_mfma_f32_16x16x32_bf16 v[38:41], v[138:141], v[190:193], v[38:41]
	v_mfma_f32_16x16x32_bf16 v[18:21], v[130:133], v[198:201], v[18:21]
	v_mfma_f32_16x16x32_bf16 v[10:13], v[138:141], v[198:201], v[10:13]
	v_mfma_f32_16x16x32_bf16 v[62:65], v[134:137], v[178:181], v[62:65]
	v_mfma_f32_16x16x32_bf16 v[58:61], v[142:145], v[178:181], v[58:61]
	v_mfma_f32_16x16x32_bf16 v[54:57], v[134:137], v[186:189], v[54:57]
	v_mfma_f32_16x16x32_bf16 v[50:53], v[142:145], v[186:189], v[50:53]
	v_mfma_f32_16x16x32_bf16 v[46:49], v[134:137], v[194:197], v[46:49]
	v_mfma_f32_16x16x32_bf16 v[38:41], v[142:145], v[194:197], v[38:41]
	v_mfma_f32_16x16x32_bf16 v[18:21], v[134:137], v[202:205], v[18:21]
	v_mfma_f32_16x16x32_bf16 v[10:13], v[142:145], v[202:205], v[10:13]
	v_mfma_f32_16x16x32_bf16 v[42:45], v[152:155], v[174:177], v[42:45]
	v_mfma_f32_16x16x32_bf16 v[34:37], v[166:169], v[174:177], v[34:37]
	v_mfma_f32_16x16x32_bf16 v[30:33], v[152:155], v[182:185], v[30:33]
	v_mfma_f32_16x16x32_bf16 v[26:29], v[166:169], v[182:185], v[26:29]
	v_mfma_f32_16x16x32_bf16 v[22:25], v[152:155], v[190:193], v[22:25]
	v_mfma_f32_16x16x32_bf16 v[14:17], v[166:169], v[190:193], v[14:17]
	v_mfma_f32_16x16x32_bf16 v[6:9], v[152:155], v[198:201], v[6:9]
	v_mfma_f32_16x16x32_bf16 v[2:5], v[166:169], v[198:201], v[2:5]
	v_mfma_f32_16x16x32_bf16 v[42:45], v[162:165], v[178:181], v[42:45]
	v_mfma_f32_16x16x32_bf16 v[34:37], v[170:173], v[178:181], v[34:37]
	v_mfma_f32_16x16x32_bf16 v[30:33], v[162:165], v[186:189], v[30:33]
	v_mfma_f32_16x16x32_bf16 v[26:29], v[170:173], v[186:189], v[26:29]
	v_mfma_f32_16x16x32_bf16 v[22:25], v[162:165], v[194:197], v[22:25]
	v_mfma_f32_16x16x32_bf16 v[14:17], v[170:173], v[194:197], v[14:17]
	v_mfma_f32_16x16x32_bf16 v[6:9], v[162:165], v[202:205], v[6:9]
	v_mfma_f32_16x16x32_bf16 v[2:5], v[170:173], v[202:205], v[2:5]
	s_barrier
	s_movk_i32 s71, 0x100
	s_and_b64 vcc, exec, s[30:31]
	s_mov_b64 s[34:35], -1
	s_mov_b64 s[30:31], 0
	s_cbranch_vccnz .LBB0_1344
	s_andn2_b64 vcc, exec, s[8:9]
	s_cbranch_vccnz .LBB0_1347
	s_barrier

; #define PG8_STAGE(bufoff, gbase, voff) do { _Pragma("unroll") for (int _i = 0; _i < 2; ++_i) \
;         __builtin_amdgcn_global_load_lds((const unsigned*)((const char*)(gbase) + (voff)[_i]), (PG8_LAS unsigned*)(lds + (bufoff) + ldsw + _i * 8192), 16, 0, 0); } while (0)
; #define PG8_LDA(dst, b, h) do { _Pragma("unroll") for (int m = 0; m < 4; ++m) _Pragma("unroll") for (int k = 0; k < 2; ++k) dst[m][k] = *(const PG8_LAS bf16x8*)(lds + PG8_SA(b, h) + aoff + m * 2048 + k * 1024); } while (0)
; #define PG8_LDB(dst, b, h) do { _Pragma("unroll") for (int n = 0; n < 2; ++n) _Pragma("unroll") for (int k = 0; k < 2; ++k) dst[n][k] = *(const PG8_LAS bf16x8*)(lds + PG8_SB(b, h) + boff + n * 2048 + k * 1024); } while (0)
; #define PG8_MMA(ai, bj, At, Bt) do { __builtin_amdgcn_s_setprio(1); _Pragma("unroll") for (int m = 0; m < 4; ++m) _Pragma("unroll") for (int n = 0; n < 2; ++n) _Pragma("unroll") for (int k = 0; k < 2; ++k) \
;         acc[ai][bj][m][n] = __builtin_amdgcn_mfma_f32_16x16x32_bf16(Bt[n][k], At[m][k], acc[ai][bj][m][n], 0, 0, 0); __builtin_amdgcn_s_setprio(0); } while (0)
; #define PG8_WAIT_V(n) asm volatile("s_waitcnt vmcnt(" #n ")" ::: "memory")
; #define PG8_BAR __builtin_amdgcn_s_barrier()
; template <class Epi, class Sched, bool ALIGN_EPI = false, bool SP2 = false>
; __device__ __forceinline__ void gemm_phase(PG8_LAS unsigned char* lds, const Gemm g, const Sched& S, const Epi& E) {
;     ...
;         for (int t = 0; t < nt; t += 2) {
;             const bool last = (t == nt - 2);
;             const char* a1 = cA + (size_t)(t + 1) * kstep;
;             const char* a2 = last ? nA : cA + (size_t)(t + 2) * kstep; const char* b2 = last ? nB : cB + (size_t)(t + 2) * kstep;
;             const char* a3 = a2 + kstep; const char* b3 = b2 + kstep;
;             if (last && has_next) S.a_ready(nxt);
;             if constexpr (SP2) {
;             PG8_LDB(B0, 0, 0); PG8_LDB(B1, 0, 1); PG8_SCHED; PG8_LDA(At, 0, 0); PG8_STAGE(PG8_SA(1, 1), a1 + hstepA, voffA);
;             PG8_WAIT_V(8); PG8_WAIT_L(0); PG8_BAR; PG8_MMA(0, 0, At, B0); PG8_MMA(0, 1, At, B1); PG8_BAR; PG8_SCHED;
;             PG8_LDA(At, 0, 1); PG8_STAGE(PG8_SB(0, 0), b2, voffB); PG8_STAGE(PG8_SB(0, 1), b2 + hstepB, voffB); PG8_STAGE(PG8_SA(0, 0), a2, voffA);
;             PG8_WAIT_V(8); PG8_WAIT_L(0); PG8_BAR; PG8_MMA(1, 0, At, B0); PG8_MMA(1, 1, At, B1); PG8_BAR; PG8_SCHED;
.LBB0_1364:
	s_add_u32 s73, s28, s72
	ds_read_b128 v[130:133], v158
	ds_read_b128 v[134:137], v158 offset:1024
	ds_read_b128 v[138:141], v158 offset:2048
	ds_read_b128 v[142:145], v158 offset:3072
	ds_read_b128 v[152:155], v159
	ds_read_b128 v[162:165], v159 offset:1024
	ds_read_b128 v[166:169], v159 offset:2048
	ds_read_b128 v[170:173], v159 offset:3072
	s_addc_u32 s74, s29, 0
	s_add_u32 s75, s73, 0x100
	s_addc_u32 s76, s74, 0
	s_and_b64 s[36:37], s[34:35], exec
	s_cselect_b32 s37, s17, s76
	s_cselect_b32 s36, s70, s75
	s_add_u32 s72, s26, s72
	s_addc_u32 s75, s27, 0
	s_add_u32 s72, s72, 0x100
	s_addc_u32 s75, s75, 0
	s_and_b64 s[34:35], s[34:35], exec
	s_cselect_b32 s35, s15, s75
	s_cselect_b32 s34, s71, s72
	s_add_u32 s72, s73, 0x40080
	s_addc_u32 s73, s74, 0
	v_lshl_add_u64 v[206:207], s[72:73], 0, v[148:149]
	s_add_i32 m0, s50, 0xc000
	ds_read_b128 v[174:177], v160
	ds_read_b128 v[178:181], v160 offset:1024
	ds_read_b128 v[182:185], v160 offset:2048
	ds_read_b128 v[186:189], v160 offset:3072
	ds_read_b128 v[190:193], v160 offset:4096
	ds_read_b128 v[194:197], v160 offset:5120
	ds_read_b128 v[198:201], v160 offset:6144
	ds_read_b128 v[202:205], v160 offset:7168
	global_load_lds_dwordx4 v[206:207], off
	v_lshl_add_u64 v[206:207], s[72:73], 0, v[146:147]
	s_add_i32 m0, s50, 0xe000
	s_nop 0
	global_load_lds_dwordx4 v[206:207], off
	s_waitcnt vmcnt(8)
	s_waitcnt lgkmcnt(0)
	s_barrier
	s_waitcnt lgkmcnt(0)
	v_mfma_f32_16x16x32_bf16 v[126:129], v[130:133], v[174:177], v[126:129]
	v_mfma_f32_16x16x32_bf16 v[122:125], v[138:141], v[174:177], v[122:125]
	v_mfma_f32_16x16x32_bf16 v[118:121], v[130:133], v[182:185], v[118:121]
	v_mfma_f32_16x16x32_bf16 v[114:117], v[138:141], v[182:185], v[114:117]
	v_mfma_f32_16x16x32_bf16 v[102:105], v[130:133], v[190:193], v[102:105]
	v_mfma_f32_16x16x32_bf16 v[90:93], v[138:141], v[190:193], v[90:93]
	v_mfma_f32_16x16x32_bf16 v[82:85], v[130:133], v[198:201], v[82:85]
	v_mfma_f32_16x16x32_bf16 v[74:77], v[138:141], v[198:201], v[74:77]
	v_mfma_f32_16x16x32_bf16 v[126:129], v[134:137], v[178:181], v[126:129]
	v_mfma_f32_16x16x32_bf16 v[122:125], v[142:145], v[178:181], v[122:125]
	v_mfma_f32_16x16x32_bf16 v[118:121], v[134:137], v[186:189], v[118:121]
	v_mfma_f32_16x16x32_bf16 v[114:117], v[142:145], v[186:189], v[114:117]
	v_mfma_f32_16x16x32_bf16 v[102:105], v[134:137], v[194:197], v[102:105]
	v_mfma_f32_16x16x32_bf16 v[90:93], v[142:145], v[194:197], v[90:93]
	v_mfma_f32_16x16x32_bf16 v[82:85], v[134:137], v[202:205], v[82:85]
	v_mfma_f32_16x16x32_bf16 v[74:77], v[142:145], v[202:205], v[74:77]
	v_mfma_f32_16x16x32_bf16 v[110:113], v[152:155], v[174:177], v[110:113]
	v_mfma_f32_16x16x32_bf16 v[106:109], v[166:169], v[174:177], v[106:109]
	v_mfma_f32_16x16x32_bf16 v[98:101], v[152:155], v[182:185], v[98:101]
	v_mfma_f32_16x16x32_bf16 v[94:97], v[166:169], v[182:185], v[94:97]
	v_mfma_f32_16x16x32_bf16 v[86:89], v[152:155], v[190:193], v[86:89]
	v_mfma_f32_16x16x32_bf16 v[78:81], v[166:169], v[190:193], v[78:81]
	v_mfma_f32_16x16x32_bf16 v[70:73], v[152:155], v[198:201], v[70:73]
	v_mfma_f32_16x16x32_bf16 v[66:69], v[166:169], v[198:201], v[66:69]
	v_mfma_f32_16x16x32_bf16 v[110:113], v[162:165], v[178:181], v[110:113]
	v_mfma_f32_16x16x32_bf16 v[106:109], v[170:173], v[178:181], v[106:109]
	v_mfma_f32_16x16x32_bf16 v[98:101], v[162:165], v[186:189], v[98:101]
	v_mfma_f32_16x16x32_bf16 v[94:97], v[170:173], v[186:189], v[94:97]
	v_mfma_f32_16x16x32_bf16 v[86:89], v[162:165], v[194:197], v[86:89]
	v_mfma_f32_16x16x32_bf16 v[78:81], v[170:173], v[194:197], v[78:81]
	v_mfma_f32_16x16x32_bf16 v[70:73], v[162:165], v[202:205], v[70:73]
	v_mfma_f32_16x16x32_bf16 v[66:69], v[170:173], v[202:205], v[66:69]
	s_barrier
	s_add_i32 s72, s62, s48
	v_lshl_add_u64 v[206:207], s[34:35], 0, v[148:149]
	s_mov_b32 m0, s72
	ds_read_b128 v[174:177], v160 offset:16384
	ds_read_b128 v[178:181], v160 offset:17408
	ds_read_b128 v[182:185], v160 offset:18432
	ds_read_b128 v[186:189], v160 offset:19456
	ds_read_b128 v[190:193], v160 offset:20480
	ds_read_b128 v[194:197], v160 offset:21504
	ds_read_b128 v[198:201], v160 offset:22528
	ds_read_b128 v[202:205], v160 offset:23552
	global_load_lds_dwordx4 v[206:207], off
	s_add_i32 m0, s72, 0x2000
	s_add_u32 s72, s34, 0x40000
	v_lshl_add_u64 v[208:209], s[34:35], 0, v[146:147]
	s_addc_u32 s73, s35, 0
	s_add_i32 s74, s63, s48
	global_load_lds_dwordx4 v[208:209], off
	v_lshl_add_u64 v[210:211], s[72:73], 0, v[148:149]
	s_mov_b32 m0, s74
	v_lshl_add_u64 v[212:213], s[36:37], 0, v[146:147]
	global_load_lds_dwordx4 v[210:211], off
	v_lshl_add_u64 v[210:211], s[72:73], 0, v[146:147]
	s_add_i32 m0, s74, 0x2000
	s_nop 0
	global_load_lds_dwordx4 v[210:211], off
	v_lshl_add_u64 v[210:211], s[36:37], 0, v[148:149]
	s_mov_b32 m0, s50
	s_nop 0
	global_load_lds_dwordx4 v[210:211], off
	s_mov_b32 m0, s51
	s_nop 0
	global_load_lds_dwordx4 v[212:213], off
	s_waitcnt vmcnt(8)
	s_waitcnt lgkmcnt(0)
	s_barrier
; #define PG8_STAGE(bufoff, gbase, voff) do { _Pragma("unroll") for (int _i = 0; _i < 2; ++_i) \
;         __builtin_amdgcn_global_load_lds((const unsigned*)((const char*)(gbase) + (voff)[_i]), (PG8_LAS unsigned*)(lds + (bufoff) + ldsw + _i * 8192), 16, 0, 0); } while (0)
; #define PG8_LDA(dst, b, h) do { _Pragma("unroll") for (int m = 0; m < 4; ++m) _Pragma("unroll") for (int k = 0; k < 2; ++k) dst[m][k] = *(const PG8_LAS bf16x8*)(lds + PG8_SA(b, h) + aoff + m * 2048 + k * 1024); } while (0)
; #define PG8_LDB(dst, b, h) do { _Pragma("unroll") for (int n = 0; n < 2; ++n) _Pragma("unroll") for (int k = 0; k < 2; ++k) dst[n][k] = *(const PG8_LAS bf16x8*)(lds + PG8_SB(b, h) + boff + n * 2048 + k * 1024); } while (0)
; #define PG8_MMA(ai, bj, At, Bt) do { __builtin_amdgcn_s_setprio(1); _Pragma("unroll") for (int m = 0; m < 4; ++m) _Pragma("unroll") for (int n = 0; n < 2; ++n) _Pragma("unroll") for (int k = 0; k < 2; ++k) \
;         acc[ai][bj][m][n] = __builtin_amdgcn_mfma_f32_16x16x32_bf16(Bt[n][k], At[m][k], acc[ai][bj][m][n], 0, 0, 0); __builtin_amdgcn_s_setprio(0); } while (0)
; #define PG8_WAIT_V(n) asm volatile("s_waitcnt vmcnt(" #n ")" ::: "memory")
; #define PG8_WAIT_L(n) asm volatile("s_waitcnt lgkmcnt(" #n ")" ::: "memory")
; #define PG8_BAR __builtin_amdgcn_s_barrier()
; #define PG8_SCHED __builtin_amdgcn_sched_barrier(0)
; template <class Epi, class Sched, bool ALIGN_EPI = false, bool SP2 = false>
; __device__ __forceinline__ void gemm_phase(PG8_LAS unsigned char* lds, const Gemm g, const Sched& S, const Epi& E) {
;     ...
;             PG8_WAIT_V(8); PG8_WAIT_L(0); PG8_BAR; PG8_MMA(1, 0, At, B0); PG8_MMA(1, 1, At, B1); PG8_BAR; PG8_SCHED;
;             PG8_LDB(B0, 1, 0); PG8_LDB(B1, 1, 1); PG8_SCHED; PG8_LDA(At, 1, 0); PG8_STAGE(PG8_SA(0, 1), a2 + hstepA, voffA);
;             PG8_WAIT_V(8); PG8_WAIT_L(0); PG8_BAR; PG8_MMA(0, 0, At, B0); PG8_MMA(0, 1, At, B1); PG8_BAR; PG8_SCHED;
	s_waitcnt lgkmcnt(0)
	v_mfma_f32_16x16x32_bf16 v[62:65], v[130:133], v[174:177], v[62:65]
	v_mfma_f32_16x16x32_bf16 v[58:61], v[138:141], v[174:177], v[58:61]
	v_mfma_f32_16x16x32_bf16 v[54:57], v[130:133], v[182:185], v[54:57]
	v_mfma_f32_16x16x32_bf16 v[50:53], v[138:141], v[182:185], v[50:53]
	v_mfma_f32_16x16x32_bf16 v[46:49], v[130:133], v[190:193], v[46:49]
	v_mfma_f32_16x16x32_bf16 v[38:41], v[138:141], v[190:193], v[38:41]
	v_mfma_f32_16x16x32_bf16 v[18:21], v[130:133], v[198:201], v[18:21]
	v_mfma_f32_16x16x32_bf16 v[10:13], v[138:141], v[198:201], v[10:13]
	v_mfma_f32_16x16x32_bf16 v[62:65], v[134:137], v[178:181], v[62:65]
	v_mfma_f32_16x16x32_bf16 v[58:61], v[142:145], v[178:181], v[58:61]
	v_mfma_f32_16x16x32_bf16 v[54:57], v[134:137], v[186:189], v[54:57]
	v_mfma_f32_16x16x32_bf16 v[50:53], v[142:145], v[186:189], v[50:53]
	v_mfma_f32_16x16x32_bf16 v[46:49], v[134:137], v[194:197], v[46:49]
	v_mfma_f32_16x16x32_bf16 v[38:41], v[142:145], v[194:197], v[38:41]
	v_mfma_f32_16x16x32_bf16 v[18:21], v[134:137], v[202:205], v[18:21]
	v_mfma_f32_16x16x32_bf16 v[10:13], v[142:145], v[202:205], v[10:13]
	v_mfma_f32_16x16x32_bf16 v[42:45], v[152:155], v[174:177], v[42:45]
	v_mfma_f32_16x16x32_bf16 v[34:37], v[166:169], v[174:177], v[34:37]
	v_mfma_f32_16x16x32_bf16 v[30:33], v[152:155], v[182:185], v[30:33]
	v_mfma_f32_16x16x32_bf16 v[26:29], v[166:169], v[182:185], v[26:29]
	v_mfma_f32_16x16x32_bf16 v[22:25], v[152:155], v[190:193], v[22:25]
	v_mfma_f32_16x16x32_bf16 v[14:17], v[166:169], v[190:193], v[14:17]
	v_mfma_f32_16x16x32_bf16 v[6:9], v[152:155], v[198:201], v[6:9]
	v_mfma_f32_16x16x32_bf16 v[2:5], v[166:169], v[198:201], v[2:5]
	v_mfma_f32_16x16x32_bf16 v[42:45], v[162:165], v[178:181], v[42:45]
	v_mfma_f32_16x16x32_bf16 v[34:37], v[170:173], v[178:181], v[34:37]
	v_mfma_f32_16x16x32_bf16 v[30:33], v[162:165], v[186:189], v[30:33]
	v_mfma_f32_16x16x32_bf16 v[26:29], v[170:173], v[186:189], v[26:29]
	v_mfma_f32_16x16x32_bf16 v[22:25], v[162:165], v[194:197], v[22:25]
	v_mfma_f32_16x16x32_bf16 v[14:17], v[170:173], v[194:197], v[14:17]
	v_mfma_f32_16x16x32_bf16 v[6:9], v[162:165], v[202:205], v[6:9]
	v_mfma_f32_16x16x32_bf16 v[2:5], v[170:173], v[202:205], v[2:5]
	s_barrier
	s_add_i32 s72, 0, 0x18000
	s_add_i32 s73, 0, 0x1c000
	v_add_u32_e32 v142, s72, v1
	v_add_u32_e32 v170, s73, v1
	ds_read_b128 v[130:133], v142
	ds_read_b128 v[134:137], v142 offset:1024
	ds_read_b128 v[138:141], v142 offset:2048
	ds_read_b128 v[142:145], v142 offset:3072
	ds_read_b128 v[152:155], v170
	ds_read_b128 v[162:165], v170 offset:1024
	ds_read_b128 v[166:169], v170 offset:2048
	ds_read_b128 v[170:173], v170 offset:3072
	s_add_u32 s36, s36, 0x40000
	s_addc_u32 s37, s37, 0
	s_mov_b32 m0, s52
	v_lshl_add_u64 v[214:215], s[36:37], 0, v[148:149]
	ds_read_b128 v[174:177], v160 offset:32768
	ds_read_b128 v[178:181], v160 offset:33792
	ds_read_b128 v[182:185], v160 offset:34816
	ds_read_b128 v[186:189], v160 offset:35840
	ds_read_b128 v[190:193], v160 offset:36864
	ds_read_b128 v[194:197], v160 offset:37888
	ds_read_b128 v[198:201], v160 offset:38912
	ds_read_b128 v[202:205], v160 offset:39936
	global_load_lds_dwordx4 v[214:215], off
	v_lshl_add_u64 v[214:215], s[36:37], 0, v[146:147]
	s_mov_b32 m0, s53
	s_nop 0
	global_load_lds_dwordx4 v[214:215], off
	s_waitcnt vmcnt(8)
	s_waitcnt lgkmcnt(0)
	s_barrier
	s_waitcnt lgkmcnt(0)
	v_mfma_f32_16x16x32_bf16 v[126:129], v[130:133], v[174:177], v[126:129]
	v_mfma_f32_16x16x32_bf16 v[122:125], v[138:141], v[174:177], v[122:125]
	v_mfma_f32_16x16x32_bf16 v[118:121], v[130:133], v[182:185], v[118:121]
	v_mfma_f32_16x16x32_bf16 v[114:117], v[138:141], v[182:185], v[114:117]
	v_mfma_f32_16x16x32_bf16 v[102:105], v[130:133], v[190:193], v[102:105]
	v_mfma_f32_16x16x32_bf16 v[90:93], v[138:141], v[190:193], v[90:93]
	v_mfma_f32_16x16x32_bf16 v[82:85], v[130:133], v[198:201], v[82:85]
	v_mfma_f32_16x16x32_bf16 v[74:77], v[138:141], v[198:201], v[74:77]
	v_mfma_f32_16x16x32_bf16 v[126:129], v[134:137], v[178:181], v[126:129]
	v_mfma_f32_16x16x32_bf16 v[122:125], v[142:145], v[178:181], v[122:125]
	v_mfma_f32_16x16x32_bf16 v[118:121], v[134:137], v[186:189], v[118:121]
	v_mfma_f32_16x16x32_bf16 v[114:117], v[142:145], v[186:189], v[114:117]
	v_mfma_f32_16x16x32_bf16 v[102:105], v[134:137], v[194:197], v[102:105]
	v_mfma_f32_16x16x32_bf16 v[90:93], v[142:145], v[194:197], v[90:93]
	v_mfma_f32_16x16x32_bf16 v[82:85], v[134:137], v[202:205], v[82:85]
	v_mfma_f32_16x16x32_bf16 v[74:77], v[142:145], v[202:205], v[74:77]
	v_mfma_f32_16x16x32_bf16 v[110:113], v[152:155], v[174:177], v[110:113]
	v_mfma_f32_16x16x32_bf16 v[106:109], v[166:169], v[174:177], v[106:109]
	v_mfma_f32_16x16x32_bf16 v[98:101], v[152:155], v[182:185], v[98:101]
	v_mfma_f32_16x16x32_bf16 v[94:97], v[166:169], v[182:185], v[94:97]
	v_mfma_f32_16x16x32_bf16 v[86:89], v[152:155], v[190:193], v[86:89]
	v_mfma_f32_16x16x32_bf16 v[78:81], v[166:169], v[190:193], v[78:81]
	v_mfma_f32_16x16x32_bf16 v[70:73], v[152:155], v[198:201], v[70:73]
	v_mfma_f32_16x16x32_bf16 v[66:69], v[166:169], v[198:201], v[66:69]
	v_mfma_f32_16x16x32_bf16 v[110:113], v[162:165], v[178:181], v[110:113]
	v_mfma_f32_16x16x32_bf16 v[106:109], v[170:173], v[178:181], v[106:109]
	v_mfma_f32_16x16x32_bf16 v[98:101], v[162:165], v[186:189], v[98:101]
	v_mfma_f32_16x16x32_bf16 v[94:97], v[170:173], v[186:189], v[94:97]
	v_mfma_f32_16x16x32_bf16 v[86:89], v[162:165], v[194:197], v[86:89]
	v_mfma_f32_16x16x32_bf16 v[78:81], v[170:173], v[194:197], v[78:81]
	v_mfma_f32_16x16x32_bf16 v[70:73], v[162:165], v[202:205], v[70:73]
	v_mfma_f32_16x16x32_bf16 v[66:69], v[170:173], v[202:205], v[66:69]
	s_barrier
; #define PG8_STAGE(bufoff, gbase, voff) do { _Pragma("unroll") for (int _i = 0; _i < 2; ++_i) \
;         __builtin_amdgcn_global_load_lds((const unsigned*)((const char*)(gbase) + (voff)[_i]), (PG8_LAS unsigned*)(lds + (bufoff) + ldsw + _i * 8192), 16, 0, 0); } while (0)
; #define PG8_LDA(dst, b, h) do { _Pragma("unroll") for (int m = 0; m < 4; ++m) _Pragma("unroll") for (int k = 0; k < 2; ++k) dst[m][k] = *(const PG8_LAS bf16x8*)(lds + PG8_SA(b, h) + aoff + m * 2048 + k * 1024); } while (0)
; #define PG8_MMA(ai, bj, At, Bt) do { __builtin_amdgcn_s_setprio(1); _Pragma("unroll") for (int m = 0; m < 4; ++m) _Pragma("unroll") for (int n = 0; n < 2; ++n) _Pragma("unroll") for (int k = 0; k < 2; ++k) \
;         acc[ai][bj][m][n] = __builtin_amdgcn_mfma_f32_16x16x32_bf16(Bt[n][k], At[m][k], acc[ai][bj][m][n], 0, 0, 0); __builtin_amdgcn_s_setprio(0); } while (0)
; #define PG8_WAIT_V(n) asm volatile("s_waitcnt vmcnt(" #n ")" ::: "memory")
; #define PG8_WAIT_L(n) asm volatile("s_waitcnt lgkmcnt(" #n ")" ::: "memory")
; #define PG8_BAR __builtin_amdgcn_s_barrier()
; #define PG8_SCHED __builtin_amdgcn_sched_barrier(0)
; template <class Epi, class Sched, bool ALIGN_EPI = false, bool SP2 = false>
; __device__ __forceinline__ void gemm_phase(PG8_LAS unsigned char* lds, const Gemm g, const Sched& S, const Epi& E) {
;     ...
;             PG8_LDA(At, 1, 1); PG8_STAGE(PG8_SB(1, 0), b3, voffB); PG8_STAGE(PG8_SB(1, 1), b3 + hstepB, voffB); PG8_STAGE(PG8_SA(1, 0), a3, voffA);
;             PG8_WAIT_V(8); PG8_WAIT_L(0); PG8_BAR; PG8_MMA(1, 0, At, B0); PG8_MMA(1, 1, At, B1); PG8_BAR; PG8_SCHED;
;     ...
;         if constexpr (ALIGN_EPI) { if (wr == 0) PG8_BAR; }
	s_add_i32 s36, s72, s48
	v_lshl_add_u64 v[206:207], v[206:207], 0, s[4:5]
	s_mov_b32 m0, s36
	ds_read_b128 v[174:177], v160 offset:49152
	ds_read_b128 v[178:181], v160 offset:50176
	ds_read_b128 v[182:185], v160 offset:51200
	ds_read_b128 v[186:189], v160 offset:52224
	ds_read_b128 v[190:193], v160 offset:53248
	ds_read_b128 v[194:197], v160 offset:54272
	ds_read_b128 v[198:201], v160 offset:55296
	ds_read_b128 v[202:205], v160 offset:56320
	global_load_lds_dwordx4 v[206:207], off
	s_add_i32 m0, s36, 0x2000
	s_add_u32 s34, s34, 0x40080
	v_lshl_add_u64 v[206:207], v[208:209], 0, s[4:5]
	s_addc_u32 s35, s35, 0
	s_add_i32 s36, s73, s48
	global_load_lds_dwordx4 v[206:207], off
	v_lshl_add_u64 v[206:207], s[34:35], 0, v[148:149]
	s_mov_b32 m0, s36
	s_nop 0
	global_load_lds_dwordx4 v[206:207], off
	v_lshl_add_u64 v[206:207], s[34:35], 0, v[146:147]
	s_add_i32 m0, s36, 0x2000
	s_nop 0
	global_load_lds_dwordx4 v[206:207], off
	v_lshl_add_u64 v[206:207], v[210:211], 0, s[4:5]
	s_mov_b32 m0, s59
	s_nop 0
	global_load_lds_dwordx4 v[206:207], off
	v_lshl_add_u64 v[206:207], v[212:213], 0, s[4:5]
	s_mov_b32 m0, s60
	s_nop 0
	global_load_lds_dwordx4 v[206:207], off
	s_waitcnt vmcnt(8)
	s_waitcnt lgkmcnt(0)
	s_barrier
	s_waitcnt lgkmcnt(0)
	v_mfma_f32_16x16x32_bf16 v[62:65], v[130:133], v[174:177], v[62:65]
	v_mfma_f32_16x16x32_bf16 v[58:61], v[138:141], v[174:177], v[58:61]
	v_mfma_f32_16x16x32_bf16 v[54:57], v[130:133], v[182:185], v[54:57]
	v_mfma_f32_16x16x32_bf16 v[50:53], v[138:141], v[182:185], v[50:53]
	v_mfma_f32_16x16x32_bf16 v[46:49], v[130:133], v[190:193], v[46:49]
	v_mfma_f32_16x16x32_bf16 v[38:41], v[138:141], v[190:193], v[38:41]
	v_mfma_f32_16x16x32_bf16 v[18:21], v[130:133], v[198:201], v[18:21]
	v_mfma_f32_16x16x32_bf16 v[10:13], v[138:141], v[198:201], v[10:13]
	v_mfma_f32_16x16x32_bf16 v[62:65], v[134:137], v[178:181], v[62:65]
	v_mfma_f32_16x16x32_bf16 v[58:61], v[142:145], v[178:181], v[58:61]
	v_mfma_f32_16x16x32_bf16 v[54:57], v[134:137], v[186:189], v[54:57]
	v_mfma_f32_16x16x32_bf16 v[50:53], v[142:145], v[186:189], v[50:53]
	v_mfma_f32_16x16x32_bf16 v[46:49], v[134:137], v[194:197], v[46:49]
	v_mfma_f32_16x16x32_bf16 v[38:41], v[142:145], v[194:197], v[38:41]
	v_mfma_f32_16x16x32_bf16 v[18:21], v[134:137], v[202:205], v[18:21]
	v_mfma_f32_16x16x32_bf16 v[10:13], v[142:145], v[202:205], v[10:13]
	v_mfma_f32_16x16x32_bf16 v[42:45], v[152:155], v[174:177], v[42:45]
	v_mfma_f32_16x16x32_bf16 v[34:37], v[166:169], v[174:177], v[34:37]
	v_mfma_f32_16x16x32_bf16 v[30:33], v[152:155], v[182:185], v[30:33]
	v_mfma_f32_16x16x32_bf16 v[26:29], v[166:169], v[182:185], v[26:29]
	v_mfma_f32_16x16x32_bf16 v[22:25], v[152:155], v[190:193], v[22:25]
	v_mfma_f32_16x16x32_bf16 v[14:17], v[166:169], v[190:193], v[14:17]
	v_mfma_f32_16x16x32_bf16 v[6:9], v[152:155], v[198:201], v[6:9]
	v_mfma_f32_16x16x32_bf16 v[2:5], v[166:169], v[198:201], v[2:5]
	v_mfma_f32_16x16x32_bf16 v[42:45], v[162:165], v[178:181], v[42:45]
	v_mfma_f32_16x16x32_bf16 v[34:37], v[170:173], v[178:181], v[34:37]
	v_mfma_f32_16x16x32_bf16 v[30:33], v[162:165], v[186:189], v[30:33]
	v_mfma_f32_16x16x32_bf16 v[26:29], v[170:173], v[186:189], v[26:29]
	v_mfma_f32_16x16x32_bf16 v[22:25], v[162:165], v[194:197], v[22:25]
	v_mfma_f32_16x16x32_bf16 v[14:17], v[170:173], v[194:197], v[14:17]
	v_mfma_f32_16x16x32_bf16 v[6:9], v[162:165], v[202:205], v[6:9]
	v_mfma_f32_16x16x32_bf16 v[2:5], v[170:173], v[202:205], v[2:5]
	s_barrier
	s_movk_i32 s72, 0x100
	s_and_b64 vcc, exec, s[30:31]
	s_mov_b64 s[34:35], -1
	s_mov_b64 s[30:31], 0
	s_cbranch_vccnz .LBB0_1364
	s_andn2_b64 vcc, exec, s[8:9]
	s_cbranch_vccnz .LBB0_1367
	s_barrier

; #define PG8_STAGE(bufoff, gbase, voff) do { _Pragma("unroll") for (int _i = 0; _i < 2; ++_i) \
;         __builtin_amdgcn_global_load_lds((const unsigned*)((const char*)(gbase) + (voff)[_i]), (PG8_LAS unsigned*)(lds + (bufoff) + ldsw + _i * 8192), 16, 0, 0); } while (0)
; #define PG8_LDA(dst, b, h) do { _Pragma("unroll") for (int m = 0; m < 4; ++m) _Pragma("unroll") for (int k = 0; k < 2; ++k) dst[m][k] = *(const PG8_LAS bf16x8*)(lds + PG8_SA(b, h) + aoff + m * 2048 + k * 1024); } while (0)
; #define PG8_LDB(dst, b, h) do { _Pragma("unroll") for (int n = 0; n < 2; ++n) _Pragma("unroll") for (int k = 0; k < 2; ++k) dst[n][k] = *(const PG8_LAS bf16x8*)(lds + PG8_SB(b, h) + boff + n * 2048 + k * 1024); } while (0)
; #define PG8_MMA(ai, bj, At, Bt) do { __builtin_amdgcn_s_setprio(1); _Pragma("unroll") for (int m = 0; m < 4; ++m) _Pragma("unroll") for (int n = 0; n < 2; ++n) _Pragma("unroll") for (int k = 0; k < 2; ++k) \
;         acc[ai][bj][m][n] = __builtin_amdgcn_mfma_f32_16x16x32_bf16(Bt[n][k], At[m][k], acc[ai][bj][m][n], 0, 0, 0); __builtin_amdgcn_s_setprio(0); } while (0)
; #define PG8_WAIT_V(n) asm volatile("s_waitcnt vmcnt(" #n ")" ::: "memory")
; #define PG8_WAIT_L(n) asm volatile("s_waitcnt lgkmcnt(" #n ")" ::: "memory")
; template <class Epi, class Sched, bool ALIGN_EPI = false, bool SP2 = false>
; __device__ __forceinline__ void gemm_phase(PG8_LAS unsigned char* lds, const Gemm g, const Sched& S, const Epi& E) {
;     ...
;             const bool last = (t == nt - 2);
;             const char* a1 = cA + (size_t)(t + 1) * kstep;
;             const char* a2 = last ? nA : cA + (size_t)(t + 2) * kstep; const char* b2 = last ? nB : cB + (size_t)(t + 2) * kstep;
;             const char* a3 = a2 + kstep; const char* b3 = b2 + kstep;
;             if (last && has_next) S.a_ready(nxt);
;             if constexpr (SP2) {
;             PG8_LDB(B0, 0, 0); PG8_LDB(B1, 0, 1); PG8_SCHED; PG8_LDA(At, 0, 0); PG8_STAGE(PG8_SA(1, 1), a1 + hstepA, voffA);
;             PG8_WAIT_V(8); PG8_WAIT_L(0); PG8_BAR; PG8_MMA(0, 0, At, B0); PG8_MMA(0, 1, At, B1); PG8_BAR; PG8_SCHED;
;             PG8_LDA(At, 0, 1); PG8_STAGE(PG8_SB(0, 0), b2, voffB); PG8_STAGE(PG8_SB(0, 1), b2 + hstepB, voffB); PG8_STAGE(PG8_SA(0, 0), a2, voffA);
;             PG8_WAIT_V(8); PG8_WAIT_L(0); PG8_BAR; PG8_MMA(1, 0, At, B0); PG8_MMA(1, 1, At, B1); PG8_BAR; PG8_SCHED;
.LBB0_1384:
	s_add_u32 s70, s28, s69
	ds_read_b128 v[130:133], v158
	ds_read_b128 v[134:137], v158 offset:1024
	ds_read_b128 v[138:141], v158 offset:2048
	ds_read_b128 v[142:145], v158 offset:3072
	ds_read_b128 v[152:155], v159
	ds_read_b128 v[162:165], v159 offset:1024
	ds_read_b128 v[166:169], v159 offset:2048
	ds_read_b128 v[170:173], v159 offset:3072
	s_addc_u32 s71, s29, 0
	s_add_u32 s72, s70, 0x100
	s_addc_u32 s73, s71, 0
	s_and_b64 s[36:37], s[34:35], exec
	s_cselect_b32 s37, s17, s73
	s_cselect_b32 s36, s67, s72
	s_add_u32 s69, s26, s69
	s_addc_u32 s72, s27, 0
	s_add_u32 s69, s69, 0x100
	s_addc_u32 s72, s72, 0
	s_and_b64 s[34:35], s[34:35], exec
	s_cselect_b32 s35, s15, s72
	s_cselect_b32 s34, s68, s69
	s_add_u32 s70, s70, 0x40080
	s_addc_u32 s71, s71, 0
	v_lshl_add_u64 v[206:207], s[70:71], 0, v[148:149]
	s_add_i32 m0, s47, 0xc000
	ds_read_b128 v[174:177], v160
	ds_read_b128 v[178:181], v160 offset:1024
	ds_read_b128 v[182:185], v160 offset:2048
	ds_read_b128 v[186:189], v160 offset:3072
	ds_read_b128 v[190:193], v160 offset:4096
	ds_read_b128 v[194:197], v160 offset:5120
	ds_read_b128 v[198:201], v160 offset:6144
	ds_read_b128 v[202:205], v160 offset:7168
	global_load_lds_dwordx4 v[206:207], off
	v_lshl_add_u64 v[206:207], s[70:71], 0, v[146:147]
	s_add_i32 m0, s47, 0xe000
	s_nop 0
	global_load_lds_dwordx4 v[206:207], off
	s_waitcnt vmcnt(8)
	s_waitcnt lgkmcnt(0)
	s_barrier
	s_waitcnt lgkmcnt(0)
	v_mfma_f32_16x16x32_bf16 v[126:129], v[130:133], v[174:177], v[126:129]
	v_mfma_f32_16x16x32_bf16 v[122:125], v[138:141], v[174:177], v[122:125]
	v_mfma_f32_16x16x32_bf16 v[118:121], v[130:133], v[182:185], v[118:121]
	v_mfma_f32_16x16x32_bf16 v[114:117], v[138:141], v[182:185], v[114:117]
	v_mfma_f32_16x16x32_bf16 v[102:105], v[130:133], v[190:193], v[102:105]
	v_mfma_f32_16x16x32_bf16 v[90:93], v[138:141], v[190:193], v[90:93]
	v_mfma_f32_16x16x32_bf16 v[82:85], v[130:133], v[198:201], v[82:85]
	v_mfma_f32_16x16x32_bf16 v[74:77], v[138:141], v[198:201], v[74:77]
	v_mfma_f32_16x16x32_bf16 v[126:129], v[134:137], v[178:181], v[126:129]
	v_mfma_f32_16x16x32_bf16 v[122:125], v[142:145], v[178:181], v[122:125]
	v_mfma_f32_16x16x32_bf16 v[118:121], v[134:137], v[186:189], v[118:121]
	v_mfma_f32_16x16x32_bf16 v[114:117], v[142:145], v[186:189], v[114:117]
	v_mfma_f32_16x16x32_bf16 v[102:105], v[134:137], v[194:197], v[102:105]
	v_mfma_f32_16x16x32_bf16 v[90:93], v[142:145], v[194:197], v[90:93]
	v_mfma_f32_16x16x32_bf16 v[82:85], v[134:137], v[202:205], v[82:85]
	v_mfma_f32_16x16x32_bf16 v[74:77], v[142:145], v[202:205], v[74:77]
	v_mfma_f32_16x16x32_bf16 v[110:113], v[152:155], v[174:177], v[110:113]
	v_mfma_f32_16x16x32_bf16 v[106:109], v[166:169], v[174:177], v[106:109]
	v_mfma_f32_16x16x32_bf16 v[98:101], v[152:155], v[182:185], v[98:101]
	v_mfma_f32_16x16x32_bf16 v[94:97], v[166:169], v[182:185], v[94:97]
	v_mfma_f32_16x16x32_bf16 v[86:89], v[152:155], v[190:193], v[86:89]
	v_mfma_f32_16x16x32_bf16 v[78:81], v[166:169], v[190:193], v[78:81]
	v_mfma_f32_16x16x32_bf16 v[70:73], v[152:155], v[198:201], v[70:73]
	v_mfma_f32_16x16x32_bf16 v[66:69], v[166:169], v[198:201], v[66:69]
	v_mfma_f32_16x16x32_bf16 v[110:113], v[162:165], v[178:181], v[110:113]
	v_mfma_f32_16x16x32_bf16 v[106:109], v[170:173], v[178:181], v[106:109]
	v_mfma_f32_16x16x32_bf16 v[98:101], v[162:165], v[186:189], v[98:101]
	v_mfma_f32_16x16x32_bf16 v[94:97], v[170:173], v[186:189], v[94:97]
	v_mfma_f32_16x16x32_bf16 v[86:89], v[162:165], v[194:197], v[86:89]
	v_mfma_f32_16x16x32_bf16 v[78:81], v[170:173], v[194:197], v[78:81]
	v_mfma_f32_16x16x32_bf16 v[70:73], v[162:165], v[202:205], v[70:73]
	v_mfma_f32_16x16x32_bf16 v[66:69], v[170:173], v[202:205], v[66:69]
	s_barrier
	s_add_i32 s69, s59, s44
	v_lshl_add_u64 v[206:207], s[34:35], 0, v[148:149]
	s_mov_b32 m0, s69
	ds_read_b128 v[174:177], v160 offset:16384
	ds_read_b128 v[178:181], v160 offset:17408
	ds_read_b128 v[182:185], v160 offset:18432
	ds_read_b128 v[186:189], v160 offset:19456
	ds_read_b128 v[190:193], v160 offset:20480
	ds_read_b128 v[194:197], v160 offset:21504
	ds_read_b128 v[198:201], v160 offset:22528
	ds_read_b128 v[202:205], v160 offset:23552
	global_load_lds_dwordx4 v[206:207], off
	s_add_i32 m0, s69, 0x2000
	s_add_u32 s70, s34, 0x40000
	v_lshl_add_u64 v[208:209], s[34:35], 0, v[146:147]
	s_addc_u32 s71, s35, 0
	s_add_i32 s69, s60, s44
	global_load_lds_dwordx4 v[208:209], off
	v_lshl_add_u64 v[210:211], s[70:71], 0, v[148:149]
	s_mov_b32 m0, s69
	v_lshl_add_u64 v[212:213], s[36:37], 0, v[146:147]
	global_load_lds_dwordx4 v[210:211], off
	v_lshl_add_u64 v[210:211], s[70:71], 0, v[146:147]
	s_add_i32 m0, s69, 0x2000
	s_nop 0
	global_load_lds_dwordx4 v[210:211], off
	v_lshl_add_u64 v[210:211], s[36:37], 0, v[148:149]
	s_mov_b32 m0, s47
	s_nop 0
	global_load_lds_dwordx4 v[210:211], off
	s_mov_b32 m0, s48
	s_nop 0
	global_load_lds_dwordx4 v[212:213], off
	s_waitcnt vmcnt(8)
	s_waitcnt lgkmcnt(0)
	s_barrier
; #define PG8_STAGE(bufoff, gbase, voff) do { _Pragma("unroll") for (int _i = 0; _i < 2; ++_i) \
;         __builtin_amdgcn_global_load_lds((const unsigned*)((const char*)(gbase) + (voff)[_i]), (PG8_LAS unsigned*)(lds + (bufoff) + ldsw + _i * 8192), 16, 0, 0); } while (0)
; #define PG8_LDA(dst, b, h) do { _Pragma("unroll") for (int m = 0; m < 4; ++m) _Pragma("unroll") for (int k = 0; k < 2; ++k) dst[m][k] = *(const PG8_LAS bf16x8*)(lds + PG8_SA(b, h) + aoff + m * 2048 + k * 1024); } while (0)
; #define PG8_LDB(dst, b, h) do { _Pragma("unroll") for (int n = 0; n < 2; ++n) _Pragma("unroll") for (int k = 0; k < 2; ++k) dst[n][k] = *(const PG8_LAS bf16x8*)(lds + PG8_SB(b, h) + boff + n * 2048 + k * 1024); } while (0)
; #define PG8_MMA(ai, bj, At, Bt) do { __builtin_amdgcn_s_setprio(1); _Pragma("unroll") for (int m = 0; m < 4; ++m) _Pragma("unroll") for (int n = 0; n < 2; ++n) _Pragma("unroll") for (int k = 0; k < 2; ++k) \
;         acc[ai][bj][m][n] = __builtin_amdgcn_mfma_f32_16x16x32_bf16(Bt[n][k], At[m][k], acc[ai][bj][m][n], 0, 0, 0); __builtin_amdgcn_s_setprio(0); } while (0)
; #define PG8_WAIT_V(n) asm volatile("s_waitcnt vmcnt(" #n ")" ::: "memory")
; #define PG8_WAIT_L(n) asm volatile("s_waitcnt lgkmcnt(" #n ")" ::: "memory")
; #define PG8_BAR __builtin_amdgcn_s_barrier()
; #define PG8_SCHED __builtin_amdgcn_sched_barrier(0)
; template <class Epi, class Sched, bool ALIGN_EPI = false, bool SP2 = false>
; __device__ __forceinline__ void gemm_phase(PG8_LAS unsigned char* lds, const Gemm g, const Sched& S, const Epi& E) {
;     ...
;             PG8_WAIT_V(8); PG8_WAIT_L(0); PG8_BAR; PG8_MMA(1, 0, At, B0); PG8_MMA(1, 1, At, B1); PG8_BAR; PG8_SCHED;
;             PG8_LDB(B0, 1, 0); PG8_LDB(B1, 1, 1); PG8_SCHED; PG8_LDA(At, 1, 0); PG8_STAGE(PG8_SA(0, 1), a2 + hstepA, voffA);
;             PG8_WAIT_V(8); PG8_WAIT_L(0); PG8_BAR; PG8_MMA(0, 0, At, B0); PG8_MMA(0, 1, At, B1); PG8_BAR; PG8_SCHED;
	s_waitcnt lgkmcnt(0)
	v_mfma_f32_16x16x32_bf16 v[62:65], v[130:133], v[174:177], v[62:65]
	v_mfma_f32_16x16x32_bf16 v[58:61], v[138:141], v[174:177], v[58:61]
	v_mfma_f32_16x16x32_bf16 v[54:57], v[130:133], v[182:185], v[54:57]
	v_mfma_f32_16x16x32_bf16 v[50:53], v[138:141], v[182:185], v[50:53]
	v_mfma_f32_16x16x32_bf16 v[46:49], v[130:133], v[190:193], v[46:49]
	v_mfma_f32_16x16x32_bf16 v[38:41], v[138:141], v[190:193], v[38:41]
	v_mfma_f32_16x16x32_bf16 v[18:21], v[130:133], v[198:201], v[18:21]
	v_mfma_f32_16x16x32_bf16 v[10:13], v[138:141], v[198:201], v[10:13]
	v_mfma_f32_16x16x32_bf16 v[62:65], v[134:137], v[178:181], v[62:65]
	v_mfma_f32_16x16x32_bf16 v[58:61], v[142:145], v[178:181], v[58:61]
	v_mfma_f32_16x16x32_bf16 v[54:57], v[134:137], v[186:189], v[54:57]
	v_mfma_f32_16x16x32_bf16 v[50:53], v[142:145], v[186:189], v[50:53]
	v_mfma_f32_16x16x32_bf16 v[46:49], v[134:137], v[194:197], v[46:49]
	v_mfma_f32_16x16x32_bf16 v[38:41], v[142:145], v[194:197], v[38:41]
	v_mfma_f32_16x16x32_bf16 v[18:21], v[134:137], v[202:205], v[18:21]
	v_mfma_f32_16x16x32_bf16 v[10:13], v[142:145], v[202:205], v[10:13]
	v_mfma_f32_16x16x32_bf16 v[42:45], v[152:155], v[174:177], v[42:45]
	v_mfma_f32_16x16x32_bf16 v[34:37], v[166:169], v[174:177], v[34:37]
	v_mfma_f32_16x16x32_bf16 v[30:33], v[152:155], v[182:185], v[30:33]
	v_mfma_f32_16x16x32_bf16 v[26:29], v[166:169], v[182:185], v[26:29]
	v_mfma_f32_16x16x32_bf16 v[22:25], v[152:155], v[190:193], v[22:25]
	v_mfma_f32_16x16x32_bf16 v[14:17], v[166:169], v[190:193], v[14:17]
	v_mfma_f32_16x16x32_bf16 v[6:9], v[152:155], v[198:201], v[6:9]
	v_mfma_f32_16x16x32_bf16 v[2:5], v[166:169], v[198:201], v[2:5]
	v_mfma_f32_16x16x32_bf16 v[42:45], v[162:165], v[178:181], v[42:45]
	v_mfma_f32_16x16x32_bf16 v[34:37], v[170:173], v[178:181], v[34:37]
	v_mfma_f32_16x16x32_bf16 v[30:33], v[162:165], v[186:189], v[30:33]
	v_mfma_f32_16x16x32_bf16 v[26:29], v[170:173], v[186:189], v[26:29]
	v_mfma_f32_16x16x32_bf16 v[22:25], v[162:165], v[194:197], v[22:25]
	v_mfma_f32_16x16x32_bf16 v[14:17], v[170:173], v[194:197], v[14:17]
	v_mfma_f32_16x16x32_bf16 v[6:9], v[162:165], v[202:205], v[6:9]
	v_mfma_f32_16x16x32_bf16 v[2:5], v[170:173], v[202:205], v[2:5]
	s_barrier
	s_add_i32 s69, 0, 0x18000
	s_add_i32 s70, 0, 0x1c000
	v_add_u32_e32 v142, s69, v1
	v_add_u32_e32 v170, s70, v1
	ds_read_b128 v[130:133], v142
	ds_read_b128 v[134:137], v142 offset:1024
	ds_read_b128 v[138:141], v142 offset:2048
	ds_read_b128 v[142:145], v142 offset:3072
	ds_read_b128 v[152:155], v170
	ds_read_b128 v[162:165], v170 offset:1024
	ds_read_b128 v[166:169], v170 offset:2048
	ds_read_b128 v[170:173], v170 offset:3072
	s_add_u32 s36, s36, 0x40000
	s_addc_u32 s37, s37, 0
	s_mov_b32 m0, s49
	v_lshl_add_u64 v[214:215], s[36:37], 0, v[148:149]
	ds_read_b128 v[174:177], v160 offset:32768
	ds_read_b128 v[178:181], v160 offset:33792
	ds_read_b128 v[182:185], v160 offset:34816
	ds_read_b128 v[186:189], v160 offset:35840
	ds_read_b128 v[190:193], v160 offset:36864
	ds_read_b128 v[194:197], v160 offset:37888
	ds_read_b128 v[198:201], v160 offset:38912
	ds_read_b128 v[202:205], v160 offset:39936
	global_load_lds_dwordx4 v[214:215], off
	v_lshl_add_u64 v[214:215], s[36:37], 0, v[146:147]
	s_mov_b32 m0, s50
	s_nop 0
	global_load_lds_dwordx4 v[214:215], off
	s_waitcnt vmcnt(8)
	s_waitcnt lgkmcnt(0)
	s_barrier
	s_waitcnt lgkmcnt(0)
	v_mfma_f32_16x16x32_bf16 v[126:129], v[130:133], v[174:177], v[126:129]
	v_mfma_f32_16x16x32_bf16 v[122:125], v[138:141], v[174:177], v[122:125]
	v_mfma_f32_16x16x32_bf16 v[118:121], v[130:133], v[182:185], v[118:121]
	v_mfma_f32_16x16x32_bf16 v[114:117], v[138:141], v[182:185], v[114:117]
	v_mfma_f32_16x16x32_bf16 v[102:105], v[130:133], v[190:193], v[102:105]
	v_mfma_f32_16x16x32_bf16 v[90:93], v[138:141], v[190:193], v[90:93]
	v_mfma_f32_16x16x32_bf16 v[82:85], v[130:133], v[198:201], v[82:85]
	v_mfma_f32_16x16x32_bf16 v[74:77], v[138:141], v[198:201], v[74:77]
	v_mfma_f32_16x16x32_bf16 v[126:129], v[134:137], v[178:181], v[126:129]
	v_mfma_f32_16x16x32_bf16 v[122:125], v[142:145], v[178:181], v[122:125]
	v_mfma_f32_16x16x32_bf16 v[118:121], v[134:137], v[186:189], v[118:121]
	v_mfma_f32_16x16x32_bf16 v[114:117], v[142:145], v[186:189], v[114:117]
	v_mfma_f32_16x16x32_bf16 v[102:105], v[134:137], v[194:197], v[102:105]
	v_mfma_f32_16x16x32_bf16 v[90:93], v[142:145], v[194:197], v[90:93]
	v_mfma_f32_16x16x32_bf16 v[82:85], v[134:137], v[202:205], v[82:85]
	v_mfma_f32_16x16x32_bf16 v[74:77], v[142:145], v[202:205], v[74:77]
	v_mfma_f32_16x16x32_bf16 v[110:113], v[152:155], v[174:177], v[110:113]
	v_mfma_f32_16x16x32_bf16 v[106:109], v[166:169], v[174:177], v[106:109]
	v_mfma_f32_16x16x32_bf16 v[98:101], v[152:155], v[182:185], v[98:101]
	v_mfma_f32_16x16x32_bf16 v[94:97], v[166:169], v[182:185], v[94:97]
	v_mfma_f32_16x16x32_bf16 v[86:89], v[152:155], v[190:193], v[86:89]
	v_mfma_f32_16x16x32_bf16 v[78:81], v[166:169], v[190:193], v[78:81]
	v_mfma_f32_16x16x32_bf16 v[70:73], v[152:155], v[198:201], v[70:73]
	v_mfma_f32_16x16x32_bf16 v[66:69], v[166:169], v[198:201], v[66:69]
	v_mfma_f32_16x16x32_bf16 v[110:113], v[162:165], v[178:181], v[110:113]
	v_mfma_f32_16x16x32_bf16 v[106:109], v[170:173], v[178:181], v[106:109]
	v_mfma_f32_16x16x32_bf16 v[98:101], v[162:165], v[186:189], v[98:101]
	v_mfma_f32_16x16x32_bf16 v[94:97], v[170:173], v[186:189], v[94:97]
	v_mfma_f32_16x16x32_bf16 v[86:89], v[162:165], v[194:197], v[86:89]
	v_mfma_f32_16x16x32_bf16 v[78:81], v[170:173], v[194:197], v[78:81]
	v_mfma_f32_16x16x32_bf16 v[70:73], v[162:165], v[202:205], v[70:73]
	v_mfma_f32_16x16x32_bf16 v[66:69], v[170:173], v[202:205], v[66:69]
	s_barrier
; #define PG8_STAGE(bufoff, gbase, voff) do { _Pragma("unroll") for (int _i = 0; _i < 2; ++_i) \
;         __builtin_amdgcn_global_load_lds((const unsigned*)((const char*)(gbase) + (voff)[_i]), (PG8_LAS unsigned*)(lds + (bufoff) + ldsw + _i * 8192), 16, 0, 0); } while (0)
; #define PG8_LDA(dst, b, h) do { _Pragma("unroll") for (int m = 0; m < 4; ++m) _Pragma("unroll") for (int k = 0; k < 2; ++k) dst[m][k] = *(const PG8_LAS bf16x8*)(lds + PG8_SA(b, h) + aoff + m * 2048 + k * 1024); } while (0)
; #define PG8_MMA(ai, bj, At, Bt) do { __builtin_amdgcn_s_setprio(1); _Pragma("unroll") for (int m = 0; m < 4; ++m) _Pragma("unroll") for (int n = 0; n < 2; ++n) _Pragma("unroll") for (int k = 0; k < 2; ++k) \
;         acc[ai][bj][m][n] = __builtin_amdgcn_mfma_f32_16x16x32_bf16(Bt[n][k], At[m][k], acc[ai][bj][m][n], 0, 0, 0); __builtin_amdgcn_s_setprio(0); } while (0)
; #define PG8_WAIT_V(n) asm volatile("s_waitcnt vmcnt(" #n ")" ::: "memory")
; #define PG8_WAIT_L(n) asm volatile("s_waitcnt lgkmcnt(" #n ")" ::: "memory")
; #define PG8_BAR __builtin_amdgcn_s_barrier()
; #define PG8_SCHED __builtin_amdgcn_sched_barrier(0)
; template <class Epi, class Sched, bool ALIGN_EPI = false, bool SP2 = false>
; __device__ __forceinline__ void gemm_phase(PG8_LAS unsigned char* lds, const Gemm g, const Sched& S, const Epi& E) {
;     ...
;             PG8_LDA(At, 1, 1); PG8_STAGE(PG8_SB(1, 0), b3, voffB); PG8_STAGE(PG8_SB(1, 1), b3 + hstepB, voffB); PG8_STAGE(PG8_SA(1, 0), a3, voffA);
;             PG8_WAIT_V(8); PG8_WAIT_L(0); PG8_BAR; PG8_MMA(1, 0, At, B0); PG8_MMA(1, 1, At, B1); PG8_BAR; PG8_SCHED;
;     ...
;         if constexpr (ALIGN_EPI) { if (wr == 0) PG8_BAR; }
	s_add_i32 s36, s69, s44
	v_lshl_add_u64 v[206:207], v[206:207], 0, s[4:5]
	s_mov_b32 m0, s36
	ds_read_b128 v[174:177], v160 offset:49152
	ds_read_b128 v[178:181], v160 offset:50176
	ds_read_b128 v[182:185], v160 offset:51200
	ds_read_b128 v[186:189], v160 offset:52224
	ds_read_b128 v[190:193], v160 offset:53248
	ds_read_b128 v[194:197], v160 offset:54272
	ds_read_b128 v[198:201], v160 offset:55296
	ds_read_b128 v[202:205], v160 offset:56320
	global_load_lds_dwordx4 v[206:207], off
	s_add_i32 m0, s36, 0x2000
	s_add_u32 s34, s34, 0x40080
	v_lshl_add_u64 v[206:207], v[208:209], 0, s[4:5]
	s_addc_u32 s35, s35, 0
	s_add_i32 s36, s70, s44
	global_load_lds_dwordx4 v[206:207], off
	v_lshl_add_u64 v[206:207], s[34:35], 0, v[148:149]
	s_mov_b32 m0, s36
	s_nop 0
	global_load_lds_dwordx4 v[206:207], off
	v_lshl_add_u64 v[206:207], s[34:35], 0, v[146:147]
	s_add_i32 m0, s36, 0x2000
	s_nop 0
	global_load_lds_dwordx4 v[206:207], off
	v_lshl_add_u64 v[206:207], v[210:211], 0, s[4:5]
	s_mov_b32 m0, s57
	s_nop 0
	global_load_lds_dwordx4 v[206:207], off
	v_lshl_add_u64 v[206:207], v[212:213], 0, s[4:5]
	s_mov_b32 m0, s58
	s_nop 0
	global_load_lds_dwordx4 v[206:207], off
	s_waitcnt vmcnt(8)
	s_waitcnt lgkmcnt(0)
	s_barrier
	s_waitcnt lgkmcnt(0)
	v_mfma_f32_16x16x32_bf16 v[62:65], v[130:133], v[174:177], v[62:65]
	v_mfma_f32_16x16x32_bf16 v[58:61], v[138:141], v[174:177], v[58:61]
	v_mfma_f32_16x16x32_bf16 v[54:57], v[130:133], v[182:185], v[54:57]
	v_mfma_f32_16x16x32_bf16 v[50:53], v[138:141], v[182:185], v[50:53]
	v_mfma_f32_16x16x32_bf16 v[46:49], v[130:133], v[190:193], v[46:49]
	v_mfma_f32_16x16x32_bf16 v[38:41], v[138:141], v[190:193], v[38:41]
	v_mfma_f32_16x16x32_bf16 v[18:21], v[130:133], v[198:201], v[18:21]
	v_mfma_f32_16x16x32_bf16 v[10:13], v[138:141], v[198:201], v[10:13]
	v_mfma_f32_16x16x32_bf16 v[62:65], v[134:137], v[178:181], v[62:65]
	v_mfma_f32_16x16x32_bf16 v[58:61], v[142:145], v[178:181], v[58:61]
	v_mfma_f32_16x16x32_bf16 v[54:57], v[134:137], v[186:189], v[54:57]
	v_mfma_f32_16x16x32_bf16 v[50:53], v[142:145], v[186:189], v[50:53]
	v_mfma_f32_16x16x32_bf16 v[46:49], v[134:137], v[194:197], v[46:49]
	v_mfma_f32_16x16x32_bf16 v[38:41], v[142:145], v[194:197], v[38:41]
	v_mfma_f32_16x16x32_bf16 v[18:21], v[134:137], v[202:205], v[18:21]
	v_mfma_f32_16x16x32_bf16 v[10:13], v[142:145], v[202:205], v[10:13]
	v_mfma_f32_16x16x32_bf16 v[42:45], v[152:155], v[174:177], v[42:45]
	v_mfma_f32_16x16x32_bf16 v[34:37], v[166:169], v[174:177], v[34:37]
	v_mfma_f32_16x16x32_bf16 v[30:33], v[152:155], v[182:185], v[30:33]
	v_mfma_f32_16x16x32_bf16 v[26:29], v[166:169], v[182:185], v[26:29]
	v_mfma_f32_16x16x32_bf16 v[22:25], v[152:155], v[190:193], v[22:25]
	v_mfma_f32_16x16x32_bf16 v[14:17], v[166:169], v[190:193], v[14:17]
	v_mfma_f32_16x16x32_bf16 v[6:9], v[152:155], v[198:201], v[6:9]
	v_mfma_f32_16x16x32_bf16 v[2:5], v[166:169], v[198:201], v[2:5]
	v_mfma_f32_16x16x32_bf16 v[42:45], v[162:165], v[178:181], v[42:45]
	v_mfma_f32_16x16x32_bf16 v[34:37], v[170:173], v[178:181], v[34:37]
	v_mfma_f32_16x16x32_bf16 v[30:33], v[162:165], v[186:189], v[30:33]
	v_mfma_f32_16x16x32_bf16 v[26:29], v[170:173], v[186:189], v[26:29]
	v_mfma_f32_16x16x32_bf16 v[22:25], v[162:165], v[194:197], v[22:25]
	v_mfma_f32_16x16x32_bf16 v[14:17], v[170:173], v[194:197], v[14:17]
	v_mfma_f32_16x16x32_bf16 v[6:9], v[162:165], v[202:205], v[6:9]
	v_mfma_f32_16x16x32_bf16 v[2:5], v[170:173], v[202:205], v[2:5]
	s_barrier
	s_movk_i32 s69, 0x100
	s_and_b64 vcc, exec, s[30:31]
	s_mov_b64 s[34:35], -1
	s_mov_b64 s[30:31], 0
	s_cbranch_vccnz .LBB0_1384
	s_andn2_b64 vcc, exec, s[8:9]
	s_cbranch_vccnz .LBB0_1387
	s_barrier

; #define PG8_STAGE(bufoff, gbase, voff) do { _Pragma("unroll") for (int _i = 0; _i < 2; ++_i) \
;         __builtin_amdgcn_global_load_lds((const unsigned*)((const char*)(gbase) + (voff)[_i]), (PG8_LAS unsigned*)(lds + (bufoff) + ldsw + _i * 8192), 16, 0, 0); } while (0)
; #define PG8_LDA(dst, b, h) do { _Pragma("unroll") for (int m = 0; m < 4; ++m) _Pragma("unroll") for (int k = 0; k < 2; ++k) dst[m][k] = *(const PG8_LAS bf16x8*)(lds + PG8_SA(b, h) + aoff + m * 2048 + k * 1024); } while (0)
; #define PG8_LDB(dst, b, h) do { _Pragma("unroll") for (int n = 0; n < 2; ++n) _Pragma("unroll") for (int k = 0; k < 2; ++k) dst[n][k] = *(const PG8_LAS bf16x8*)(lds + PG8_SB(b, h) + boff + n * 2048 + k * 1024); } while (0)
; #define PG8_MMA(ai, bj, At, Bt) do { __builtin_amdgcn_s_setprio(1); _Pragma("unroll") for (int m = 0; m < 4; ++m) _Pragma("unroll") for (int n = 0; n < 2; ++n) _Pragma("unroll") for (int k = 0; k < 2; ++k) \
;         acc[ai][bj][m][n] = __builtin_amdgcn_mfma_f32_16x16x32_bf16(Bt[n][k], At[m][k], acc[ai][bj][m][n], 0, 0, 0); __builtin_amdgcn_s_setprio(0); } while (0)
; #define PG8_WAIT_V(n) asm volatile("s_waitcnt vmcnt(" #n ")" ::: "memory")
; #define PG8_WAIT_L(n) asm volatile("s_waitcnt lgkmcnt(" #n ")" ::: "memory")
; template <class Epi, class Sched, bool ALIGN_EPI = false, bool SP2 = false>
; __device__ __forceinline__ void gemm_phase(PG8_LAS unsigned char* lds, const Gemm g, const Sched& S, const Epi& E) {
;     ...
;             const bool last = (t == nt - 2);
;             const char* a1 = cA + (size_t)(t + 1) * kstep;
;             const char* a2 = last ? nA : cA + (size_t)(t + 2) * kstep; const char* b2 = last ? nB : cB + (size_t)(t + 2) * kstep;
;             const char* a3 = a2 + kstep; const char* b3 = b2 + kstep;
;             if (last && has_next) S.a_ready(nxt);
;             if constexpr (SP2) {
;             PG8_LDB(B0, 0, 0); PG8_LDB(B1, 0, 1); PG8_SCHED; PG8_LDA(At, 0, 0); PG8_STAGE(PG8_SA(1, 1), a1 + hstepA, voffA);
;             PG8_WAIT_V(8); PG8_WAIT_L(0); PG8_BAR; PG8_MMA(0, 0, At, B0); PG8_MMA(0, 1, At, B1); PG8_BAR; PG8_SCHED;
;             PG8_LDA(At, 0, 1); PG8_STAGE(PG8_SB(0, 0), b2, voffB); PG8_STAGE(PG8_SB(0, 1), b2 + hstepB, voffB); PG8_STAGE(PG8_SA(0, 0), a2, voffA);
;             PG8_WAIT_V(8); PG8_WAIT_L(0); PG8_BAR; PG8_MMA(1, 0, At, B0); PG8_MMA(1, 1, At, B1); PG8_BAR; PG8_SCHED;
.LBB0_1921:
	ds_read_b128 v[130:133], v162
	ds_read_b128 v[134:137], v162 offset:1024
	ds_read_b128 v[138:141], v162 offset:2048
	ds_read_b128 v[142:145], v162 offset:3072
	ds_read_b128 v[156:159], v163
	ds_read_b128 v[166:169], v163 offset:1024
	ds_read_b128 v[170:173], v163 offset:2048
	ds_read_b128 v[174:177], v163 offset:3072
	s_add_u32 s22, s20, 0x100
	s_addc_u32 s23, s21, 0
	s_cmp_eq_u32 s67, 4
	s_cselect_b32 s27, s19, s23
	s_cselect_b32 s26, s18, s22
	s_cselect_b32 s25, s1, s66
	s_cselect_b32 s24, s0, s65
	v_lshl_add_u64 v[210:211], s[20:21], 0, v[154:155]
	s_add_i32 m0, s41, 0xc000
	ds_read_b128 v[178:181], v164
	ds_read_b128 v[182:185], v164 offset:1024
	ds_read_b128 v[186:189], v164 offset:2048
	ds_read_b128 v[190:193], v164 offset:3072
	ds_read_b128 v[194:197], v164 offset:4096
	ds_read_b128 v[198:201], v164 offset:5120
	ds_read_b128 v[202:205], v164 offset:6144
	ds_read_b128 v[206:209], v164 offset:7168
	global_load_lds_dwordx4 v[210:211], off
	v_lshl_add_u64 v[210:211], s[20:21], 0, v[152:153]
	s_add_i32 m0, s41, 0xe000
	s_nop 0
	global_load_lds_dwordx4 v[210:211], off
	s_waitcnt vmcnt(8)
	s_waitcnt lgkmcnt(0)
	s_barrier
	s_waitcnt lgkmcnt(0)
	v_mfma_f32_16x16x32_bf16 v[126:129], v[130:133], v[178:181], v[126:129]
	v_mfma_f32_16x16x32_bf16 v[122:125], v[138:141], v[178:181], v[122:125]
	v_mfma_f32_16x16x32_bf16 v[118:121], v[130:133], v[186:189], v[118:121]
	v_mfma_f32_16x16x32_bf16 v[114:117], v[138:141], v[186:189], v[114:117]
	v_mfma_f32_16x16x32_bf16 v[102:105], v[130:133], v[194:197], v[102:105]
	v_mfma_f32_16x16x32_bf16 v[90:93], v[138:141], v[194:197], v[90:93]
	v_mfma_f32_16x16x32_bf16 v[82:85], v[130:133], v[202:205], v[82:85]
	v_mfma_f32_16x16x32_bf16 v[74:77], v[138:141], v[202:205], v[74:77]
	v_mfma_f32_16x16x32_bf16 v[126:129], v[134:137], v[182:185], v[126:129]
	v_mfma_f32_16x16x32_bf16 v[122:125], v[142:145], v[182:185], v[122:125]
	v_mfma_f32_16x16x32_bf16 v[118:121], v[134:137], v[190:193], v[118:121]
	v_mfma_f32_16x16x32_bf16 v[114:117], v[142:145], v[190:193], v[114:117]
	v_mfma_f32_16x16x32_bf16 v[102:105], v[134:137], v[198:201], v[102:105]
	v_mfma_f32_16x16x32_bf16 v[90:93], v[142:145], v[198:201], v[90:93]
	v_mfma_f32_16x16x32_bf16 v[82:85], v[134:137], v[206:209], v[82:85]
	v_mfma_f32_16x16x32_bf16 v[74:77], v[142:145], v[206:209], v[74:77]
	v_mfma_f32_16x16x32_bf16 v[110:113], v[156:159], v[178:181], v[110:113]
	v_mfma_f32_16x16x32_bf16 v[106:109], v[170:173], v[178:181], v[106:109]
	v_mfma_f32_16x16x32_bf16 v[98:101], v[156:159], v[186:189], v[98:101]
	v_mfma_f32_16x16x32_bf16 v[94:97], v[170:173], v[186:189], v[94:97]
	v_mfma_f32_16x16x32_bf16 v[86:89], v[156:159], v[194:197], v[86:89]
	v_mfma_f32_16x16x32_bf16 v[78:81], v[170:173], v[194:197], v[78:81]
	v_mfma_f32_16x16x32_bf16 v[70:73], v[156:159], v[202:205], v[70:73]
	v_mfma_f32_16x16x32_bf16 v[66:69], v[170:173], v[202:205], v[66:69]
	v_mfma_f32_16x16x32_bf16 v[110:113], v[166:169], v[182:185], v[110:113]
	v_mfma_f32_16x16x32_bf16 v[106:109], v[174:177], v[182:185], v[106:109]
	v_mfma_f32_16x16x32_bf16 v[98:101], v[166:169], v[190:193], v[98:101]
	v_mfma_f32_16x16x32_bf16 v[94:97], v[174:177], v[190:193], v[94:97]
	v_mfma_f32_16x16x32_bf16 v[86:89], v[166:169], v[198:201], v[86:89]
	v_mfma_f32_16x16x32_bf16 v[78:81], v[174:177], v[198:201], v[78:81]
	v_mfma_f32_16x16x32_bf16 v[70:73], v[166:169], v[206:209], v[70:73]
	v_mfma_f32_16x16x32_bf16 v[66:69], v[174:177], v[206:209], v[66:69]
	s_barrier
	s_add_i32 s20, s53, s39
	v_lshl_add_u64 v[210:211], s[24:25], 0, v[148:149]
	s_mov_b32 m0, s20
	ds_read_b128 v[178:181], v164 offset:16384
	ds_read_b128 v[182:185], v164 offset:17408
	ds_read_b128 v[186:189], v164 offset:18432
	ds_read_b128 v[190:193], v164 offset:19456
	ds_read_b128 v[194:197], v164 offset:20480
	ds_read_b128 v[198:201], v164 offset:21504
	ds_read_b128 v[202:205], v164 offset:22528
	ds_read_b128 v[206:209], v164 offset:23552
	global_load_lds_dwordx4 v[210:211], off
	s_add_i32 m0, s20, 0x2000
	s_add_u32 s20, s24, 0xb0000
	v_lshl_add_u64 v[212:213], s[24:25], 0, v[146:147]
	s_addc_u32 s21, s25, 0
	s_add_i32 s68, s54, s39
	global_load_lds_dwordx4 v[212:213], off
	v_lshl_add_u64 v[214:215], s[20:21], 0, v[148:149]
	s_mov_b32 m0, s68
	v_lshl_add_u64 v[216:217], s[26:27], 0, v[146:147]
	global_load_lds_dwordx4 v[214:215], off
	v_lshl_add_u64 v[214:215], s[20:21], 0, v[146:147]
	s_add_i32 m0, s68, 0x2000
	s_nop 0
	global_load_lds_dwordx4 v[214:215], off
	v_lshl_add_u64 v[214:215], s[26:27], 0, v[148:149]
	s_mov_b32 m0, s41
	s_nop 0
	global_load_lds_dwordx4 v[214:215], off
	s_mov_b32 m0, s42
	s_nop 0
	global_load_lds_dwordx4 v[216:217], off
	s_waitcnt vmcnt(8)
	s_waitcnt lgkmcnt(0)
	s_barrier
; #define PG8_STAGE(bufoff, gbase, voff) do { _Pragma("unroll") for (int _i = 0; _i < 2; ++_i) \
;         __builtin_amdgcn_global_load_lds((const unsigned*)((const char*)(gbase) + (voff)[_i]), (PG8_LAS unsigned*)(lds + (bufoff) + ldsw + _i * 8192), 16, 0, 0); } while (0)
; #define PG8_LDA(dst, b, h) do { _Pragma("unroll") for (int m = 0; m < 4; ++m) _Pragma("unroll") for (int k = 0; k < 2; ++k) dst[m][k] = *(const PG8_LAS bf16x8*)(lds + PG8_SA(b, h) + aoff + m * 2048 + k * 1024); } while (0)
; #define PG8_LDB(dst, b, h) do { _Pragma("unroll") for (int n = 0; n < 2; ++n) _Pragma("unroll") for (int k = 0; k < 2; ++k) dst[n][k] = *(const PG8_LAS bf16x8*)(lds + PG8_SB(b, h) + boff + n * 2048 + k * 1024); } while (0)
; #define PG8_MMA(ai, bj, At, Bt) do { __builtin_amdgcn_s_setprio(1); _Pragma("unroll") for (int m = 0; m < 4; ++m) _Pragma("unroll") for (int n = 0; n < 2; ++n) _Pragma("unroll") for (int k = 0; k < 2; ++k) \
;         acc[ai][bj][m][n] = __builtin_amdgcn_mfma_f32_16x16x32_bf16(Bt[n][k], At[m][k], acc[ai][bj][m][n], 0, 0, 0); __builtin_amdgcn_s_setprio(0); } while (0)
; #define PG8_WAIT_V(n) asm volatile("s_waitcnt vmcnt(" #n ")" ::: "memory")
; #define PG8_WAIT_L(n) asm volatile("s_waitcnt lgkmcnt(" #n ")" ::: "memory")
; #define PG8_BAR __builtin_amdgcn_s_barrier()
; #define PG8_SCHED __builtin_amdgcn_sched_barrier(0)
; template <class Epi, class Sched, bool ALIGN_EPI = false, bool SP2 = false>
; __device__ __forceinline__ void gemm_phase(PG8_LAS unsigned char* lds, const Gemm g, const Sched& S, const Epi& E) {
;     ...
;             PG8_WAIT_V(8); PG8_WAIT_L(0); PG8_BAR; PG8_MMA(1, 0, At, B0); PG8_MMA(1, 1, At, B1); PG8_BAR; PG8_SCHED;
;             PG8_LDB(B0, 1, 0); PG8_LDB(B1, 1, 1); PG8_SCHED; PG8_LDA(At, 1, 0); PG8_STAGE(PG8_SA(0, 1), a2 + hstepA, voffA);
;             PG8_WAIT_V(8); PG8_WAIT_L(0); PG8_BAR; PG8_MMA(0, 0, At, B0); PG8_MMA(0, 1, At, B1); PG8_BAR; PG8_SCHED;
	s_waitcnt lgkmcnt(0)
	v_mfma_f32_16x16x32_bf16 v[62:65], v[130:133], v[178:181], v[62:65]
	v_mfma_f32_16x16x32_bf16 v[58:61], v[138:141], v[178:181], v[58:61]
	v_mfma_f32_16x16x32_bf16 v[54:57], v[130:133], v[186:189], v[54:57]
	v_mfma_f32_16x16x32_bf16 v[50:53], v[138:141], v[186:189], v[50:53]
	v_mfma_f32_16x16x32_bf16 v[46:49], v[130:133], v[194:197], v[46:49]
	v_mfma_f32_16x16x32_bf16 v[38:41], v[138:141], v[194:197], v[38:41]
	v_mfma_f32_16x16x32_bf16 v[18:21], v[130:133], v[202:205], v[18:21]
	v_mfma_f32_16x16x32_bf16 v[10:13], v[138:141], v[202:205], v[10:13]
	v_mfma_f32_16x16x32_bf16 v[62:65], v[134:137], v[182:185], v[62:65]
	v_mfma_f32_16x16x32_bf16 v[58:61], v[142:145], v[182:185], v[58:61]
	v_mfma_f32_16x16x32_bf16 v[54:57], v[134:137], v[190:193], v[54:57]
	v_mfma_f32_16x16x32_bf16 v[50:53], v[142:145], v[190:193], v[50:53]
	v_mfma_f32_16x16x32_bf16 v[46:49], v[134:137], v[198:201], v[46:49]
	v_mfma_f32_16x16x32_bf16 v[38:41], v[142:145], v[198:201], v[38:41]
	v_mfma_f32_16x16x32_bf16 v[18:21], v[134:137], v[206:209], v[18:21]
	v_mfma_f32_16x16x32_bf16 v[10:13], v[142:145], v[206:209], v[10:13]
	v_mfma_f32_16x16x32_bf16 v[42:45], v[156:159], v[178:181], v[42:45]
	v_mfma_f32_16x16x32_bf16 v[34:37], v[170:173], v[178:181], v[34:37]
	v_mfma_f32_16x16x32_bf16 v[30:33], v[156:159], v[186:189], v[30:33]
	v_mfma_f32_16x16x32_bf16 v[26:29], v[170:173], v[186:189], v[26:29]
	v_mfma_f32_16x16x32_bf16 v[22:25], v[156:159], v[194:197], v[22:25]
	v_mfma_f32_16x16x32_bf16 v[14:17], v[170:173], v[194:197], v[14:17]
	v_mfma_f32_16x16x32_bf16 v[6:9], v[156:159], v[202:205], v[6:9]
	v_mfma_f32_16x16x32_bf16 v[2:5], v[170:173], v[202:205], v[2:5]
	v_mfma_f32_16x16x32_bf16 v[42:45], v[166:169], v[182:185], v[42:45]
	v_mfma_f32_16x16x32_bf16 v[34:37], v[174:177], v[182:185], v[34:37]
	v_mfma_f32_16x16x32_bf16 v[30:33], v[166:169], v[190:193], v[30:33]
	v_mfma_f32_16x16x32_bf16 v[26:29], v[174:177], v[190:193], v[26:29]
	v_mfma_f32_16x16x32_bf16 v[22:25], v[166:169], v[198:201], v[22:25]
	v_mfma_f32_16x16x32_bf16 v[14:17], v[174:177], v[198:201], v[14:17]
	v_mfma_f32_16x16x32_bf16 v[6:9], v[166:169], v[206:209], v[6:9]
	v_mfma_f32_16x16x32_bf16 v[2:5], v[174:177], v[206:209], v[2:5]
	s_barrier
	s_add_i32 s68, 0, 0x18000
	s_add_i32 s69, 0, 0x1c000
	v_add_u32_e32 v142, s68, v1
	v_add_u32_e32 v174, s69, v1
	ds_read_b128 v[130:133], v142
	ds_read_b128 v[134:137], v142 offset:1024
	ds_read_b128 v[138:141], v142 offset:2048
	ds_read_b128 v[142:145], v142 offset:3072
	ds_read_b128 v[156:159], v174
	ds_read_b128 v[166:169], v174 offset:1024
	ds_read_b128 v[170:173], v174 offset:2048
	ds_read_b128 v[174:177], v174 offset:3072
	s_add_u32 s20, s26, 0xb0000
	s_addc_u32 s21, s27, 0
	s_mov_b32 m0, s43
	v_lshl_add_u64 v[218:219], s[20:21], 0, v[148:149]
	ds_read_b128 v[178:181], v164 offset:32768
	ds_read_b128 v[182:185], v164 offset:33792
	ds_read_b128 v[186:189], v164 offset:34816
	ds_read_b128 v[190:193], v164 offset:35840
	ds_read_b128 v[194:197], v164 offset:36864
	ds_read_b128 v[198:201], v164 offset:37888
	ds_read_b128 v[202:205], v164 offset:38912
	ds_read_b128 v[206:209], v164 offset:39936
	global_load_lds_dwordx4 v[218:219], off
	v_lshl_add_u64 v[218:219], s[20:21], 0, v[146:147]
	s_mov_b32 m0, s44
	s_nop 0
	global_load_lds_dwordx4 v[218:219], off
	s_waitcnt vmcnt(8)
	s_waitcnt lgkmcnt(0)
	s_barrier
	s_waitcnt lgkmcnt(0)
	v_mfma_f32_16x16x32_bf16 v[126:129], v[130:133], v[178:181], v[126:129]
	v_mfma_f32_16x16x32_bf16 v[122:125], v[138:141], v[178:181], v[122:125]
	v_mfma_f32_16x16x32_bf16 v[118:121], v[130:133], v[186:189], v[118:121]
	v_mfma_f32_16x16x32_bf16 v[114:117], v[138:141], v[186:189], v[114:117]
	v_mfma_f32_16x16x32_bf16 v[102:105], v[130:133], v[194:197], v[102:105]
	v_mfma_f32_16x16x32_bf16 v[90:93], v[138:141], v[194:197], v[90:93]
	v_mfma_f32_16x16x32_bf16 v[82:85], v[130:133], v[202:205], v[82:85]
	v_mfma_f32_16x16x32_bf16 v[74:77], v[138:141], v[202:205], v[74:77]
	v_mfma_f32_16x16x32_bf16 v[126:129], v[134:137], v[182:185], v[126:129]
	v_mfma_f32_16x16x32_bf16 v[122:125], v[142:145], v[182:185], v[122:125]
	v_mfma_f32_16x16x32_bf16 v[118:121], v[134:137], v[190:193], v[118:121]
	v_mfma_f32_16x16x32_bf16 v[114:117], v[142:145], v[190:193], v[114:117]
	v_mfma_f32_16x16x32_bf16 v[102:105], v[134:137], v[198:201], v[102:105]
	v_mfma_f32_16x16x32_bf16 v[90:93], v[142:145], v[198:201], v[90:93]
	v_mfma_f32_16x16x32_bf16 v[82:85], v[134:137], v[206:209], v[82:85]
	v_mfma_f32_16x16x32_bf16 v[74:77], v[142:145], v[206:209], v[74:77]
	v_mfma_f32_16x16x32_bf16 v[110:113], v[156:159], v[178:181], v[110:113]
	v_mfma_f32_16x16x32_bf16 v[106:109], v[170:173], v[178:181], v[106:109]
	v_mfma_f32_16x16x32_bf16 v[98:101], v[156:159], v[186:189], v[98:101]
	v_mfma_f32_16x16x32_bf16 v[94:97], v[170:173], v[186:189], v[94:97]
	v_mfma_f32_16x16x32_bf16 v[86:89], v[156:159], v[194:197], v[86:89]
	v_mfma_f32_16x16x32_bf16 v[78:81], v[170:173], v[194:197], v[78:81]
	v_mfma_f32_16x16x32_bf16 v[70:73], v[156:159], v[202:205], v[70:73]
	v_mfma_f32_16x16x32_bf16 v[66:69], v[170:173], v[202:205], v[66:69]
	v_mfma_f32_16x16x32_bf16 v[110:113], v[166:169], v[182:185], v[110:113]
	v_mfma_f32_16x16x32_bf16 v[106:109], v[174:177], v[182:185], v[106:109]
	v_mfma_f32_16x16x32_bf16 v[98:101], v[166:169], v[190:193], v[98:101]
	v_mfma_f32_16x16x32_bf16 v[94:97], v[174:177], v[190:193], v[94:97]
	v_mfma_f32_16x16x32_bf16 v[86:89], v[166:169], v[198:201], v[86:89]
	v_mfma_f32_16x16x32_bf16 v[78:81], v[174:177], v[198:201], v[78:81]
	v_mfma_f32_16x16x32_bf16 v[70:73], v[166:169], v[206:209], v[70:73]
	v_mfma_f32_16x16x32_bf16 v[66:69], v[174:177], v[206:209], v[66:69]
	s_barrier
; #define PG8_STAGE(bufoff, gbase, voff) do { _Pragma("unroll") for (int _i = 0; _i < 2; ++_i) \
;         __builtin_amdgcn_global_load_lds((const unsigned*)((const char*)(gbase) + (voff)[_i]), (PG8_LAS unsigned*)(lds + (bufoff) + ldsw + _i * 8192), 16, 0, 0); } while (0)
; #define PG8_LDA(dst, b, h) do { _Pragma("unroll") for (int m = 0; m < 4; ++m) _Pragma("unroll") for (int k = 0; k < 2; ++k) dst[m][k] = *(const PG8_LAS bf16x8*)(lds + PG8_SA(b, h) + aoff + m * 2048 + k * 1024); } while (0)
; #define PG8_MMA(ai, bj, At, Bt) do { __builtin_amdgcn_s_setprio(1); _Pragma("unroll") for (int m = 0; m < 4; ++m) _Pragma("unroll") for (int n = 0; n < 2; ++n) _Pragma("unroll") for (int k = 0; k < 2; ++k) \
;         acc[ai][bj][m][n] = __builtin_amdgcn_mfma_f32_16x16x32_bf16(Bt[n][k], At[m][k], acc[ai][bj][m][n], 0, 0, 0); __builtin_amdgcn_s_setprio(0); } while (0)
; #define PG8_WAIT_V(n) asm volatile("s_waitcnt vmcnt(" #n ")" ::: "memory")
; #define PG8_WAIT_L(n) asm volatile("s_waitcnt lgkmcnt(" #n ")" ::: "memory")
; #define PG8_BAR __builtin_amdgcn_s_barrier()
; #define PG8_SCHED __builtin_amdgcn_sched_barrier(0)
; template <class Epi, class Sched, bool ALIGN_EPI = false, bool SP2 = false>
; __device__ __forceinline__ void gemm_phase(PG8_LAS unsigned char* lds, const Gemm g, const Sched& S, const Epi& E) {
;     ...
;             PG8_LDA(At, 1, 1); PG8_STAGE(PG8_SB(1, 0), b3, voffB); PG8_STAGE(PG8_SB(1, 1), b3 + hstepB, voffB); PG8_STAGE(PG8_SA(1, 0), a3, voffA);
;             PG8_WAIT_V(8); PG8_WAIT_L(0); PG8_BAR; PG8_MMA(1, 0, At, B0); PG8_MMA(1, 1, At, B1); PG8_BAR; PG8_SCHED;
;     ...
;         }
;         if constexpr (ALIGN_EPI) { if (wr == 0) PG8_BAR; }
	s_add_i32 s20, s68, s39
	v_lshl_add_u64 v[210:211], v[210:211], 0, s[8:9]
	s_mov_b32 m0, s20
	ds_read_b128 v[178:181], v164 offset:49152
	ds_read_b128 v[182:185], v164 offset:50176
	ds_read_b128 v[186:189], v164 offset:51200
	ds_read_b128 v[190:193], v164 offset:52224
	ds_read_b128 v[194:197], v164 offset:53248
	ds_read_b128 v[198:201], v164 offset:54272
	ds_read_b128 v[202:205], v164 offset:55296
	ds_read_b128 v[206:209], v164 offset:56320
	global_load_lds_dwordx4 v[210:211], off
	s_add_i32 m0, s20, 0x2000
	s_add_u32 s20, s24, 0xb0080
	v_lshl_add_u64 v[210:211], v[212:213], 0, s[8:9]
	s_addc_u32 s21, s25, 0
	s_add_i32 s24, s69, s39
	global_load_lds_dwordx4 v[210:211], off
	v_lshl_add_u64 v[210:211], s[20:21], 0, v[148:149]
	s_mov_b32 m0, s24
	s_nop 0
	global_load_lds_dwordx4 v[210:211], off
	v_lshl_add_u64 v[210:211], s[20:21], 0, v[146:147]
	s_add_i32 m0, s24, 0x2000
	s_nop 0
	global_load_lds_dwordx4 v[210:211], off
	v_lshl_add_u64 v[210:211], v[214:215], 0, s[8:9]
	s_mov_b32 m0, s51
	s_nop 0
	global_load_lds_dwordx4 v[210:211], off
	v_lshl_add_u64 v[210:211], v[216:217], 0, s[8:9]
	s_mov_b32 m0, s52
	s_nop 0
	global_load_lds_dwordx4 v[210:211], off
	s_waitcnt vmcnt(8)
	s_waitcnt lgkmcnt(0)
	s_barrier
	s_waitcnt lgkmcnt(0)
	v_mfma_f32_16x16x32_bf16 v[62:65], v[130:133], v[178:181], v[62:65]
	v_mfma_f32_16x16x32_bf16 v[58:61], v[138:141], v[178:181], v[58:61]
	v_mfma_f32_16x16x32_bf16 v[54:57], v[130:133], v[186:189], v[54:57]
	v_mfma_f32_16x16x32_bf16 v[50:53], v[138:141], v[186:189], v[50:53]
	v_mfma_f32_16x16x32_bf16 v[46:49], v[130:133], v[194:197], v[46:49]
	v_mfma_f32_16x16x32_bf16 v[38:41], v[138:141], v[194:197], v[38:41]
	v_mfma_f32_16x16x32_bf16 v[18:21], v[130:133], v[202:205], v[18:21]
	v_mfma_f32_16x16x32_bf16 v[10:13], v[138:141], v[202:205], v[10:13]
	v_mfma_f32_16x16x32_bf16 v[62:65], v[134:137], v[182:185], v[62:65]
	v_mfma_f32_16x16x32_bf16 v[58:61], v[142:145], v[182:185], v[58:61]
	v_mfma_f32_16x16x32_bf16 v[54:57], v[134:137], v[190:193], v[54:57]
	v_mfma_f32_16x16x32_bf16 v[50:53], v[142:145], v[190:193], v[50:53]
	v_mfma_f32_16x16x32_bf16 v[46:49], v[134:137], v[198:201], v[46:49]
	v_mfma_f32_16x16x32_bf16 v[38:41], v[142:145], v[198:201], v[38:41]
	v_mfma_f32_16x16x32_bf16 v[18:21], v[134:137], v[206:209], v[18:21]
	v_mfma_f32_16x16x32_bf16 v[10:13], v[142:145], v[206:209], v[10:13]
	v_mfma_f32_16x16x32_bf16 v[42:45], v[156:159], v[178:181], v[42:45]
	v_mfma_f32_16x16x32_bf16 v[34:37], v[170:173], v[178:181], v[34:37]
	v_mfma_f32_16x16x32_bf16 v[30:33], v[156:159], v[186:189], v[30:33]
	v_mfma_f32_16x16x32_bf16 v[26:29], v[170:173], v[186:189], v[26:29]
	v_mfma_f32_16x16x32_bf16 v[22:25], v[156:159], v[194:197], v[22:25]
	v_mfma_f32_16x16x32_bf16 v[14:17], v[170:173], v[194:197], v[14:17]
	v_mfma_f32_16x16x32_bf16 v[6:9], v[156:159], v[202:205], v[6:9]
	v_mfma_f32_16x16x32_bf16 v[2:5], v[170:173], v[202:205], v[2:5]
	v_mfma_f32_16x16x32_bf16 v[42:45], v[166:169], v[182:185], v[42:45]
	v_mfma_f32_16x16x32_bf16 v[34:37], v[174:177], v[182:185], v[34:37]
	v_mfma_f32_16x16x32_bf16 v[30:33], v[166:169], v[190:193], v[30:33]
	v_mfma_f32_16x16x32_bf16 v[26:29], v[174:177], v[190:193], v[26:29]
	v_mfma_f32_16x16x32_bf16 v[22:25], v[166:169], v[198:201], v[22:25]
	v_mfma_f32_16x16x32_bf16 v[14:17], v[174:177], v[198:201], v[14:17]
	v_mfma_f32_16x16x32_bf16 v[6:9], v[166:169], v[206:209], v[6:9]
	v_mfma_f32_16x16x32_bf16 v[2:5], v[174:177], v[206:209], v[2:5]
	s_barrier
	s_add_i32 s67, s67, 2
	s_add_u32 s65, s65, 0x100
	s_addc_u32 s66, s66, 0
	s_cmp_lt_u32 s67, 6
	s_mov_b64 s[20:21], s[22:23]
	s_cbranch_scc1 .LBB0_1921
	s_andn2_b64 vcc, exec, s[10:11]
	s_cbranch_vccnz .LBB0_1924
	s_barrier

; #define PG8_STAGE(bufoff, gbase, voff) do { _Pragma("unroll") for (int _i = 0; _i < 2; ++_i) \
;         __builtin_amdgcn_global_load_lds((const unsigned*)((const char*)(gbase) + (voff)[_i]), (PG8_LAS unsigned*)(lds + (bufoff) + ldsw + _i * 8192), 16, 0, 0); } while (0)
; #define PG8_LDA(dst, b, h) do { _Pragma("unroll") for (int m = 0; m < 4; ++m) _Pragma("unroll") for (int k = 0; k < 2; ++k) dst[m][k] = *(const PG8_LAS bf16x8*)(lds + PG8_SA(b, h) + aoff + m * 2048 + k * 1024); } while (0)
; #define PG8_LDB(dst, b, h) do { _Pragma("unroll") for (int n = 0; n < 2; ++n) _Pragma("unroll") for (int k = 0; k < 2; ++k) dst[n][k] = *(const PG8_LAS bf16x8*)(lds + PG8_SB(b, h) + boff + n * 2048 + k * 1024); } while (0)
; #define PG8_MMA(ai, bj, At, Bt) do { __builtin_amdgcn_s_setprio(1); _Pragma("unroll") for (int m = 0; m < 4; ++m) _Pragma("unroll") for (int n = 0; n < 2; ++n) _Pragma("unroll") for (int k = 0; k < 2; ++k) \
;         acc[ai][bj][m][n] = __builtin_amdgcn_mfma_f32_16x16x32_bf16(Bt[n][k], At[m][k], acc[ai][bj][m][n], 0, 0, 0); __builtin_amdgcn_s_setprio(0); } while (0)
; #define PG8_WAIT_V(n) asm volatile("s_waitcnt vmcnt(" #n ")" ::: "memory")
; #define PG8_WAIT_L(n) asm volatile("s_waitcnt lgkmcnt(" #n ")" ::: "memory")
; template <class Epi, class Sched, bool ALIGN_EPI = false, bool SP2 = false>
; __device__ __forceinline__ void gemm_phase(PG8_LAS unsigned char* lds, const Gemm g, const Sched& S, const Epi& E) {
;     ...
;             const bool last = (t == nt - 2);
;             const char* a1 = cA + (size_t)(t + 1) * kstep;
;             const char* a2 = last ? nA : cA + (size_t)(t + 2) * kstep; const char* b2 = last ? nB : cB + (size_t)(t + 2) * kstep;
;             const char* a3 = a2 + kstep; const char* b3 = b2 + kstep;
;             if (last && has_next) S.a_ready(nxt);
;             if constexpr (SP2) {
;             PG8_LDB(B0, 0, 0); PG8_LDB(B1, 0, 1); PG8_SCHED; PG8_LDA(At, 0, 0); PG8_STAGE(PG8_SA(1, 1), a1 + hstepA, voffA);
;             PG8_WAIT_V(8); PG8_WAIT_L(0); PG8_BAR; PG8_MMA(0, 0, At, B0); PG8_MMA(0, 1, At, B1); PG8_BAR; PG8_SCHED;
;             PG8_LDA(At, 0, 1); PG8_STAGE(PG8_SB(0, 0), b2, voffB); PG8_STAGE(PG8_SB(0, 1), b2 + hstepB, voffB); PG8_STAGE(PG8_SA(0, 0), a2, voffA);
;             PG8_WAIT_V(8); PG8_WAIT_L(0); PG8_BAR; PG8_MMA(1, 0, At, B0); PG8_MMA(1, 1, At, B1); PG8_BAR; PG8_SCHED;
.LBB0_1945:
	ds_read_b128 v[130:133], v162
	ds_read_b128 v[134:137], v162 offset:1024
	ds_read_b128 v[138:141], v162 offset:2048
	ds_read_b128 v[142:145], v162 offset:3072
	ds_read_b128 v[156:159], v163
	ds_read_b128 v[166:169], v163 offset:1024
	ds_read_b128 v[170:173], v163 offset:2048
	ds_read_b128 v[174:177], v163 offset:3072
	s_add_u32 s22, s20, 0x100
	s_addc_u32 s23, s21, 0
	s_cmp_eq_u32 s68, 4
	s_cselect_b32 s27, s19, s23
	s_cselect_b32 s26, s18, s22
	s_cselect_b32 s25, s1, s67
	s_cselect_b32 s24, s0, s66
	v_lshl_add_u64 v[210:211], s[20:21], 0, v[154:155]
	s_add_i32 m0, s42, 0xc000
	ds_read_b128 v[178:181], v164
	ds_read_b128 v[182:185], v164 offset:1024
	ds_read_b128 v[186:189], v164 offset:2048
	ds_read_b128 v[190:193], v164 offset:3072
	ds_read_b128 v[194:197], v164 offset:4096
	ds_read_b128 v[198:201], v164 offset:5120
	ds_read_b128 v[202:205], v164 offset:6144
	ds_read_b128 v[206:209], v164 offset:7168
	global_load_lds_dwordx4 v[210:211], off
	v_lshl_add_u64 v[210:211], s[20:21], 0, v[152:153]
	s_add_i32 m0, s42, 0xe000
	s_nop 0
	global_load_lds_dwordx4 v[210:211], off
	s_waitcnt vmcnt(8)
	s_waitcnt lgkmcnt(0)
	s_barrier
	s_waitcnt lgkmcnt(0)
	v_mfma_f32_16x16x32_bf16 v[126:129], v[130:133], v[178:181], v[126:129]
	v_mfma_f32_16x16x32_bf16 v[122:125], v[138:141], v[178:181], v[122:125]
	v_mfma_f32_16x16x32_bf16 v[118:121], v[130:133], v[186:189], v[118:121]
	v_mfma_f32_16x16x32_bf16 v[114:117], v[138:141], v[186:189], v[114:117]
	v_mfma_f32_16x16x32_bf16 v[102:105], v[130:133], v[194:197], v[102:105]
	v_mfma_f32_16x16x32_bf16 v[90:93], v[138:141], v[194:197], v[90:93]
	v_mfma_f32_16x16x32_bf16 v[82:85], v[130:133], v[202:205], v[82:85]
	v_mfma_f32_16x16x32_bf16 v[74:77], v[138:141], v[202:205], v[74:77]
	v_mfma_f32_16x16x32_bf16 v[126:129], v[134:137], v[182:185], v[126:129]
	v_mfma_f32_16x16x32_bf16 v[122:125], v[142:145], v[182:185], v[122:125]
	v_mfma_f32_16x16x32_bf16 v[118:121], v[134:137], v[190:193], v[118:121]
	v_mfma_f32_16x16x32_bf16 v[114:117], v[142:145], v[190:193], v[114:117]
	v_mfma_f32_16x16x32_bf16 v[102:105], v[134:137], v[198:201], v[102:105]
	v_mfma_f32_16x16x32_bf16 v[90:93], v[142:145], v[198:201], v[90:93]
	v_mfma_f32_16x16x32_bf16 v[82:85], v[134:137], v[206:209], v[82:85]
	v_mfma_f32_16x16x32_bf16 v[74:77], v[142:145], v[206:209], v[74:77]
	v_mfma_f32_16x16x32_bf16 v[110:113], v[156:159], v[178:181], v[110:113]
	v_mfma_f32_16x16x32_bf16 v[106:109], v[170:173], v[178:181], v[106:109]
	v_mfma_f32_16x16x32_bf16 v[98:101], v[156:159], v[186:189], v[98:101]
	v_mfma_f32_16x16x32_bf16 v[94:97], v[170:173], v[186:189], v[94:97]
	v_mfma_f32_16x16x32_bf16 v[86:89], v[156:159], v[194:197], v[86:89]
	v_mfma_f32_16x16x32_bf16 v[78:81], v[170:173], v[194:197], v[78:81]
	v_mfma_f32_16x16x32_bf16 v[70:73], v[156:159], v[202:205], v[70:73]
	v_mfma_f32_16x16x32_bf16 v[66:69], v[170:173], v[202:205], v[66:69]
	v_mfma_f32_16x16x32_bf16 v[110:113], v[166:169], v[182:185], v[110:113]
	v_mfma_f32_16x16x32_bf16 v[106:109], v[174:177], v[182:185], v[106:109]
	v_mfma_f32_16x16x32_bf16 v[98:101], v[166:169], v[190:193], v[98:101]
	v_mfma_f32_16x16x32_bf16 v[94:97], v[174:177], v[190:193], v[94:97]
	v_mfma_f32_16x16x32_bf16 v[86:89], v[166:169], v[198:201], v[86:89]
	v_mfma_f32_16x16x32_bf16 v[78:81], v[174:177], v[198:201], v[78:81]
	v_mfma_f32_16x16x32_bf16 v[70:73], v[166:169], v[206:209], v[70:73]
	v_mfma_f32_16x16x32_bf16 v[66:69], v[174:177], v[206:209], v[66:69]
	s_barrier
	s_add_i32 s20, s54, s40
	v_lshl_add_u64 v[210:211], s[24:25], 0, v[148:149]
	s_mov_b32 m0, s20
	ds_read_b128 v[178:181], v164 offset:16384
	ds_read_b128 v[182:185], v164 offset:17408
	ds_read_b128 v[186:189], v164 offset:18432
	ds_read_b128 v[190:193], v164 offset:19456
	ds_read_b128 v[194:197], v164 offset:20480
	ds_read_b128 v[198:201], v164 offset:21504
	ds_read_b128 v[202:205], v164 offset:22528
	ds_read_b128 v[206:209], v164 offset:23552
	global_load_lds_dwordx4 v[210:211], off
	s_add_i32 m0, s20, 0x2000
	s_add_u32 s20, s24, 0xb0000
	v_lshl_add_u64 v[212:213], s[24:25], 0, v[146:147]
	s_addc_u32 s21, s25, 0
	s_add_i32 s69, s55, s40
	global_load_lds_dwordx4 v[212:213], off
	v_lshl_add_u64 v[214:215], s[20:21], 0, v[148:149]
	s_mov_b32 m0, s69
	v_lshl_add_u64 v[216:217], s[26:27], 0, v[146:147]
	global_load_lds_dwordx4 v[214:215], off
	v_lshl_add_u64 v[214:215], s[20:21], 0, v[146:147]
	s_add_i32 m0, s69, 0x2000
	s_nop 0
	global_load_lds_dwordx4 v[214:215], off
	v_lshl_add_u64 v[214:215], s[26:27], 0, v[148:149]
	s_mov_b32 m0, s42
	s_nop 0
	global_load_lds_dwordx4 v[214:215], off
	s_mov_b32 m0, s43
	s_nop 0
	global_load_lds_dwordx4 v[216:217], off
	s_waitcnt vmcnt(8)
	s_waitcnt lgkmcnt(0)
	s_barrier
; #define PG8_STAGE(bufoff, gbase, voff) do { _Pragma("unroll") for (int _i = 0; _i < 2; ++_i) \
;         __builtin_amdgcn_global_load_lds((const unsigned*)((const char*)(gbase) + (voff)[_i]), (PG8_LAS unsigned*)(lds + (bufoff) + ldsw + _i * 8192), 16, 0, 0); } while (0)
; #define PG8_LDA(dst, b, h) do { _Pragma("unroll") for (int m = 0; m < 4; ++m) _Pragma("unroll") for (int k = 0; k < 2; ++k) dst[m][k] = *(const PG8_LAS bf16x8*)(lds + PG8_SA(b, h) + aoff + m * 2048 + k * 1024); } while (0)
; #define PG8_LDB(dst, b, h) do { _Pragma("unroll") for (int n = 0; n < 2; ++n) _Pragma("unroll") for (int k = 0; k < 2; ++k) dst[n][k] = *(const PG8_LAS bf16x8*)(lds + PG8_SB(b, h) + boff + n * 2048 + k * 1024); } while (0)
; #define PG8_MMA(ai, bj, At, Bt) do { __builtin_amdgcn_s_setprio(1); _Pragma("unroll") for (int m = 0; m < 4; ++m) _Pragma("unroll") for (int n = 0; n < 2; ++n) _Pragma("unroll") for (int k = 0; k < 2; ++k) \
;         acc[ai][bj][m][n] = __builtin_amdgcn_mfma_f32_16x16x32_bf16(Bt[n][k], At[m][k], acc[ai][bj][m][n], 0, 0, 0); __builtin_amdgcn_s_setprio(0); } while (0)
; #define PG8_WAIT_V(n) asm volatile("s_waitcnt vmcnt(" #n ")" ::: "memory")
; #define PG8_WAIT_L(n) asm volatile("s_waitcnt lgkmcnt(" #n ")" ::: "memory")
; #define PG8_BAR __builtin_amdgcn_s_barrier()
; #define PG8_SCHED __builtin_amdgcn_sched_barrier(0)
; template <class Epi, class Sched, bool ALIGN_EPI = false, bool SP2 = false>
; __device__ __forceinline__ void gemm_phase(PG8_LAS unsigned char* lds, const Gemm g, const Sched& S, const Epi& E) {
;     ...
;             PG8_WAIT_V(8); PG8_WAIT_L(0); PG8_BAR; PG8_MMA(1, 0, At, B0); PG8_MMA(1, 1, At, B1); PG8_BAR; PG8_SCHED;
;             PG8_LDB(B0, 1, 0); PG8_LDB(B1, 1, 1); PG8_SCHED; PG8_LDA(At, 1, 0); PG8_STAGE(PG8_SA(0, 1), a2 + hstepA, voffA);
;             PG8_WAIT_V(8); PG8_WAIT_L(0); PG8_BAR; PG8_MMA(0, 0, At, B0); PG8_MMA(0, 1, At, B1); PG8_BAR; PG8_SCHED;
	s_waitcnt lgkmcnt(0)
	v_mfma_f32_16x16x32_bf16 v[62:65], v[130:133], v[178:181], v[62:65]
	v_mfma_f32_16x16x32_bf16 v[58:61], v[138:141], v[178:181], v[58:61]
	v_mfma_f32_16x16x32_bf16 v[54:57], v[130:133], v[186:189], v[54:57]
	v_mfma_f32_16x16x32_bf16 v[50:53], v[138:141], v[186:189], v[50:53]
	v_mfma_f32_16x16x32_bf16 v[46:49], v[130:133], v[194:197], v[46:49]
	v_mfma_f32_16x16x32_bf16 v[38:41], v[138:141], v[194:197], v[38:41]
	v_mfma_f32_16x16x32_bf16 v[18:21], v[130:133], v[202:205], v[18:21]
	v_mfma_f32_16x16x32_bf16 v[10:13], v[138:141], v[202:205], v[10:13]
	v_mfma_f32_16x16x32_bf16 v[62:65], v[134:137], v[182:185], v[62:65]
	v_mfma_f32_16x16x32_bf16 v[58:61], v[142:145], v[182:185], v[58:61]
	v_mfma_f32_16x16x32_bf16 v[54:57], v[134:137], v[190:193], v[54:57]
	v_mfma_f32_16x16x32_bf16 v[50:53], v[142:145], v[190:193], v[50:53]
	v_mfma_f32_16x16x32_bf16 v[46:49], v[134:137], v[198:201], v[46:49]
	v_mfma_f32_16x16x32_bf16 v[38:41], v[142:145], v[198:201], v[38:41]
	v_mfma_f32_16x16x32_bf16 v[18:21], v[134:137], v[206:209], v[18:21]
	v_mfma_f32_16x16x32_bf16 v[10:13], v[142:145], v[206:209], v[10:13]
	v_mfma_f32_16x16x32_bf16 v[42:45], v[156:159], v[178:181], v[42:45]
	v_mfma_f32_16x16x32_bf16 v[34:37], v[170:173], v[178:181], v[34:37]
	v_mfma_f32_16x16x32_bf16 v[30:33], v[156:159], v[186:189], v[30:33]
	v_mfma_f32_16x16x32_bf16 v[26:29], v[170:173], v[186:189], v[26:29]
	v_mfma_f32_16x16x32_bf16 v[22:25], v[156:159], v[194:197], v[22:25]
	v_mfma_f32_16x16x32_bf16 v[14:17], v[170:173], v[194:197], v[14:17]
	v_mfma_f32_16x16x32_bf16 v[6:9], v[156:159], v[202:205], v[6:9]
	v_mfma_f32_16x16x32_bf16 v[2:5], v[170:173], v[202:205], v[2:5]
	v_mfma_f32_16x16x32_bf16 v[42:45], v[166:169], v[182:185], v[42:45]
	v_mfma_f32_16x16x32_bf16 v[34:37], v[174:177], v[182:185], v[34:37]
	v_mfma_f32_16x16x32_bf16 v[30:33], v[166:169], v[190:193], v[30:33]
	v_mfma_f32_16x16x32_bf16 v[26:29], v[174:177], v[190:193], v[26:29]
	v_mfma_f32_16x16x32_bf16 v[22:25], v[166:169], v[198:201], v[22:25]
	v_mfma_f32_16x16x32_bf16 v[14:17], v[174:177], v[198:201], v[14:17]
	v_mfma_f32_16x16x32_bf16 v[6:9], v[166:169], v[206:209], v[6:9]
	v_mfma_f32_16x16x32_bf16 v[2:5], v[174:177], v[206:209], v[2:5]
	s_barrier
	s_add_i32 s69, 0, 0x18000
	s_add_i32 s70, 0, 0x1c000
	v_add_u32_e32 v142, s69, v1
	v_add_u32_e32 v174, s70, v1
	ds_read_b128 v[130:133], v142
	ds_read_b128 v[134:137], v142 offset:1024
	ds_read_b128 v[138:141], v142 offset:2048
	ds_read_b128 v[142:145], v142 offset:3072
	ds_read_b128 v[156:159], v174
	ds_read_b128 v[166:169], v174 offset:1024
	ds_read_b128 v[170:173], v174 offset:2048
	ds_read_b128 v[174:177], v174 offset:3072
	s_add_u32 s20, s26, 0xb0000
	s_addc_u32 s21, s27, 0
	s_mov_b32 m0, s44
	v_lshl_add_u64 v[218:219], s[20:21], 0, v[148:149]
	ds_read_b128 v[178:181], v164 offset:32768
	ds_read_b128 v[182:185], v164 offset:33792
	ds_read_b128 v[186:189], v164 offset:34816
	ds_read_b128 v[190:193], v164 offset:35840
	ds_read_b128 v[194:197], v164 offset:36864
	ds_read_b128 v[198:201], v164 offset:37888
	ds_read_b128 v[202:205], v164 offset:38912
	ds_read_b128 v[206:209], v164 offset:39936
	global_load_lds_dwordx4 v[218:219], off
	v_lshl_add_u64 v[218:219], s[20:21], 0, v[146:147]
	s_mov_b32 m0, s45
	s_nop 0
	global_load_lds_dwordx4 v[218:219], off
	s_waitcnt vmcnt(8)
	s_waitcnt lgkmcnt(0)
	s_barrier
	s_waitcnt lgkmcnt(0)
	v_mfma_f32_16x16x32_bf16 v[126:129], v[130:133], v[178:181], v[126:129]
	v_mfma_f32_16x16x32_bf16 v[122:125], v[138:141], v[178:181], v[122:125]
	v_mfma_f32_16x16x32_bf16 v[118:121], v[130:133], v[186:189], v[118:121]
	v_mfma_f32_16x16x32_bf16 v[114:117], v[138:141], v[186:189], v[114:117]
	v_mfma_f32_16x16x32_bf16 v[102:105], v[130:133], v[194:197], v[102:105]
	v_mfma_f32_16x16x32_bf16 v[90:93], v[138:141], v[194:197], v[90:93]
	v_mfma_f32_16x16x32_bf16 v[82:85], v[130:133], v[202:205], v[82:85]
	v_mfma_f32_16x16x32_bf16 v[74:77], v[138:141], v[202:205], v[74:77]
	v_mfma_f32_16x16x32_bf16 v[126:129], v[134:137], v[182:185], v[126:129]
	v_mfma_f32_16x16x32_bf16 v[122:125], v[142:145], v[182:185], v[122:125]
	v_mfma_f32_16x16x32_bf16 v[118:121], v[134:137], v[190:193], v[118:121]
	v_mfma_f32_16x16x32_bf16 v[114:117], v[142:145], v[190:193], v[114:117]
	v_mfma_f32_16x16x32_bf16 v[102:105], v[134:137], v[198:201], v[102:105]
	v_mfma_f32_16x16x32_bf16 v[90:93], v[142:145], v[198:201], v[90:93]
	v_mfma_f32_16x16x32_bf16 v[82:85], v[134:137], v[206:209], v[82:85]
	v_mfma_f32_16x16x32_bf16 v[74:77], v[142:145], v[206:209], v[74:77]
	v_mfma_f32_16x16x32_bf16 v[110:113], v[156:159], v[178:181], v[110:113]
	v_mfma_f32_16x16x32_bf16 v[106:109], v[170:173], v[178:181], v[106:109]
	v_mfma_f32_16x16x32_bf16 v[98:101], v[156:159], v[186:189], v[98:101]
	v_mfma_f32_16x16x32_bf16 v[94:97], v[170:173], v[186:189], v[94:97]
	v_mfma_f32_16x16x32_bf16 v[86:89], v[156:159], v[194:197], v[86:89]
	v_mfma_f32_16x16x32_bf16 v[78:81], v[170:173], v[194:197], v[78:81]
	v_mfma_f32_16x16x32_bf16 v[70:73], v[156:159], v[202:205], v[70:73]
	v_mfma_f32_16x16x32_bf16 v[66:69], v[170:173], v[202:205], v[66:69]
	v_mfma_f32_16x16x32_bf16 v[110:113], v[166:169], v[182:185], v[110:113]
	v_mfma_f32_16x16x32_bf16 v[106:109], v[174:177], v[182:185], v[106:109]
	v_mfma_f32_16x16x32_bf16 v[98:101], v[166:169], v[190:193], v[98:101]
	v_mfma_f32_16x16x32_bf16 v[94:97], v[174:177], v[190:193], v[94:97]
	v_mfma_f32_16x16x32_bf16 v[86:89], v[166:169], v[198:201], v[86:89]
	v_mfma_f32_16x16x32_bf16 v[78:81], v[174:177], v[198:201], v[78:81]
	v_mfma_f32_16x16x32_bf16 v[70:73], v[166:169], v[206:209], v[70:73]
	v_mfma_f32_16x16x32_bf16 v[66:69], v[174:177], v[206:209], v[66:69]
	s_barrier
; #define PG8_STAGE(bufoff, gbase, voff) do { _Pragma("unroll") for (int _i = 0; _i < 2; ++_i) \
;         __builtin_amdgcn_global_load_lds((const unsigned*)((const char*)(gbase) + (voff)[_i]), (PG8_LAS unsigned*)(lds + (bufoff) + ldsw + _i * 8192), 16, 0, 0); } while (0)
; #define PG8_LDA(dst, b, h) do { _Pragma("unroll") for (int m = 0; m < 4; ++m) _Pragma("unroll") for (int k = 0; k < 2; ++k) dst[m][k] = *(const PG8_LAS bf16x8*)(lds + PG8_SA(b, h) + aoff + m * 2048 + k * 1024); } while (0)
; #define PG8_MMA(ai, bj, At, Bt) do { __builtin_amdgcn_s_setprio(1); _Pragma("unroll") for (int m = 0; m < 4; ++m) _Pragma("unroll") for (int n = 0; n < 2; ++n) _Pragma("unroll") for (int k = 0; k < 2; ++k) \
;         acc[ai][bj][m][n] = __builtin_amdgcn_mfma_f32_16x16x32_bf16(Bt[n][k], At[m][k], acc[ai][bj][m][n], 0, 0, 0); __builtin_amdgcn_s_setprio(0); } while (0)
; #define PG8_WAIT_V(n) asm volatile("s_waitcnt vmcnt(" #n ")" ::: "memory")
; #define PG8_WAIT_L(n) asm volatile("s_waitcnt lgkmcnt(" #n ")" ::: "memory")
; #define PG8_BAR __builtin_amdgcn_s_barrier()
; #define PG8_SCHED __builtin_amdgcn_sched_barrier(0)
; template <class Epi, class Sched, bool ALIGN_EPI = false, bool SP2 = false>
; __device__ __forceinline__ void gemm_phase(PG8_LAS unsigned char* lds, const Gemm g, const Sched& S, const Epi& E) {
;     ...
;             PG8_LDA(At, 1, 1); PG8_STAGE(PG8_SB(1, 0), b3, voffB); PG8_STAGE(PG8_SB(1, 1), b3 + hstepB, voffB); PG8_STAGE(PG8_SA(1, 0), a3, voffA);
;             PG8_WAIT_V(8); PG8_WAIT_L(0); PG8_BAR; PG8_MMA(1, 0, At, B0); PG8_MMA(1, 1, At, B1); PG8_BAR; PG8_SCHED;
;     ...
;         }
;         if constexpr (ALIGN_EPI) { if (wr == 0) PG8_BAR; }
	s_add_i32 s20, s69, s40
	v_lshl_add_u64 v[210:211], v[210:211], 0, s[8:9]
	s_mov_b32 m0, s20
	ds_read_b128 v[178:181], v164 offset:49152
	ds_read_b128 v[182:185], v164 offset:50176
	ds_read_b128 v[186:189], v164 offset:51200
	ds_read_b128 v[190:193], v164 offset:52224
	ds_read_b128 v[194:197], v164 offset:53248
	ds_read_b128 v[198:201], v164 offset:54272
	ds_read_b128 v[202:205], v164 offset:55296
	ds_read_b128 v[206:209], v164 offset:56320
	global_load_lds_dwordx4 v[210:211], off
	s_add_i32 m0, s20, 0x2000
	s_add_u32 s20, s24, 0xb0080
	v_lshl_add_u64 v[210:211], v[212:213], 0, s[8:9]
	s_addc_u32 s21, s25, 0
	s_add_i32 s24, s70, s40
	global_load_lds_dwordx4 v[210:211], off
	v_lshl_add_u64 v[210:211], s[20:21], 0, v[148:149]
	s_mov_b32 m0, s24
	s_nop 0
	global_load_lds_dwordx4 v[210:211], off
	v_lshl_add_u64 v[210:211], s[20:21], 0, v[146:147]
	s_add_i32 m0, s24, 0x2000
	s_nop 0
	global_load_lds_dwordx4 v[210:211], off
	v_lshl_add_u64 v[210:211], v[214:215], 0, s[8:9]
	s_mov_b32 m0, s51
	s_nop 0
	global_load_lds_dwordx4 v[210:211], off
	v_lshl_add_u64 v[210:211], v[216:217], 0, s[8:9]
	s_mov_b32 m0, s52
	s_nop 0
	global_load_lds_dwordx4 v[210:211], off
	s_waitcnt vmcnt(8)
	s_waitcnt lgkmcnt(0)
	s_barrier
	s_waitcnt lgkmcnt(0)
	v_mfma_f32_16x16x32_bf16 v[62:65], v[130:133], v[178:181], v[62:65]
	v_mfma_f32_16x16x32_bf16 v[58:61], v[138:141], v[178:181], v[58:61]
	v_mfma_f32_16x16x32_bf16 v[54:57], v[130:133], v[186:189], v[54:57]
	v_mfma_f32_16x16x32_bf16 v[50:53], v[138:141], v[186:189], v[50:53]
	v_mfma_f32_16x16x32_bf16 v[46:49], v[130:133], v[194:197], v[46:49]
	v_mfma_f32_16x16x32_bf16 v[38:41], v[138:141], v[194:197], v[38:41]
	v_mfma_f32_16x16x32_bf16 v[18:21], v[130:133], v[202:205], v[18:21]
	v_mfma_f32_16x16x32_bf16 v[10:13], v[138:141], v[202:205], v[10:13]
	v_mfma_f32_16x16x32_bf16 v[62:65], v[134:137], v[182:185], v[62:65]
	v_mfma_f32_16x16x32_bf16 v[58:61], v[142:145], v[182:185], v[58:61]
	v_mfma_f32_16x16x32_bf16 v[54:57], v[134:137], v[190:193], v[54:57]
	v_mfma_f32_16x16x32_bf16 v[50:53], v[142:145], v[190:193], v[50:53]
	v_mfma_f32_16x16x32_bf16 v[46:49], v[134:137], v[198:201], v[46:49]
	v_mfma_f32_16x16x32_bf16 v[38:41], v[142:145], v[198:201], v[38:41]
	v_mfma_f32_16x16x32_bf16 v[18:21], v[134:137], v[206:209], v[18:21]
	v_mfma_f32_16x16x32_bf16 v[10:13], v[142:145], v[206:209], v[10:13]
	v_mfma_f32_16x16x32_bf16 v[42:45], v[156:159], v[178:181], v[42:45]
	v_mfma_f32_16x16x32_bf16 v[34:37], v[170:173], v[178:181], v[34:37]
	v_mfma_f32_16x16x32_bf16 v[30:33], v[156:159], v[186:189], v[30:33]
	v_mfma_f32_16x16x32_bf16 v[26:29], v[170:173], v[186:189], v[26:29]
	v_mfma_f32_16x16x32_bf16 v[22:25], v[156:159], v[194:197], v[22:25]
	v_mfma_f32_16x16x32_bf16 v[14:17], v[170:173], v[194:197], v[14:17]
	v_mfma_f32_16x16x32_bf16 v[6:9], v[156:159], v[202:205], v[6:9]
	v_mfma_f32_16x16x32_bf16 v[2:5], v[170:173], v[202:205], v[2:5]
	v_mfma_f32_16x16x32_bf16 v[42:45], v[166:169], v[182:185], v[42:45]
	v_mfma_f32_16x16x32_bf16 v[34:37], v[174:177], v[182:185], v[34:37]
	v_mfma_f32_16x16x32_bf16 v[30:33], v[166:169], v[190:193], v[30:33]
	v_mfma_f32_16x16x32_bf16 v[26:29], v[174:177], v[190:193], v[26:29]
	v_mfma_f32_16x16x32_bf16 v[22:25], v[166:169], v[198:201], v[22:25]
	v_mfma_f32_16x16x32_bf16 v[14:17], v[174:177], v[198:201], v[14:17]
	v_mfma_f32_16x16x32_bf16 v[6:9], v[166:169], v[206:209], v[6:9]
	v_mfma_f32_16x16x32_bf16 v[2:5], v[174:177], v[206:209], v[2:5]
	s_barrier
	s_add_i32 s68, s68, 2
	s_add_u32 s66, s66, 0x100
	s_addc_u32 s67, s67, 0
	s_cmp_lt_u32 s68, 6
	s_mov_b64 s[20:21], s[22:23]
	s_cbranch_scc1 .LBB0_1945
	s_andn2_b64 vcc, exec, s[10:11]
	s_cbranch_vccnz .LBB0_1948
	s_barrier

; #define PG8_STAGE(bufoff, gbase, voff) do { _Pragma("unroll") for (int _i = 0; _i < 2; ++_i) \
;         __builtin_amdgcn_global_load_lds((const unsigned*)((const char*)(gbase) + (voff)[_i]), (PG8_LAS unsigned*)(lds + (bufoff) + ldsw + _i * 8192), 16, 0, 0); } while (0)
; #define PG8_LDA(dst, b, h) do { _Pragma("unroll") for (int m = 0; m < 4; ++m) _Pragma("unroll") for (int k = 0; k < 2; ++k) dst[m][k] = *(const PG8_LAS bf16x8*)(lds + PG8_SA(b, h) + aoff + m * 2048 + k * 1024); } while (0)
; #define PG8_LDB(dst, b, h) do { _Pragma("unroll") for (int n = 0; n < 2; ++n) _Pragma("unroll") for (int k = 0; k < 2; ++k) dst[n][k] = *(const PG8_LAS bf16x8*)(lds + PG8_SB(b, h) + boff + n * 2048 + k * 1024); } while (0)
; #define PG8_MMA(ai, bj, At, Bt) do { __builtin_amdgcn_s_setprio(1); _Pragma("unroll") for (int m = 0; m < 4; ++m) _Pragma("unroll") for (int n = 0; n < 2; ++n) _Pragma("unroll") for (int k = 0; k < 2; ++k) \
;         acc[ai][bj][m][n] = __builtin_amdgcn_mfma_f32_16x16x32_bf16(Bt[n][k], At[m][k], acc[ai][bj][m][n], 0, 0, 0); __builtin_amdgcn_s_setprio(0); } while (0)
; #define PG8_WAIT_V(n) asm volatile("s_waitcnt vmcnt(" #n ")" ::: "memory")
; #define PG8_WAIT_L(n) asm volatile("s_waitcnt lgkmcnt(" #n ")" ::: "memory")
; template <class Epi, class Sched, bool ALIGN_EPI = false, bool SP2 = false>
; __device__ __forceinline__ void gemm_phase(PG8_LAS unsigned char* lds, const Gemm g, const Sched& S, const Epi& E) {
;     ...
;             const bool last = (t == nt - 2);
;             const char* a1 = cA + (size_t)(t + 1) * kstep;
;             const char* a2 = last ? nA : cA + (size_t)(t + 2) * kstep; const char* b2 = last ? nB : cB + (size_t)(t + 2) * kstep;
;             const char* a3 = a2 + kstep; const char* b3 = b2 + kstep;
;             if (last && has_next) S.a_ready(nxt);
;             if constexpr (SP2) {
;             PG8_LDB(B0, 0, 0); PG8_LDB(B1, 0, 1); PG8_SCHED; PG8_LDA(At, 0, 0); PG8_STAGE(PG8_SA(1, 1), a1 + hstepA, voffA);
;             PG8_WAIT_V(8); PG8_WAIT_L(0); PG8_BAR; PG8_MMA(0, 0, At, B0); PG8_MMA(0, 1, At, B1); PG8_BAR; PG8_SCHED;
;             PG8_LDA(At, 0, 1); PG8_STAGE(PG8_SB(0, 0), b2, voffB); PG8_STAGE(PG8_SB(0, 1), b2 + hstepB, voffB); PG8_STAGE(PG8_SA(0, 0), a2, voffA);
;             PG8_WAIT_V(8); PG8_WAIT_L(0); PG8_BAR; PG8_MMA(1, 0, At, B0); PG8_MMA(1, 1, At, B1); PG8_BAR; PG8_SCHED;
.LBB0_2017:
	s_add_u32 s66, s22, s65
	ds_read_b128 v[130:133], v158
	ds_read_b128 v[134:137], v158 offset:1024
	ds_read_b128 v[138:141], v158 offset:2048
	ds_read_b128 v[142:145], v158 offset:3072
	ds_read_b128 v[152:155], v159
	ds_read_b128 v[162:165], v159 offset:1024
	ds_read_b128 v[166:169], v159 offset:2048
	ds_read_b128 v[170:173], v159 offset:3072
	s_addc_u32 s67, s23, 0
	s_add_u32 s68, s66, 0x100
	s_addc_u32 s69, s67, 0
	s_and_b64 s[28:29], s[26:27], exec
	s_cselect_b32 s29, s19, s69
	s_cselect_b32 s28, s18, s68
	s_add_u32 s65, s20, s65
	s_addc_u32 s68, s21, 0
	s_add_u32 s65, s65, 0x100
	s_addc_u32 s68, s68, 0
	s_and_b64 s[26:27], s[26:27], exec
	s_cselect_b32 s27, s1, s68
	s_cselect_b32 s26, s0, s65
	s_add_u32 s66, s66, 0xb0080
	s_addc_u32 s67, s67, 0
	v_lshl_add_u64 v[206:207], s[66:67], 0, v[148:149]
	s_add_i32 m0, s41, 0xc000
	ds_read_b128 v[174:177], v160
	ds_read_b128 v[178:181], v160 offset:1024
	ds_read_b128 v[182:185], v160 offset:2048
	ds_read_b128 v[186:189], v160 offset:3072
	ds_read_b128 v[190:193], v160 offset:4096
	ds_read_b128 v[194:197], v160 offset:5120
	ds_read_b128 v[198:201], v160 offset:6144
	ds_read_b128 v[202:205], v160 offset:7168
	global_load_lds_dwordx4 v[206:207], off
	v_lshl_add_u64 v[206:207], s[66:67], 0, v[146:147]
	s_add_i32 m0, s41, 0xe000
	s_nop 0
	global_load_lds_dwordx4 v[206:207], off
	s_waitcnt vmcnt(8)
	s_waitcnt lgkmcnt(0)
	s_barrier
	s_waitcnt lgkmcnt(0)
	v_mfma_f32_16x16x32_bf16 v[126:129], v[130:133], v[174:177], v[126:129]
	v_mfma_f32_16x16x32_bf16 v[122:125], v[138:141], v[174:177], v[122:125]
	v_mfma_f32_16x16x32_bf16 v[118:121], v[130:133], v[182:185], v[118:121]
	v_mfma_f32_16x16x32_bf16 v[114:117], v[138:141], v[182:185], v[114:117]
	v_mfma_f32_16x16x32_bf16 v[102:105], v[130:133], v[190:193], v[102:105]
	v_mfma_f32_16x16x32_bf16 v[90:93], v[138:141], v[190:193], v[90:93]
	v_mfma_f32_16x16x32_bf16 v[82:85], v[130:133], v[198:201], v[82:85]
	v_mfma_f32_16x16x32_bf16 v[74:77], v[138:141], v[198:201], v[74:77]
	v_mfma_f32_16x16x32_bf16 v[126:129], v[134:137], v[178:181], v[126:129]
	v_mfma_f32_16x16x32_bf16 v[122:125], v[142:145], v[178:181], v[122:125]
	v_mfma_f32_16x16x32_bf16 v[118:121], v[134:137], v[186:189], v[118:121]
	v_mfma_f32_16x16x32_bf16 v[114:117], v[142:145], v[186:189], v[114:117]
	v_mfma_f32_16x16x32_bf16 v[102:105], v[134:137], v[194:197], v[102:105]
	v_mfma_f32_16x16x32_bf16 v[90:93], v[142:145], v[194:197], v[90:93]
	v_mfma_f32_16x16x32_bf16 v[82:85], v[134:137], v[202:205], v[82:85]
	v_mfma_f32_16x16x32_bf16 v[74:77], v[142:145], v[202:205], v[74:77]
	v_mfma_f32_16x16x32_bf16 v[110:113], v[152:155], v[174:177], v[110:113]
	v_mfma_f32_16x16x32_bf16 v[106:109], v[166:169], v[174:177], v[106:109]
	v_mfma_f32_16x16x32_bf16 v[98:101], v[152:155], v[182:185], v[98:101]
	v_mfma_f32_16x16x32_bf16 v[94:97], v[166:169], v[182:185], v[94:97]
	v_mfma_f32_16x16x32_bf16 v[86:89], v[152:155], v[190:193], v[86:89]
	v_mfma_f32_16x16x32_bf16 v[78:81], v[166:169], v[190:193], v[78:81]
	v_mfma_f32_16x16x32_bf16 v[70:73], v[152:155], v[198:201], v[70:73]
	v_mfma_f32_16x16x32_bf16 v[66:69], v[166:169], v[198:201], v[66:69]
	v_mfma_f32_16x16x32_bf16 v[110:113], v[162:165], v[178:181], v[110:113]
	v_mfma_f32_16x16x32_bf16 v[106:109], v[170:173], v[178:181], v[106:109]
	v_mfma_f32_16x16x32_bf16 v[98:101], v[162:165], v[186:189], v[98:101]
	v_mfma_f32_16x16x32_bf16 v[94:97], v[170:173], v[186:189], v[94:97]
	v_mfma_f32_16x16x32_bf16 v[86:89], v[162:165], v[194:197], v[86:89]
	v_mfma_f32_16x16x32_bf16 v[78:81], v[170:173], v[194:197], v[78:81]
	v_mfma_f32_16x16x32_bf16 v[70:73], v[162:165], v[202:205], v[70:73]
	v_mfma_f32_16x16x32_bf16 v[66:69], v[170:173], v[202:205], v[66:69]
	s_barrier
	s_add_i32 s65, s53, s39
	v_lshl_add_u64 v[206:207], s[26:27], 0, v[148:149]
	s_mov_b32 m0, s65
	ds_read_b128 v[174:177], v160 offset:16384
	ds_read_b128 v[178:181], v160 offset:17408
	ds_read_b128 v[182:185], v160 offset:18432
	ds_read_b128 v[186:189], v160 offset:19456
	ds_read_b128 v[190:193], v160 offset:20480
	ds_read_b128 v[194:197], v160 offset:21504
	ds_read_b128 v[198:201], v160 offset:22528
	ds_read_b128 v[202:205], v160 offset:23552
	global_load_lds_dwordx4 v[206:207], off
	s_add_i32 m0, s65, 0x2000
	s_add_u32 s66, s26, 0xb0000
	v_lshl_add_u64 v[208:209], s[26:27], 0, v[146:147]
	s_addc_u32 s67, s27, 0
	s_add_i32 s65, s54, s39
	global_load_lds_dwordx4 v[208:209], off
	v_lshl_add_u64 v[210:211], s[66:67], 0, v[148:149]
	s_mov_b32 m0, s65
	v_lshl_add_u64 v[212:213], s[28:29], 0, v[146:147]
	global_load_lds_dwordx4 v[210:211], off
	v_lshl_add_u64 v[210:211], s[66:67], 0, v[146:147]
	s_add_i32 m0, s65, 0x2000
	s_nop 0
	global_load_lds_dwordx4 v[210:211], off
	v_lshl_add_u64 v[210:211], s[28:29], 0, v[148:149]
	s_mov_b32 m0, s41
	s_nop 0
	global_load_lds_dwordx4 v[210:211], off
	s_mov_b32 m0, s42
	s_nop 0
	global_load_lds_dwordx4 v[212:213], off
	s_waitcnt vmcnt(8)
	s_waitcnt lgkmcnt(0)
	s_barrier
; #define PG8_STAGE(bufoff, gbase, voff) do { _Pragma("unroll") for (int _i = 0; _i < 2; ++_i) \
;         __builtin_amdgcn_global_load_lds((const unsigned*)((const char*)(gbase) + (voff)[_i]), (PG8_LAS unsigned*)(lds + (bufoff) + ldsw + _i * 8192), 16, 0, 0); } while (0)
; #define PG8_LDA(dst, b, h) do { _Pragma("unroll") for (int m = 0; m < 4; ++m) _Pragma("unroll") for (int k = 0; k < 2; ++k) dst[m][k] = *(const PG8_LAS bf16x8*)(lds + PG8_SA(b, h) + aoff + m * 2048 + k * 1024); } while (0)
; #define PG8_LDB(dst, b, h) do { _Pragma("unroll") for (int n = 0; n < 2; ++n) _Pragma("unroll") for (int k = 0; k < 2; ++k) dst[n][k] = *(const PG8_LAS bf16x8*)(lds + PG8_SB(b, h) + boff + n * 2048 + k * 1024); } while (0)
; #define PG8_MMA(ai, bj, At, Bt) do { __builtin_amdgcn_s_setprio(1); _Pragma("unroll") for (int m = 0; m < 4; ++m) _Pragma("unroll") for (int n = 0; n < 2; ++n) _Pragma("unroll") for (int k = 0; k < 2; ++k) \
;         acc[ai][bj][m][n] = __builtin_amdgcn_mfma_f32_16x16x32_bf16(Bt[n][k], At[m][k], acc[ai][bj][m][n], 0, 0, 0); __builtin_amdgcn_s_setprio(0); } while (0)
; #define PG8_WAIT_V(n) asm volatile("s_waitcnt vmcnt(" #n ")" ::: "memory")
; #define PG8_WAIT_L(n) asm volatile("s_waitcnt lgkmcnt(" #n ")" ::: "memory")
; #define PG8_BAR __builtin_amdgcn_s_barrier()
; #define PG8_SCHED __builtin_amdgcn_sched_barrier(0)
; template <class Epi, class Sched, bool ALIGN_EPI = false, bool SP2 = false>
; __device__ __forceinline__ void gemm_phase(PG8_LAS unsigned char* lds, const Gemm g, const Sched& S, const Epi& E) {
;     ...
;             PG8_WAIT_V(8); PG8_WAIT_L(0); PG8_BAR; PG8_MMA(1, 0, At, B0); PG8_MMA(1, 1, At, B1); PG8_BAR; PG8_SCHED;
;             PG8_LDB(B0, 1, 0); PG8_LDB(B1, 1, 1); PG8_SCHED; PG8_LDA(At, 1, 0); PG8_STAGE(PG8_SA(0, 1), a2 + hstepA, voffA);
;             PG8_WAIT_V(8); PG8_WAIT_L(0); PG8_BAR; PG8_MMA(0, 0, At, B0); PG8_MMA(0, 1, At, B1); PG8_BAR; PG8_SCHED;
	s_waitcnt lgkmcnt(0)
	v_mfma_f32_16x16x32_bf16 v[62:65], v[130:133], v[174:177], v[62:65]
	v_mfma_f32_16x16x32_bf16 v[58:61], v[138:141], v[174:177], v[58:61]
	v_mfma_f32_16x16x32_bf16 v[54:57], v[130:133], v[182:185], v[54:57]
	v_mfma_f32_16x16x32_bf16 v[50:53], v[138:141], v[182:185], v[50:53]
	v_mfma_f32_16x16x32_bf16 v[46:49], v[130:133], v[190:193], v[46:49]
	v_mfma_f32_16x16x32_bf16 v[38:41], v[138:141], v[190:193], v[38:41]
	v_mfma_f32_16x16x32_bf16 v[18:21], v[130:133], v[198:201], v[18:21]
	v_mfma_f32_16x16x32_bf16 v[10:13], v[138:141], v[198:201], v[10:13]
	v_mfma_f32_16x16x32_bf16 v[62:65], v[134:137], v[178:181], v[62:65]
	v_mfma_f32_16x16x32_bf16 v[58:61], v[142:145], v[178:181], v[58:61]
	v_mfma_f32_16x16x32_bf16 v[54:57], v[134:137], v[186:189], v[54:57]
	v_mfma_f32_16x16x32_bf16 v[50:53], v[142:145], v[186:189], v[50:53]
	v_mfma_f32_16x16x32_bf16 v[46:49], v[134:137], v[194:197], v[46:49]
	v_mfma_f32_16x16x32_bf16 v[38:41], v[142:145], v[194:197], v[38:41]
	v_mfma_f32_16x16x32_bf16 v[18:21], v[134:137], v[202:205], v[18:21]
	v_mfma_f32_16x16x32_bf16 v[10:13], v[142:145], v[202:205], v[10:13]
	v_mfma_f32_16x16x32_bf16 v[42:45], v[152:155], v[174:177], v[42:45]
	v_mfma_f32_16x16x32_bf16 v[34:37], v[166:169], v[174:177], v[34:37]
	v_mfma_f32_16x16x32_bf16 v[30:33], v[152:155], v[182:185], v[30:33]
	v_mfma_f32_16x16x32_bf16 v[26:29], v[166:169], v[182:185], v[26:29]
	v_mfma_f32_16x16x32_bf16 v[22:25], v[152:155], v[190:193], v[22:25]
	v_mfma_f32_16x16x32_bf16 v[14:17], v[166:169], v[190:193], v[14:17]
	v_mfma_f32_16x16x32_bf16 v[6:9], v[152:155], v[198:201], v[6:9]
	v_mfma_f32_16x16x32_bf16 v[2:5], v[166:169], v[198:201], v[2:5]
	v_mfma_f32_16x16x32_bf16 v[42:45], v[162:165], v[178:181], v[42:45]
	v_mfma_f32_16x16x32_bf16 v[34:37], v[170:173], v[178:181], v[34:37]
	v_mfma_f32_16x16x32_bf16 v[30:33], v[162:165], v[186:189], v[30:33]
	v_mfma_f32_16x16x32_bf16 v[26:29], v[170:173], v[186:189], v[26:29]
	v_mfma_f32_16x16x32_bf16 v[22:25], v[162:165], v[194:197], v[22:25]
	v_mfma_f32_16x16x32_bf16 v[14:17], v[170:173], v[194:197], v[14:17]
	v_mfma_f32_16x16x32_bf16 v[6:9], v[162:165], v[202:205], v[6:9]
	v_mfma_f32_16x16x32_bf16 v[2:5], v[170:173], v[202:205], v[2:5]
	s_barrier
	s_add_i32 s65, 0, 0x18000
	s_add_i32 s66, 0, 0x1c000
	v_add_u32_e32 v142, s65, v1
	v_add_u32_e32 v170, s66, v1
	ds_read_b128 v[130:133], v142
	ds_read_b128 v[134:137], v142 offset:1024
	ds_read_b128 v[138:141], v142 offset:2048
	ds_read_b128 v[142:145], v142 offset:3072
	ds_read_b128 v[152:155], v170
	ds_read_b128 v[162:165], v170 offset:1024
	ds_read_b128 v[166:169], v170 offset:2048
	ds_read_b128 v[170:173], v170 offset:3072
	s_add_u32 s28, s28, 0xb0000
	s_addc_u32 s29, s29, 0
	s_mov_b32 m0, s43
	v_lshl_add_u64 v[214:215], s[28:29], 0, v[148:149]
	ds_read_b128 v[174:177], v160 offset:32768
	ds_read_b128 v[178:181], v160 offset:33792
	ds_read_b128 v[182:185], v160 offset:34816
	ds_read_b128 v[186:189], v160 offset:35840
	ds_read_b128 v[190:193], v160 offset:36864
	ds_read_b128 v[194:197], v160 offset:37888
	ds_read_b128 v[198:201], v160 offset:38912
	ds_read_b128 v[202:205], v160 offset:39936
	global_load_lds_dwordx4 v[214:215], off
	v_lshl_add_u64 v[214:215], s[28:29], 0, v[146:147]
	s_mov_b32 m0, s44
	s_nop 0
	global_load_lds_dwordx4 v[214:215], off
	s_waitcnt vmcnt(8)
	s_waitcnt lgkmcnt(0)
	s_barrier
	s_waitcnt lgkmcnt(0)
	v_mfma_f32_16x16x32_bf16 v[126:129], v[130:133], v[174:177], v[126:129]
	v_mfma_f32_16x16x32_bf16 v[122:125], v[138:141], v[174:177], v[122:125]
	v_mfma_f32_16x16x32_bf16 v[118:121], v[130:133], v[182:185], v[118:121]
	v_mfma_f32_16x16x32_bf16 v[114:117], v[138:141], v[182:185], v[114:117]
	v_mfma_f32_16x16x32_bf16 v[102:105], v[130:133], v[190:193], v[102:105]
	v_mfma_f32_16x16x32_bf16 v[90:93], v[138:141], v[190:193], v[90:93]
	v_mfma_f32_16x16x32_bf16 v[82:85], v[130:133], v[198:201], v[82:85]
	v_mfma_f32_16x16x32_bf16 v[74:77], v[138:141], v[198:201], v[74:77]
	v_mfma_f32_16x16x32_bf16 v[126:129], v[134:137], v[178:181], v[126:129]
	v_mfma_f32_16x16x32_bf16 v[122:125], v[142:145], v[178:181], v[122:125]
	v_mfma_f32_16x16x32_bf16 v[118:121], v[134:137], v[186:189], v[118:121]
	v_mfma_f32_16x16x32_bf16 v[114:117], v[142:145], v[186:189], v[114:117]
	v_mfma_f32_16x16x32_bf16 v[102:105], v[134:137], v[194:197], v[102:105]
	v_mfma_f32_16x16x32_bf16 v[90:93], v[142:145], v[194:197], v[90:93]
	v_mfma_f32_16x16x32_bf16 v[82:85], v[134:137], v[202:205], v[82:85]
	v_mfma_f32_16x16x32_bf16 v[74:77], v[142:145], v[202:205], v[74:77]
	v_mfma_f32_16x16x32_bf16 v[110:113], v[152:155], v[174:177], v[110:113]
	v_mfma_f32_16x16x32_bf16 v[106:109], v[166:169], v[174:177], v[106:109]
	v_mfma_f32_16x16x32_bf16 v[98:101], v[152:155], v[182:185], v[98:101]
	v_mfma_f32_16x16x32_bf16 v[94:97], v[166:169], v[182:185], v[94:97]
	v_mfma_f32_16x16x32_bf16 v[86:89], v[152:155], v[190:193], v[86:89]
	v_mfma_f32_16x16x32_bf16 v[78:81], v[166:169], v[190:193], v[78:81]
	v_mfma_f32_16x16x32_bf16 v[70:73], v[152:155], v[198:201], v[70:73]
	v_mfma_f32_16x16x32_bf16 v[66:69], v[166:169], v[198:201], v[66:69]
	v_mfma_f32_16x16x32_bf16 v[110:113], v[162:165], v[178:181], v[110:113]
	v_mfma_f32_16x16x32_bf16 v[106:109], v[170:173], v[178:181], v[106:109]
	v_mfma_f32_16x16x32_bf16 v[98:101], v[162:165], v[186:189], v[98:101]
	v_mfma_f32_16x16x32_bf16 v[94:97], v[170:173], v[186:189], v[94:97]
	v_mfma_f32_16x16x32_bf16 v[86:89], v[162:165], v[194:197], v[86:89]
	v_mfma_f32_16x16x32_bf16 v[78:81], v[170:173], v[194:197], v[78:81]
	v_mfma_f32_16x16x32_bf16 v[70:73], v[162:165], v[202:205], v[70:73]
	v_mfma_f32_16x16x32_bf16 v[66:69], v[170:173], v[202:205], v[66:69]
	s_barrier
; #define PG8_STAGE(bufoff, gbase, voff) do { _Pragma("unroll") for (int _i = 0; _i < 2; ++_i) \
;         __builtin_amdgcn_global_load_lds((const unsigned*)((const char*)(gbase) + (voff)[_i]), (PG8_LAS unsigned*)(lds + (bufoff) + ldsw + _i * 8192), 16, 0, 0); } while (0)
; #define PG8_LDA(dst, b, h) do { _Pragma("unroll") for (int m = 0; m < 4; ++m) _Pragma("unroll") for (int k = 0; k < 2; ++k) dst[m][k] = *(const PG8_LAS bf16x8*)(lds + PG8_SA(b, h) + aoff + m * 2048 + k * 1024); } while (0)
; #define PG8_MMA(ai, bj, At, Bt) do { __builtin_amdgcn_s_setprio(1); _Pragma("unroll") for (int m = 0; m < 4; ++m) _Pragma("unroll") for (int n = 0; n < 2; ++n) _Pragma("unroll") for (int k = 0; k < 2; ++k) \
;         acc[ai][bj][m][n] = __builtin_amdgcn_mfma_f32_16x16x32_bf16(Bt[n][k], At[m][k], acc[ai][bj][m][n], 0, 0, 0); __builtin_amdgcn_s_setprio(0); } while (0)
; #define PG8_WAIT_V(n) asm volatile("s_waitcnt vmcnt(" #n ")" ::: "memory")
; #define PG8_WAIT_L(n) asm volatile("s_waitcnt lgkmcnt(" #n ")" ::: "memory")
; #define PG8_BAR __builtin_amdgcn_s_barrier()
; #define PG8_SCHED __builtin_amdgcn_sched_barrier(0)
; template <class Epi, class Sched, bool ALIGN_EPI = false, bool SP2 = false>
; __device__ __forceinline__ void gemm_phase(PG8_LAS unsigned char* lds, const Gemm g, const Sched& S, const Epi& E) {
;     ...
;             PG8_LDA(At, 1, 1); PG8_STAGE(PG8_SB(1, 0), b3, voffB); PG8_STAGE(PG8_SB(1, 1), b3 + hstepB, voffB); PG8_STAGE(PG8_SA(1, 0), a3, voffA);
;             PG8_WAIT_V(8); PG8_WAIT_L(0); PG8_BAR; PG8_MMA(1, 0, At, B0); PG8_MMA(1, 1, At, B1); PG8_BAR; PG8_SCHED;
;     ...
;         }
;         if constexpr (ALIGN_EPI) { if (wr == 0) PG8_BAR; }
	s_add_i32 s28, s65, s39
	v_lshl_add_u64 v[206:207], v[206:207], 0, s[8:9]
	s_mov_b32 m0, s28
	ds_read_b128 v[174:177], v160 offset:49152
	ds_read_b128 v[178:181], v160 offset:50176
	ds_read_b128 v[182:185], v160 offset:51200
	ds_read_b128 v[186:189], v160 offset:52224
	ds_read_b128 v[190:193], v160 offset:53248
	ds_read_b128 v[194:197], v160 offset:54272
	ds_read_b128 v[198:201], v160 offset:55296
	ds_read_b128 v[202:205], v160 offset:56320
	global_load_lds_dwordx4 v[206:207], off
	s_add_i32 m0, s28, 0x2000
	s_add_u32 s26, s26, 0xb0080
	v_lshl_add_u64 v[206:207], v[208:209], 0, s[8:9]
	s_addc_u32 s27, s27, 0
	s_add_i32 s28, s66, s39
	global_load_lds_dwordx4 v[206:207], off
	v_lshl_add_u64 v[206:207], s[26:27], 0, v[148:149]
	s_mov_b32 m0, s28
	s_nop 0
	global_load_lds_dwordx4 v[206:207], off
	v_lshl_add_u64 v[206:207], s[26:27], 0, v[146:147]
	s_add_i32 m0, s28, 0x2000
	s_nop 0
	global_load_lds_dwordx4 v[206:207], off
	v_lshl_add_u64 v[206:207], v[210:211], 0, s[8:9]
	s_mov_b32 m0, s51
	s_nop 0
	global_load_lds_dwordx4 v[206:207], off
	v_lshl_add_u64 v[206:207], v[212:213], 0, s[8:9]
	s_mov_b32 m0, s52
	s_nop 0
	global_load_lds_dwordx4 v[206:207], off
	s_waitcnt vmcnt(8)
	s_waitcnt lgkmcnt(0)
	s_barrier
	s_waitcnt lgkmcnt(0)
	v_mfma_f32_16x16x32_bf16 v[62:65], v[130:133], v[174:177], v[62:65]
	v_mfma_f32_16x16x32_bf16 v[58:61], v[138:141], v[174:177], v[58:61]
	v_mfma_f32_16x16x32_bf16 v[54:57], v[130:133], v[182:185], v[54:57]
	v_mfma_f32_16x16x32_bf16 v[50:53], v[138:141], v[182:185], v[50:53]
	v_mfma_f32_16x16x32_bf16 v[46:49], v[130:133], v[190:193], v[46:49]
	v_mfma_f32_16x16x32_bf16 v[38:41], v[138:141], v[190:193], v[38:41]
	v_mfma_f32_16x16x32_bf16 v[18:21], v[130:133], v[198:201], v[18:21]
	v_mfma_f32_16x16x32_bf16 v[10:13], v[138:141], v[198:201], v[10:13]
	v_mfma_f32_16x16x32_bf16 v[62:65], v[134:137], v[178:181], v[62:65]
	v_mfma_f32_16x16x32_bf16 v[58:61], v[142:145], v[178:181], v[58:61]
	v_mfma_f32_16x16x32_bf16 v[54:57], v[134:137], v[186:189], v[54:57]
	v_mfma_f32_16x16x32_bf16 v[50:53], v[142:145], v[186:189], v[50:53]
	v_mfma_f32_16x16x32_bf16 v[46:49], v[134:137], v[194:197], v[46:49]
	v_mfma_f32_16x16x32_bf16 v[38:41], v[142:145], v[194:197], v[38:41]
	v_mfma_f32_16x16x32_bf16 v[18:21], v[134:137], v[202:205], v[18:21]
	v_mfma_f32_16x16x32_bf16 v[10:13], v[142:145], v[202:205], v[10:13]
	v_mfma_f32_16x16x32_bf16 v[42:45], v[152:155], v[174:177], v[42:45]
	v_mfma_f32_16x16x32_bf16 v[34:37], v[166:169], v[174:177], v[34:37]
	v_mfma_f32_16x16x32_bf16 v[30:33], v[152:155], v[182:185], v[30:33]
	v_mfma_f32_16x16x32_bf16 v[26:29], v[166:169], v[182:185], v[26:29]
	v_mfma_f32_16x16x32_bf16 v[22:25], v[152:155], v[190:193], v[22:25]
	v_mfma_f32_16x16x32_bf16 v[14:17], v[166:169], v[190:193], v[14:17]
	v_mfma_f32_16x16x32_bf16 v[6:9], v[152:155], v[198:201], v[6:9]
	v_mfma_f32_16x16x32_bf16 v[2:5], v[166:169], v[198:201], v[2:5]
	v_mfma_f32_16x16x32_bf16 v[42:45], v[162:165], v[178:181], v[42:45]
	v_mfma_f32_16x16x32_bf16 v[34:37], v[170:173], v[178:181], v[34:37]
	v_mfma_f32_16x16x32_bf16 v[30:33], v[162:165], v[186:189], v[30:33]
	v_mfma_f32_16x16x32_bf16 v[26:29], v[170:173], v[186:189], v[26:29]
	v_mfma_f32_16x16x32_bf16 v[22:25], v[162:165], v[194:197], v[22:25]
	v_mfma_f32_16x16x32_bf16 v[14:17], v[170:173], v[194:197], v[14:17]
	v_mfma_f32_16x16x32_bf16 v[6:9], v[162:165], v[202:205], v[6:9]
	v_mfma_f32_16x16x32_bf16 v[2:5], v[170:173], v[202:205], v[2:5]
	s_barrier
	s_movk_i32 s65, 0x100
	s_and_b64 vcc, exec, s[24:25]
	s_mov_b64 s[26:27], -1
	s_mov_b64 s[24:25], 0
	s_cbranch_vccnz .LBB0_2017
	s_andn2_b64 vcc, exec, s[10:11]
	s_cbranch_vccnz .LBB0_2020
	s_barrier
